# GLA output stage loop top: state-column load rounds two and three issued up front into free registers, drains replaced by counted waits
# baseline (speedup 1.0000x reference)
; #define MFMA32(a, b, c) __builtin_amdgcn_mfma_f32_32x32x16_bf16((a), (b), (c), 0, 0, 0)
; DI void gla_stage3(const Ctx& c0, int layer, int unit, int cb, LAS unsigned char* lds) {
;     ...
;     const bf16* qgp = (const bf16*)(c.ws + O_QG) + (row0 + r) * 256 + h * 64 + 8 * hi;
;     const float* sp = (const float*)(c.ws + O_UPD) + (size_t)unit * 8192;
;     const float* gn = c.a->in[I_GNORM] + (size_t)layer * 128;
;     bf16x8 qf[4];
; #pragma unroll
;     for (int s = 0; s < 4; ++s) qf[s] = *(const bf16x8*)(qgp + 16 * s);
;     f32x16 o[4];
; #pragma unroll
;     for (int vb = 0; vb < 4; ++vb) {
;         o[vb] = f32x16{};
; #pragma unroll
;         for (int s = 0; s < 4; ++s) { const float* s0 = sp + (size_t)(16 * s + 8 * hi) * 128 + 32 * vb + r;
;             const bf16x8 bfv = pack8(s0[0], s0[128], s0[256], s0[384], s0[512], s0[640], s0[768], s0[896]);
;             o[vb] = MFMA32(qf[s], bfv, o[vb]); }
;         asm volatile("" ::: "memory");
;     }
.LBB0_604:
	s_mov_b64 s[2:3], s[84:85]
	s_mov_b64 s[0:1], s[86:87]
	s_ashr_i32 s2, s35, 8
	s_ashr_i32 s3, s2, 31
	s_lshl_b64 s[2:3], s[2:3], 12
	s_and_b32 s5, s8, 0xfc0
	s_or_b32 s2, s2, s5
	s_or_b64 s[2:3], s[2:3], s[6:7]
	v_mov_b32_e32 v3, s3
	v_or_b32_e32 v2, s2, v152
	s_bfe_u32 s4, s35, 0x20006
	v_lshlrev_b64 v[2:3], 9, v[2:3]
	v_lshl_add_u64 v[2:3], s[0:1], 0, v[2:3]
	s_lshl_b32 s10, s4, 7
	v_lshl_add_u64 v[2:3], v[2:3], 0, s[10:11]
	v_lshl_add_u64 v[2:3], v[2:3], 0, v[86:87]
	v_lshl_add_u64 v[4:5], v[2:3], 0, s[16:17]
	v_add_co_u32_e32 v2, vcc, s13, v2
	v_lshl_add_u64 v[90:91], s[0:1], 0, v[84:85]
	s_nop 0
	v_addc_co_u32_e32 v3, vcc, 0, v3, vcc
	global_load_dwordx4 v[50:53], v[2:3], off
	global_load_dwordx4 v[110:113], v[4:5], off offset:96
	global_load_dwordx4 v[106:109], v[4:5], off offset:64
	global_load_dwordx4 v[102:105], v[4:5], off offset:32
	v_add_co_u32_e32 v2, vcc, s24, v90
	s_lshl_b64 s[2:3], s[2:3], 10
	s_nop 0
	v_addc_co_u32_e32 v3, vcc, -1, v91, vcc
	v_add_co_u32_e32 v58, vcc, s28, v90
	global_load_dword v2, v[2:3], off
	s_nop 0
	v_addc_co_u32_e32 v59, vcc, -1, v91, vcc
	global_load_dword v3, v[58:59], off offset:384
	global_load_dword v4, v[58:59], off offset:896
	global_load_dword v5, v[58:59], off offset:1408
	global_load_dword v6, v[58:59], off offset:1920
	global_load_dword v7, v[58:59], off offset:2432
	global_load_dword v8, v[58:59], off offset:2944
	global_load_dword v9, v[58:59], off offset:3456
	v_add_co_u32_e32 v18, vcc, s25, v90
	s_lshl_b32 s4, s4, 8
	s_nop 0
	v_addc_co_u32_e32 v19, vcc, -1, v91, vcc
	v_add_co_u32_e32 v114, vcc, s29, v90
	global_load_dword v18, v[18:19], off
	s_nop 0
	v_addc_co_u32_e32 v115, vcc, -1, v91, vcc
	global_load_dword v19, v[114:115], off offset:384
	global_load_dword v20, v[114:115], off offset:896
	global_load_dword v21, v[114:115], off offset:1408
	global_load_dword v22, v[114:115], off offset:1920
	global_load_dword v23, v[114:115], off offset:2432
	global_load_dword v24, v[114:115], off offset:2944
	global_load_dword v25, v[114:115], off offset:3456
	s_add_u32 s0, s0, s2
	s_addc_u32 s1, s1, s3
	s_add_u32 s0, s0, s4
	s_addc_u32 s1, s1, 0
	s_add_i32 s35, s35, s12
	s_add_i32 s8, s8, s9
	v_lshl_add_u64 v[84:85], v[84:85], 0, s[14:15]
	s_cmpk_lt_i32 s35, 0x800
	v_add_co_u32_e32 v26, vcc, s26, v90
	s_nop 1
	v_addc_co_u32_e32 v27, vcc, -1, v91, vcc
	v_add_co_u32_e32 v118, vcc, s30, v90
	global_load_dword v26, v[26:27], off
	s_nop 0
	v_addc_co_u32_e32 v119, vcc, -1, v91, vcc
	global_load_dword v27, v[118:119], off offset:384
	global_load_dword v28, v[118:119], off offset:896
	global_load_dword v29, v[118:119], off offset:1408
	global_load_dword v30, v[118:119], off offset:1920
	global_load_dword v31, v[118:119], off offset:2432
	global_load_dword v32, v[118:119], off offset:2944
	global_load_dword v33, v[118:119], off offset:3456
	v_add_co_u32_e32 v42, vcc, s27, v90
	s_nop 1
	v_addc_co_u32_e32 v43, vcc, -1, v91, vcc
	v_add_co_u32_e32 v120, vcc, s31, v90
	global_load_dword v42, v[42:43], off
	s_nop 0
	v_addc_co_u32_e32 v121, vcc, -1, v91, vcc
	global_load_dword v43, v[120:121], off offset:384
	global_load_dword v44, v[120:121], off offset:896
	global_load_dword v45, v[120:121], off offset:1408
	global_load_dword v46, v[120:121], off offset:1920
	global_load_dword v47, v[120:121], off offset:2432
	global_load_dword v48, v[120:121], off offset:2944
	global_load_dword v49, v[120:121], off offset:3456
	s_waitcnt vmcnt(16) lgkmcnt(0)
	global_load_dword v41, v[114:115], off offset:3584
	global_load_dword v40, v[114:115], off offset:3072
	global_load_dword v39, v[114:115], off offset:2560
	global_load_dword v38, v[114:115], off offset:2048
	global_load_dword v37, v[114:115], off offset:1536
	global_load_dword v36, v[114:115], off offset:1024
	global_load_dword v35, v[114:115], off offset:512
	global_load_dword v34, v[114:115], off
	global_load_dword v145, v[58:59], off offset:3584
	global_load_dword v146, v[58:59], off offset:3072
	global_load_dword v143, v[58:59], off offset:2560
	global_load_dword v144, v[58:59], off offset:2048
	global_load_dword v141, v[58:59], off offset:1536
	global_load_dword v142, v[58:59], off offset:1024
	global_load_dword v139, v[58:59], off offset:512
	global_load_dword v140, v[58:59], off
	v_cvt_pk_bf16_f32 v2, v2, v3
	v_cvt_pk_bf16_f32 v3, v4, v5
	v_cvt_pk_bf16_f32 v4, v6, v7
	v_cvt_pk_bf16_f32 v5, v8, v9
	v_cvt_pk_bf16_f32 v18, v18, v19
	s_nop 0
	v_mfma_f32_32x32x16_bf16 v[2:17], v[50:53], v[2:5], 0
	v_cvt_pk_bf16_f32 v19, v20, v21
	v_cvt_pk_bf16_f32 v20, v22, v23
	v_cvt_pk_bf16_f32 v21, v24, v25
	s_nop 1
	v_mfma_f32_32x32x16_bf16 v[2:17], v[102:105], v[18:21], v[2:17]
	s_waitcnt vmcnt(24) lgkmcnt(0)
	global_load_dword v63, v[114:115], off offset:3712
	global_load_dword v62, v[114:115], off offset:3200
	global_load_dword v61, v[114:115], off offset:2688
	global_load_dword v60, v[114:115], off offset:2176
	global_load_dword v57, v[114:115], off offset:1664
	global_load_dword v56, v[114:115], off offset:1152
	global_load_dword v55, v[114:115], off offset:640
	global_load_dword v54, v[114:115], off offset:128
	global_load_dword v173, v[58:59], off offset:3712
	global_load_dword v176, v[58:59], off offset:3200
	global_load_dword v171, v[58:59], off offset:2688
	global_load_dword v174, v[58:59], off offset:2176
	global_load_dword v169, v[58:59], off offset:1664
	global_load_dword v172, v[58:59], off offset:1152
	global_load_dword v167, v[58:59], off offset:640
	global_load_dword v170, v[58:59], off offset:128
	global_load_dword v157, v[118:119], off offset:3584
	global_load_dword v160, v[118:119], off offset:3072
	global_load_dword v155, v[118:119], off offset:2560
	global_load_dword v158, v[118:119], off offset:2048
	global_load_dword v149, v[118:119], off offset:1536
	global_load_dword v156, v[118:119], off offset:1024
	global_load_dword v147, v[118:119], off offset:512
	global_load_dword v148, v[118:119], off
	v_cvt_pk_bf16_f32 v26, v26, v27
	v_cvt_pk_bf16_f32 v27, v28, v29
	v_cvt_pk_bf16_f32 v28, v30, v31
	v_cvt_pk_bf16_f32 v29, v32, v33
	s_nop 1
	v_mfma_f32_32x32x16_bf16 v[2:17], v[106:109], v[26:29], v[2:17]
	v_cmp_lt_i32_e32 vcc, v94, v95
	s_waitcnt vmcnt(20) lgkmcnt(0)
; #define MFMA32(a, b, c) __builtin_amdgcn_mfma_f32_32x32x16_bf16((a), (b), (c), 0, 0, 0)
; DI void gla_stage3(const Ctx& c0, int layer, int unit, int cb, LAS unsigned char* lds) {
;     ...
;     for (int vb = 0; vb < 4; ++vb) {
;         o[vb] = f32x16{};
; #pragma unroll
;         for (int s = 0; s < 4; ++s) { const float* s0 = sp + (size_t)(16 * s + 8 * hi) * 128 + 32 * vb + r;
;             const bf16x8 bfv = pack8(s0[0], s0[128], s0[256], s0[384], s0[512], s0[640], s0[768], s0[896]);
;             o[vb] = MFMA32(qf[s], bfv, o[vb]); }
;         asm volatile("" ::: "memory");
;     }
;     ...
;     for (int vb = 0; vb < 4; ++vb) { const float g = gn[32 * vb + r];
	global_load_dword v127, v[114:115], off offset:3840
	global_load_dword v126, v[114:115], off offset:3328
	global_load_dword v125, v[114:115], off offset:2816
	global_load_dword v124, v[114:115], off offset:2304
	global_load_dword v123, v[114:115], off offset:1792
	global_load_dword v122, v[114:115], off offset:1280
	global_load_dword v117, v[114:115], off offset:768
	global_load_dword v116, v[114:115], off offset:256
	global_load_dword v214, v[58:59], off offset:3840
	global_load_dword v212, v[58:59], off offset:3328
	global_load_dword v205, v[58:59], off offset:2816
	global_load_dword v210, v[58:59], off offset:2304
	global_load_dword v203, v[58:59], off offset:1792
	global_load_dword v208, v[58:59], off offset:1280
	global_load_dword v201, v[58:59], off offset:768
	global_load_dword v206, v[58:59], off offset:256
	global_load_dword v199, v[120:121], off offset:3712
	global_load_dword v204, v[120:121], off offset:3200
	global_load_dword v197, v[120:121], off offset:2688
	global_load_dword v202, v[120:121], off offset:2176
	global_load_dword v195, v[120:121], off offset:1664
	global_load_dword v200, v[120:121], off offset:1152
	global_load_dword v183, v[120:121], off offset:640
	global_load_dword v198, v[120:121], off offset:128
	global_load_dword v181, v[118:119], off offset:3712
	global_load_dword v196, v[118:119], off offset:3200
	global_load_dword v179, v[118:119], off offset:2688
	global_load_dword v182, v[118:119], off offset:2176
	global_load_dword v177, v[118:119], off offset:1664
	global_load_dword v180, v[118:119], off offset:1152
	global_load_dword v175, v[118:119], off offset:640
	global_load_dword v178, v[118:119], off offset:128
	global_load_dword v165, v[120:121], off offset:3584
	global_load_dword v168, v[120:121], off offset:3072
	global_load_dword v163, v[120:121], off offset:2560
	global_load_dword v166, v[120:121], off offset:2048
	global_load_dword v161, v[120:121], off offset:1536
	global_load_dword v164, v[120:121], off offset:1024
	global_load_dword v159, v[120:121], off offset:512
	global_load_dword v162, v[120:121], off
	v_cvt_pk_bf16_f32 v42, v42, v43
	v_cvt_pk_bf16_f32 v43, v44, v45
	v_cvt_pk_bf16_f32 v44, v46, v47
	v_cvt_pk_bf16_f32 v45, v48, v49
	s_nop 1
	v_mfma_f32_32x32x16_bf16 v[2:17], v[110:113], v[42:45], v[2:17]
	s_waitcnt vmcnt(40) lgkmcnt(0)
	global_load_dword v238, v[82:83], off offset:384
	global_load_dword v236, v[82:83], off offset:256
	global_load_dword v234, v[82:83], off offset:128
	global_load_dword v232, v[82:83], off
	global_load_dword v90, v[90:91], off
	global_load_dword v230, v[120:121], off offset:3328
	global_load_dword v219, v[120:121], off offset:2816
	global_load_dword v228, v[120:121], off offset:2304
	global_load_dword v217, v[120:121], off offset:1792
	global_load_dword v226, v[120:121], off offset:1280
	global_load_dword v215, v[120:121], off offset:768
	global_load_dword v224, v[120:121], off offset:256
	global_load_dword v213, v[118:119], off offset:3840
	global_load_dword v222, v[118:119], off offset:3328
	global_load_dword v211, v[118:119], off offset:2816
	global_load_dword v220, v[118:119], off offset:2304
	global_load_dword v209, v[118:119], off offset:1792
	global_load_dword v218, v[118:119], off offset:1280
	global_load_dword v207, v[118:119], off offset:768
	global_load_dword v216, v[118:119], off offset:256
	v_cvt_pk_bf16_f32 v18, v140, v139
	v_cvt_pk_bf16_f32 v34, v34, v35
	v_cvt_pk_bf16_f32 v19, v142, v141
	v_cvt_pk_bf16_f32 v35, v36, v37
	v_cvt_pk_bf16_f32 v20, v144, v143
	v_cvt_pk_bf16_f32 v36, v38, v39
	v_cvt_pk_bf16_f32 v21, v146, v145
	v_cvt_pk_bf16_f32 v37, v40, v41
	s_nop 0
	v_mfma_f32_32x32x16_bf16 v[18:33], v[50:53], v[18:21], 0
	v_mfma_f32_32x32x16_bf16 v[18:33], v[102:105], v[34:37], v[18:33]
	s_waitcnt vmcnt(60) lgkmcnt(0)
	v_cvt_pk_bf16_f32 v34, v148, v147
	v_cvt_pk_bf16_f32 v35, v156, v149
	v_cvt_pk_bf16_f32 v36, v158, v155
	v_cvt_pk_bf16_f32 v37, v160, v157
	s_nop 1
	v_mfma_f32_32x32x16_bf16 v[18:33], v[106:109], v[34:37], v[18:33]
	s_waitcnt vmcnt(20) lgkmcnt(0)
	v_cvt_pk_bf16_f32 v34, v162, v159
	v_cvt_pk_bf16_f32 v35, v164, v161
	v_cvt_pk_bf16_f32 v36, v166, v163
	v_cvt_pk_bf16_f32 v37, v168, v165
	s_nop 1
	v_mfma_f32_32x32x16_bf16 v[18:33], v[110:113], v[34:37], v[18:33]
	s_waitcnt vmcnt(62) lgkmcnt(0)
	v_cvt_pk_bf16_f32 v34, v170, v167
	v_cvt_pk_bf16_f32 v54, v54, v55
	v_cvt_pk_bf16_f32 v35, v172, v169
	v_cvt_pk_bf16_f32 v55, v56, v57
	v_cvt_pk_bf16_f32 v36, v174, v171
	v_cvt_pk_bf16_f32 v56, v60, v61
	v_cvt_pk_bf16_f32 v37, v176, v173
	v_cvt_pk_bf16_f32 v57, v62, v63
	s_nop 0
	v_mfma_f32_32x32x16_bf16 v[34:49], v[50:53], v[34:37], 0
	v_mfma_f32_32x32x16_bf16 v[34:49], v[102:105], v[54:57], v[34:49]
	s_waitcnt vmcnt(28) lgkmcnt(0)
	v_cvt_pk_bf16_f32 v54, v178, v175
	v_cvt_pk_bf16_f32 v55, v180, v177
	v_cvt_pk_bf16_f32 v56, v182, v179
	v_cvt_pk_bf16_f32 v57, v196, v181
	s_nop 1
	v_mfma_f32_32x32x16_bf16 v[34:49], v[106:109], v[54:57], v[34:49]
	s_waitcnt vmcnt(36) lgkmcnt(0)
	v_cvt_pk_bf16_f32 v54, v198, v183
	v_cvt_pk_bf16_f32 v55, v200, v195
	v_cvt_pk_bf16_f32 v56, v202, v197
	v_cvt_pk_bf16_f32 v57, v204, v199
	s_nop 1
	v_mfma_f32_32x32x16_bf16 v[34:49], v[110:113], v[54:57], v[34:49]
	s_nop 0
	s_nop 0
	s_waitcnt vmcnt(44) lgkmcnt(0)
	v_cvt_pk_bf16_f32 v54, v206, v201
	v_cvt_pk_bf16_f32 v114, v116, v117
	v_cvt_pk_bf16_f32 v55, v208, v203
	v_cvt_pk_bf16_f32 v115, v122, v123
	v_cvt_pk_bf16_f32 v56, v210, v205
	v_cvt_pk_bf16_f32 v116, v124, v125
	v_cvt_pk_bf16_f32 v57, v212, v214
	v_cvt_pk_bf16_f32 v117, v126, v127
	s_nop 0
	v_mfma_f32_32x32x16_bf16 v[50:65], v[50:53], v[54:57], 0
	v_mfma_f32_32x32x16_bf16 v[50:65], v[102:105], v[114:117], v[50:65]
	s_waitcnt vmcnt(0) lgkmcnt(0)
; #define LAS __attribute__((address_space(3)))
; #define LDS_WAIT() asm volatile("s_waitcnt lgkmcnt(0)" ::: "memory")
; DI float bf2f(bf16 b) { return __uint_as_float(((unsigned)b) << 16); }
; DI void g3_tile_in(const bf16* g, LAS unsigned char* R, int lane) {
; #pragma unroll
;     for (int it = 0; it < 8; ++it) { const int row = 4 * it + (lane >> 4), ch = lane & 15;
;         *(LAS u32x4*)(R + row * G3_PITCH + ch * 16) = *(const u32x4*)(g + (size_t)row * 512 + ch * 8); }
;     LDS_WAIT();
; }
; DI void gla_stage3(const Ctx& c0, int layer, int unit, int cb, LAS unsigned char* lds) {
;     ...
;     g3_tile_in((const bf16*)(c.ws + O_OINTRA) + row0 * 512 + h * 128, R, lane);
; #pragma unroll
;     for (int vb = 0; vb < 4; ++vb) {
; #pragma unroll
;         for (int rg = 0; rg < 16; ++rg) o[vb][rg] += bf2f(*(const LAS bf16*)(Re + ((rg & 3) + 8 * (rg >> 2)) * G3_PITCH + 64 * vb));
;         asm volatile("" ::: "memory");
;     }
	v_cvt_pk_bf16_f32 v102, v216, v207
	v_cvt_pk_bf16_f32 v103, v218, v209
	v_cvt_pk_bf16_f32 v104, v220, v211
	v_cvt_pk_bf16_f32 v105, v222, v213
	s_nop 1
	v_mfma_f32_32x32x16_bf16 v[50:65], v[106:109], v[102:105], v[50:65]
	s_nop 0
	s_waitcnt vmcnt(8) lgkmcnt(0)
	v_cvt_pk_bf16_f32 v102, v224, v215
	v_cvt_pk_bf16_f32 v103, v226, v217
	v_cvt_pk_bf16_f32 v104, v228, v219
	v_cvt_pk_bf16_f32 v105, v230, v90
	v_lshl_add_u64 v[90:91], s[0:1], 0, v[88:89]
	v_lshl_add_u64 v[106:107], v[90:91], 0, s[18:19]
	v_mfma_f32_32x32x16_bf16 v[50:65], v[110:113], v[102:105], v[50:65]
	v_lshl_add_u64 v[102:103], v[106:107], 0, v[66:67]
	global_load_dwordx4 v[102:105], v[102:103], off
	s_waitcnt vmcnt(0) lgkmcnt(0)
	v_lshl_add_u64 v[168:169], v[90:91], 0, s[20:21]
	v_lshl_add_u64 v[140:141], v[168:169], 0, v[70:71]
	global_load_dwordx4 v[174:177], v[140:141], off
	v_lshl_add_u64 v[140:141], v[106:107], 0, v[70:71]
	global_load_dwordx4 v[146:149], v[140:141], off
	v_lshl_add_u64 v[144:145], v[106:107], 0, v[68:69]
	global_load_dwordx4 v[140:143], v[144:145], off
	ds_write_b128 v92, v[102:105]
	s_waitcnt vmcnt(0) lgkmcnt(0)
	v_lshl_add_u64 v[144:145], v[168:169], 0, v[76:77]
	global_load_dwordx4 v[200:203], v[144:145], off
	v_lshl_add_u64 v[144:145], v[168:169], 0, v[74:75]
	global_load_dwordx4 v[196:199], v[144:145], off
	v_lshl_add_u64 v[144:145], v[168:169], 0, v[72:73]
	global_load_dwordx4 v[178:181], v[144:145], off
	v_lshl_add_u64 v[144:145], v[106:107], 0, v[74:75]
	global_load_dwordx4 v[156:159], v[144:145], off
	v_lshl_add_u64 v[102:103], v[106:107], 0, v[72:73]
	global_load_dwordx4 v[102:105], v[102:103], off
	ds_write_b128 v92, v[140:143] offset:1088
	s_waitcnt vmcnt(5) lgkmcnt(0)
	v_lshl_add_u64 v[140:141], v[168:169], 0, v[78:79]
	global_load_dwordx4 v[204:207], v[140:141], off
	v_lshl_add_u64 v[140:141], v[106:107], 0, v[78:79]
	global_load_dwordx4 v[160:163], v[140:141], off
	v_lshl_add_u64 v[144:145], v[106:107], 0, v[76:77]
	global_load_dwordx4 v[140:143], v[144:145], off
	ds_write_b128 v92, v[146:149] offset:2176
	s_waitcnt vmcnt(3) lgkmcnt(0)
	v_lshl_add_u64 v[144:145], v[168:169], 0, v[66:67]
	global_load_dwordx4 v[164:167], v[144:145], off
	v_lshl_add_u64 v[148:149], v[106:107], 0, v[80:81]
	global_load_dwordx4 v[144:147], v[148:149], off
	ds_write_b128 v92, v[102:105] offset:3264
	s_waitcnt vmcnt(6) lgkmcnt(0)
	v_lshl_add_u64 v[148:149], v[168:169], 0, v[68:69]
	global_load_dwordx4 v[170:173], v[148:149], off
	ds_write_b128 v92, v[156:159] offset:4352
	s_waitcnt vmcnt(3) lgkmcnt(0)
	ds_write_b128 v92, v[140:143] offset:5440
	s_waitcnt vmcnt(4) lgkmcnt(0)
	ds_write_b128 v92, v[160:163] offset:6528
	s_waitcnt vmcnt(1) lgkmcnt(0)
	ds_write_b128 v92, v[144:147] offset:7616
	s_waitcnt lgkmcnt(0)
	ds_read_u16 v102, v1
	s_waitcnt lgkmcnt(0)
	v_lshlrev_b32_e32 v102, 16, v102
	v_add_f32_e32 v138, v2, v102
	ds_read_u16 v2, v1 offset:272
	s_waitcnt lgkmcnt(0)
	v_lshlrev_b32_e32 v2, 16, v2
	v_add_f32_e32 v137, v3, v2
	ds_read_u16 v2, v1 offset:544
	s_waitcnt lgkmcnt(0)
	v_lshlrev_b32_e32 v2, 16, v2
	v_add_f32_e32 v136, v4, v2
	ds_read_u16 v2, v1 offset:816
	s_waitcnt lgkmcnt(0)
	v_lshlrev_b32_e32 v2, 16, v2
	v_add_f32_e32 v135, v5, v2
	ds_read_u16 v2, v1 offset:2176
	s_waitcnt lgkmcnt(0)
	v_lshlrev_b32_e32 v2, 16, v2
	v_add_f32_e32 v134, v6, v2
	ds_read_u16 v2, v1 offset:2448
	s_waitcnt lgkmcnt(0)
	v_lshlrev_b32_e32 v2, 16, v2
	v_add_f32_e32 v133, v7, v2
	ds_read_u16 v2, v1 offset:2720
	s_waitcnt lgkmcnt(0)
	v_lshlrev_b32_e32 v2, 16, v2
	v_add_f32_e32 v132, v8, v2
	ds_read_u16 v2, v1 offset:2992
	s_waitcnt lgkmcnt(0)
	v_lshlrev_b32_e32 v2, 16, v2
	v_add_f32_e32 v131, v9, v2
	ds_read_u16 v2, v1 offset:4352
	s_waitcnt lgkmcnt(0)
	v_lshlrev_b32_e32 v2, 16, v2
	v_add_f32_e32 v130, v10, v2
	ds_read_u16 v2, v1 offset:4624
	s_waitcnt lgkmcnt(0)
	v_lshlrev_b32_e32 v2, 16, v2
	v_add_f32_e32 v129, v11, v2
	ds_read_u16 v2, v1 offset:4896
	s_waitcnt lgkmcnt(0)
	v_lshlrev_b32_e32 v2, 16, v2
	v_add_f32_e32 v128, v12, v2
	ds_read_u16 v2, v1 offset:5168
	s_waitcnt lgkmcnt(0)
	v_lshlrev_b32_e32 v2, 16, v2
	v_add_f32_e32 v127, v13, v2
	ds_read_u16 v2, v1 offset:6528
	s_waitcnt lgkmcnt(0)
	v_lshlrev_b32_e32 v2, 16, v2
	v_add_f32_e32 v126, v14, v2
	ds_read_u16 v2, v1 offset:6800
	s_waitcnt lgkmcnt(0)
	v_lshlrev_b32_e32 v2, 16, v2
	v_add_f32_e32 v125, v15, v2
	ds_read_u16 v2, v1 offset:7072
	s_waitcnt lgkmcnt(0)
	v_lshlrev_b32_e32 v2, 16, v2
	v_add_f32_e32 v124, v16, v2
	ds_read_u16 v2, v1 offset:7344
	s_waitcnt lgkmcnt(0)
	v_lshlrev_b32_e32 v2, 16, v2
	v_add_f32_e32 v123, v17, v2
	ds_read_u16 v2, v1 offset:64
	s_waitcnt lgkmcnt(0)
	v_lshlrev_b32_e32 v2, 16, v2
	v_add_f32_e32 v122, v18, v2
	ds_read_u16 v2, v1 offset:336
	s_waitcnt lgkmcnt(0)
	v_lshlrev_b32_e32 v2, 16, v2
	v_add_f32_e32 v121, v19, v2
	ds_read_u16 v2, v1 offset:608
	s_waitcnt lgkmcnt(0)
	v_lshlrev_b32_e32 v2, 16, v2
	v_add_f32_e32 v120, v20, v2
	ds_read_u16 v2, v1 offset:880
	s_waitcnt lgkmcnt(0)
	v_lshlrev_b32_e32 v2, 16, v2
	v_add_f32_e32 v119, v21, v2
	ds_read_u16 v2, v1 offset:2240
	s_waitcnt lgkmcnt(0)
	v_lshlrev_b32_e32 v2, 16, v2
	v_add_f32_e32 v118, v22, v2
	ds_read_u16 v2, v1 offset:2512
	s_waitcnt lgkmcnt(0)
	v_lshlrev_b32_e32 v2, 16, v2
	v_add_f32_e32 v117, v23, v2
	ds_read_u16 v2, v1 offset:2784
	s_waitcnt lgkmcnt(0)
	v_lshlrev_b32_e32 v2, 16, v2
	v_add_f32_e32 v116, v24, v2
	ds_read_u16 v2, v1 offset:3056
	s_waitcnt lgkmcnt(0)
	v_lshlrev_b32_e32 v2, 16, v2
	v_add_f32_e32 v115, v25, v2
	ds_read_u16 v2, v1 offset:4416
	s_waitcnt lgkmcnt(0)
	v_lshlrev_b32_e32 v2, 16, v2
	v_add_f32_e32 v114, v26, v2
	ds_read_u16 v2, v1 offset:4688
	s_waitcnt lgkmcnt(0)
; #define LAS __attribute__((address_space(3)))
; DI float bf2f(bf16 b) { return __uint_as_float(((unsigned)b) << 16); }
; DI void gla_stage3(const Ctx& c0, int layer, int unit, int cb, LAS unsigned char* lds) {
;     ...
;     for (int vb = 0; vb < 4; ++vb) {
; #pragma unroll
;         for (int rg = 0; rg < 16; ++rg) o[vb][rg] += bf2f(*(const LAS bf16*)(Re + ((rg & 3) + 8 * (rg >> 2)) * G3_PITCH + 64 * vb));
;         asm volatile("" ::: "memory");
;     }
	v_lshlrev_b32_e32 v2, 16, v2
	v_add_f32_e32 v113, v27, v2
	ds_read_u16 v2, v1 offset:4960
	s_waitcnt lgkmcnt(0)
	v_lshlrev_b32_e32 v2, 16, v2
	v_add_f32_e32 v112, v28, v2
	ds_read_u16 v2, v1 offset:5232
	s_waitcnt lgkmcnt(0)
	v_lshlrev_b32_e32 v2, 16, v2
	v_add_f32_e32 v111, v29, v2
	ds_read_u16 v2, v1 offset:6592
	s_waitcnt lgkmcnt(0)
	v_lshlrev_b32_e32 v2, 16, v2
	v_add_f32_e32 v110, v30, v2
	ds_read_u16 v2, v1 offset:6864
	s_waitcnt lgkmcnt(0)
	v_lshlrev_b32_e32 v2, 16, v2
	v_add_f32_e32 v109, v31, v2
	ds_read_u16 v2, v1 offset:7136
	s_waitcnt lgkmcnt(0)
	v_lshlrev_b32_e32 v2, 16, v2
	v_add_f32_e32 v108, v32, v2
	ds_read_u16 v2, v1 offset:7408
	s_waitcnt lgkmcnt(0)
	v_lshlrev_b32_e32 v2, 16, v2
	v_add_f32_e32 v107, v33, v2
	ds_read_u16 v2, v1 offset:128
	s_waitcnt lgkmcnt(0)
	v_lshlrev_b32_e32 v2, 16, v2
	v_add_f32_e32 v106, v34, v2
	ds_read_u16 v2, v1 offset:400
	s_waitcnt lgkmcnt(0)
	v_lshlrev_b32_e32 v2, 16, v2
	v_add_f32_e32 v105, v35, v2
	ds_read_u16 v2, v1 offset:672
	s_waitcnt lgkmcnt(0)
	v_lshlrev_b32_e32 v2, 16, v2
	v_add_f32_e32 v104, v36, v2
	ds_read_u16 v2, v1 offset:944
	s_waitcnt lgkmcnt(0)
	v_lshlrev_b32_e32 v2, 16, v2
	v_add_f32_e32 v103, v37, v2
	ds_read_u16 v2, v1 offset:2304
	s_waitcnt lgkmcnt(0)
	v_lshlrev_b32_e32 v2, 16, v2
	v_add_f32_e32 v102, v38, v2
	ds_read_u16 v2, v1 offset:2576
	s_waitcnt lgkmcnt(0)
	v_lshlrev_b32_e32 v2, 16, v2
	v_add_f32_e32 v39, v39, v2
	ds_read_u16 v2, v1 offset:2848
	s_waitcnt lgkmcnt(0)
	v_lshlrev_b32_e32 v2, 16, v2
	v_add_f32_e32 v38, v40, v2
	ds_read_u16 v2, v1 offset:3120
	s_waitcnt lgkmcnt(0)
	v_lshlrev_b32_e32 v2, 16, v2
	v_add_f32_e32 v37, v41, v2
	ds_read_u16 v2, v1 offset:4480
	s_waitcnt lgkmcnt(0)
	v_lshlrev_b32_e32 v2, 16, v2
	v_add_f32_e32 v36, v42, v2
	ds_read_u16 v2, v1 offset:4752
	s_waitcnt lgkmcnt(0)
	v_lshlrev_b32_e32 v2, 16, v2
	v_add_f32_e32 v34, v43, v2
	ds_read_u16 v2, v1 offset:5024
	s_waitcnt lgkmcnt(0)
	v_lshlrev_b32_e32 v2, 16, v2
	v_add_f32_e32 v33, v44, v2
	ds_read_u16 v2, v1 offset:5296
	s_waitcnt lgkmcnt(0)
	v_lshlrev_b32_e32 v2, 16, v2
	v_add_f32_e32 v32, v45, v2
	ds_read_u16 v2, v1 offset:6656
	s_waitcnt lgkmcnt(0)
	v_lshlrev_b32_e32 v2, 16, v2
	v_add_f32_e32 v30, v46, v2
	ds_read_u16 v2, v1 offset:6928
	s_waitcnt lgkmcnt(0)
	v_lshlrev_b32_e32 v2, 16, v2
	v_add_f32_e32 v29, v47, v2
	ds_read_u16 v2, v1 offset:7200
	s_waitcnt lgkmcnt(0)
	v_lshlrev_b32_e32 v2, 16, v2
	v_add_f32_e32 v28, v48, v2
	ds_read_u16 v2, v1 offset:7472
	s_waitcnt lgkmcnt(0)
	v_lshlrev_b32_e32 v2, 16, v2
	v_add_f32_e32 v26, v49, v2
	ds_read_u16 v2, v1 offset:192
	s_waitcnt lgkmcnt(0)
	v_lshlrev_b32_e32 v2, 16, v2
	v_add_f32_e32 v19, v50, v2
	ds_read_u16 v2, v1 offset:464
	s_waitcnt lgkmcnt(0)
	v_lshlrev_b32_e32 v2, 16, v2
	v_add_f32_e32 v18, v51, v2
	ds_read_u16 v2, v1 offset:736
	s_waitcnt lgkmcnt(0)
	v_lshlrev_b32_e32 v2, 16, v2
	v_add_f32_e32 v17, v52, v2
	ds_read_u16 v2, v1 offset:1008
	s_waitcnt lgkmcnt(0)
	v_lshlrev_b32_e32 v2, 16, v2
	v_add_f32_e32 v16, v53, v2
	ds_read_u16 v2, v1 offset:2368
	s_waitcnt lgkmcnt(0)
	v_lshlrev_b32_e32 v2, 16, v2
	v_add_f32_e32 v15, v54, v2
	ds_read_u16 v2, v1 offset:2640
	s_waitcnt lgkmcnt(0)
	v_lshlrev_b32_e32 v2, 16, v2
	v_add_f32_e32 v14, v55, v2
	ds_read_u16 v2, v1 offset:2912
	s_waitcnt lgkmcnt(0)
	v_lshlrev_b32_e32 v2, 16, v2
	v_add_f32_e32 v13, v56, v2
	ds_read_u16 v2, v1 offset:3184
	s_waitcnt lgkmcnt(0)
	v_lshlrev_b32_e32 v2, 16, v2
	v_add_f32_e32 v12, v57, v2
	ds_read_u16 v2, v1 offset:4544
	s_waitcnt lgkmcnt(0)
	v_lshlrev_b32_e32 v2, 16, v2
	v_add_f32_e32 v11, v58, v2
	ds_read_u16 v2, v1 offset:4816
	s_waitcnt lgkmcnt(0)
	v_lshlrev_b32_e32 v2, 16, v2
	v_add_f32_e32 v10, v59, v2
	ds_read_u16 v2, v1 offset:5088
	s_waitcnt lgkmcnt(0)
	v_lshlrev_b32_e32 v2, 16, v2
	v_add_f32_e32 v9, v60, v2
	ds_read_u16 v2, v1 offset:5360
	s_waitcnt lgkmcnt(0)
	v_lshlrev_b32_e32 v2, 16, v2
	v_add_f32_e32 v8, v61, v2
	ds_read_u16 v2, v1 offset:6720
	s_waitcnt lgkmcnt(0)
	v_lshlrev_b32_e32 v2, 16, v2
	v_add_f32_e32 v7, v62, v2
	ds_read_u16 v2, v1 offset:6992
	s_waitcnt lgkmcnt(0)
	v_lshlrev_b32_e32 v2, 16, v2
	v_add_f32_e32 v6, v63, v2
	ds_read_u16 v2, v1 offset:7264
	s_waitcnt lgkmcnt(0)
	v_lshlrev_b32_e32 v2, 16, v2
	v_add_f32_e32 v5, v64, v2
	ds_read_u16 v2, v1 offset:7536
	s_waitcnt lgkmcnt(0)
	s_waitcnt lgkmcnt(0)
; DI void gla_stage3(const Ctx& c0, int layer, int unit, int cb, LAS unsigned char* lds) {
;     ...
;     float rs[16];
; #pragma unroll
;     for (int rg = 0; rg < 16; ++rg) { float ss = o[0][rg] * o[0][rg] + o[1][rg] * o[1][rg] + o[2][rg] * o[2][rg] + o[3][rg] * o[3][rg];
;         ss += __shfl_xor(ss, 1); ss += __shfl_xor(ss, 2); ss += __shfl_xor(ss, 4); ss += __shfl_xor(ss, 8); ss += __shfl_xor(ss, 16);
;         rs[rg] = 1.f / sqrtf(ss * (1.f / 128.f) + EPS); }
	v_lshlrev_b32_e32 v2, 16, v2
	v_add_f32_e32 v4, v65, v2
	v_cndmask_b32_e32 v2, v93, v94, vcc
	v_cmp_lt_i32_e32 vcc, v96, v95
	v_lshlrev_b32_e32 v2, 2, v2
	s_nop 0
	v_cndmask_b32_e32 v3, v93, v96, vcc
	v_cmp_lt_i32_e32 vcc, v97, v95
	v_lshlrev_b32_e32 v3, 2, v3
	s_nop 0
	v_cndmask_b32_e32 v20, v93, v97, vcc
	v_cmp_lt_i32_e32 vcc, v98, v95
	v_lshlrev_b32_e32 v20, 2, v20
	s_nop 0
	v_cndmask_b32_e32 v21, v93, v98, vcc
	v_cmp_lt_i32_e32 vcc, v99, v95
	v_lshlrev_b32_e32 v47, 2, v21
	s_nop 0
	v_cndmask_b32_e32 v21, v93, v99, vcc
	v_lshlrev_b32_e32 v48, 2, v21
	v_mul_f32_e32 v21, v122, v122
	v_fmac_f32_e32 v21, v138, v138
	v_fmac_f32_e32 v21, v106, v106
	v_fmac_f32_e32 v21, v19, v19
	s_nop 1
	v_add_f32_dpp v21, v21, v21 quad_perm:[1,0,3,2] row_mask:0xf bank_mask:0xf
	s_nop 1
	v_add_f32_dpp v21, v21, v21 quad_perm:[2,3,0,1] row_mask:0xf bank_mask:0xf
	s_nop 1
	v_add_f32_dpp v21, v21, v21 row_half_mirror row_mask:0xf bank_mask:0xf
	s_nop 1
	v_add_f32_dpp v21, v21, v21 row_mirror row_mask:0xf bank_mask:0xf
	v_mov_b32_e32 v22, v21
	v_mov_b32_e32 v23, v21
	s_nop 1
	v_permlane16_swap_b32_e32 v22, v23
	v_add_f32_e32 v21, v22, v23
	v_fmamk_f32 v21, v21, 0x3c000000, v100
	v_cmp_gt_f32_e32 vcc, s34, v21
	v_mul_f32_e32 v22, 0x4f800000, v21
	s_nop 0
	v_cndmask_b32_e32 v21, v21, v22, vcc
	v_sqrt_f32_e32 v22, v21
	s_nop 0
	v_add_u32_e32 v23, -1, v22
	v_fma_f32 v24, -v23, v22, v21
	v_cmp_ge_f32_e64 s[4:5], 0, v24
	v_add_u32_e32 v24, 1, v22
	s_nop 0
	v_cndmask_b32_e64 v23, v22, v23, s[4:5]
	v_fma_f32 v22, -v24, v22, v21
	v_cmp_lt_f32_e64 s[4:5], 0, v22
	s_nop 1
	v_cndmask_b32_e64 v22, v23, v24, s[4:5]
	v_mul_f32_e32 v23, 0x37800000, v22
	v_cndmask_b32_e32 v22, v22, v23, vcc
	v_cmp_class_f32_e32 vcc, v21, v101
	s_nop 1
	v_cndmask_b32_e32 v21, v22, v21, vcc
	s_nop 0
	v_div_scale_f32 v24, vcc, 1.0, v21, 1.0
	v_rcp_f32_e32 v46, v21
	v_mul_f32_e32 v21, v121, v121
	v_fmac_f32_e32 v21, v137, v137
	v_fmac_f32_e32 v21, v105, v105
	v_fmac_f32_e32 v21, v18, v18
	s_nop 1
	v_add_f32_dpp v21, v21, v21 quad_perm:[1,0,3,2] row_mask:0xf bank_mask:0xf
	v_mul_f32_e32 v19, v19, v46
	s_nop 1
	v_add_f32_dpp v21, v21, v21 quad_perm:[2,3,0,1] row_mask:0xf bank_mask:0xf
	s_nop 1
	v_add_f32_dpp v21, v21, v21 row_half_mirror row_mask:0xf bank_mask:0xf
	s_nop 1
	v_add_f32_dpp v21, v21, v21 row_mirror row_mask:0xf bank_mask:0xf
	v_mov_b32_e32 v22, v21
	v_mov_b32_e32 v23, v21
	s_nop 1
	v_permlane16_swap_b32_e32 v22, v23
	v_add_f32_e32 v21, v22, v23
	v_fmamk_f32 v21, v21, 0x3c000000, v100
	v_cmp_gt_f32_e32 vcc, s34, v21
	v_mul_f32_e32 v22, 0x4f800000, v21
	s_nop 0
	v_cndmask_b32_e32 v21, v21, v22, vcc
	v_sqrt_f32_e32 v22, v21
	s_nop 0
	v_add_u32_e32 v23, -1, v22
	v_fma_f32 v24, -v23, v22, v21
	v_cmp_ge_f32_e64 s[4:5], 0, v24
	v_add_u32_e32 v24, 1, v22
	s_nop 0
	v_cndmask_b32_e64 v23, v22, v23, s[4:5]
	v_fma_f32 v22, -v24, v22, v21
	v_cmp_lt_f32_e64 s[4:5], 0, v22
	s_nop 1
	v_cndmask_b32_e64 v22, v23, v24, s[4:5]
	v_mul_f32_e32 v23, 0x37800000, v22
	v_cndmask_b32_e32 v22, v22, v23, vcc
	v_cmp_class_f32_e32 vcc, v21, v101
	s_nop 1
	v_cndmask_b32_e32 v21, v22, v21, vcc
	s_nop 0
	v_div_scale_f32 v24, vcc, 1.0, v21, 1.0
	v_rcp_f32_e32 v45, v21
	v_mul_f32_e32 v21, v120, v120
	v_fmac_f32_e32 v21, v136, v136
	v_fmac_f32_e32 v21, v104, v104
	v_fmac_f32_e32 v21, v17, v17
	s_nop 1
	v_add_f32_dpp v21, v21, v21 quad_perm:[1,0,3,2] row_mask:0xf bank_mask:0xf
	v_mul_f32_e32 v18, v18, v45
	s_nop 1
	v_add_f32_dpp v21, v21, v21 quad_perm:[2,3,0,1] row_mask:0xf bank_mask:0xf
	s_nop 1
	v_add_f32_dpp v21, v21, v21 row_half_mirror row_mask:0xf bank_mask:0xf
	s_nop 1
	v_add_f32_dpp v21, v21, v21 row_mirror row_mask:0xf bank_mask:0xf
	v_mov_b32_e32 v22, v21
	v_mov_b32_e32 v23, v21
	s_nop 1
	v_permlane16_swap_b32_e32 v22, v23
	v_add_f32_e32 v21, v22, v23
	v_fmamk_f32 v21, v21, 0x3c000000, v100
	v_cmp_gt_f32_e32 vcc, s34, v21
	v_mul_f32_e32 v22, 0x4f800000, v21
	s_nop 0
	v_cndmask_b32_e32 v21, v21, v22, vcc
	v_sqrt_f32_e32 v22, v21
	s_nop 0
	v_add_u32_e32 v23, -1, v22
	v_fma_f32 v24, -v23, v22, v21
	v_cmp_ge_f32_e64 s[4:5], 0, v24
	v_add_u32_e32 v24, 1, v22
	s_nop 0
	v_cndmask_b32_e64 v23, v22, v23, s[4:5]
	v_fma_f32 v22, -v24, v22, v21
	v_cmp_lt_f32_e64 s[4:5], 0, v22
	s_nop 1
	v_cndmask_b32_e64 v22, v23, v24, s[4:5]
	v_mul_f32_e32 v23, 0x37800000, v22
	v_cndmask_b32_e32 v22, v22, v23, vcc
	v_cmp_class_f32_e32 vcc, v21, v101
	s_nop 1
	v_cndmask_b32_e32 v21, v22, v21, vcc
	s_nop 0
	v_div_scale_f32 v24, vcc, 1.0, v21, 1.0
	v_rcp_f32_e32 v44, v21
	v_mul_f32_e32 v21, v119, v119
	v_fmac_f32_e32 v21, v135, v135
	v_fmac_f32_e32 v21, v103, v103
	v_fmac_f32_e32 v21, v16, v16
	s_nop 1
	v_add_f32_dpp v21, v21, v21 quad_perm:[1,0,3,2] row_mask:0xf bank_mask:0xf
	v_mul_f32_e32 v17, v17, v44
	s_nop 1
	v_add_f32_dpp v21, v21, v21 quad_perm:[2,3,0,1] row_mask:0xf bank_mask:0xf
	s_nop 1
	v_add_f32_dpp v21, v21, v21 row_half_mirror row_mask:0xf bank_mask:0xf
	s_nop 1
	v_add_f32_dpp v21, v21, v21 row_mirror row_mask:0xf bank_mask:0xf
	v_mov_b32_e32 v22, v21
	v_mov_b32_e32 v23, v21
	s_nop 1
	v_permlane16_swap_b32_e32 v22, v23
	v_add_f32_e32 v21, v22, v23
	v_fmamk_f32 v21, v21, 0x3c000000, v100
	v_cmp_gt_f32_e32 vcc, s34, v21
	v_mul_f32_e32 v22, 0x4f800000, v21
	s_nop 0
	v_cndmask_b32_e32 v21, v21, v22, vcc
	v_sqrt_f32_e32 v22, v21
	s_nop 0
	v_add_u32_e32 v23, -1, v22
	v_fma_f32 v24, -v23, v22, v21
	v_cmp_ge_f32_e64 s[4:5], 0, v24
	v_add_u32_e32 v24, 1, v22
	s_nop 0
	v_cndmask_b32_e64 v23, v22, v23, s[4:5]
	v_fma_f32 v22, -v24, v22, v21
	v_cmp_lt_f32_e64 s[4:5], 0, v22
	s_nop 1
	v_cndmask_b32_e64 v22, v23, v24, s[4:5]
	v_mul_f32_e32 v23, 0x37800000, v22
	v_cndmask_b32_e32 v22, v22, v23, vcc
	v_cmp_class_f32_e32 vcc, v21, v101
	s_nop 1
; DI void gla_stage3(const Ctx& c0, int layer, int unit, int cb, LAS unsigned char* lds) {
;     ...
;     for (int rg = 0; rg < 16; ++rg) { float ss = o[0][rg] * o[0][rg] + o[1][rg] * o[1][rg] + o[2][rg] * o[2][rg] + o[3][rg] * o[3][rg];
;         ss += __shfl_xor(ss, 1); ss += __shfl_xor(ss, 2); ss += __shfl_xor(ss, 4); ss += __shfl_xor(ss, 8); ss += __shfl_xor(ss, 16);
;         rs[rg] = 1.f / sqrtf(ss * (1.f / 128.f) + EPS); }
	v_cndmask_b32_e32 v21, v22, v21, vcc
	s_nop 0
	v_div_scale_f32 v24, vcc, 1.0, v21, 1.0
	v_rcp_f32_e32 v43, v21
	v_mul_f32_e32 v21, v118, v118
	v_fmac_f32_e32 v21, v134, v134
	v_fmac_f32_e32 v21, v102, v102
	v_fmac_f32_e32 v21, v15, v15
	s_nop 1
	v_add_f32_dpp v21, v21, v21 quad_perm:[1,0,3,2] row_mask:0xf bank_mask:0xf
	v_mul_f32_e32 v16, v16, v43
	s_nop 1
	v_add_f32_dpp v21, v21, v21 quad_perm:[2,3,0,1] row_mask:0xf bank_mask:0xf
	s_nop 1
	v_add_f32_dpp v21, v21, v21 row_half_mirror row_mask:0xf bank_mask:0xf
	s_nop 1
	v_add_f32_dpp v21, v21, v21 row_mirror row_mask:0xf bank_mask:0xf
	v_mov_b32_e32 v22, v21
	v_mov_b32_e32 v23, v21
	s_nop 1
	v_permlane16_swap_b32_e32 v22, v23
	v_add_f32_e32 v21, v22, v23
	v_fmamk_f32 v21, v21, 0x3c000000, v100
	v_cmp_gt_f32_e32 vcc, s34, v21
	v_mul_f32_e32 v22, 0x4f800000, v21
	s_nop 0
	v_cndmask_b32_e32 v21, v21, v22, vcc
	v_sqrt_f32_e32 v22, v21
	s_nop 0
	v_add_u32_e32 v23, -1, v22
	v_fma_f32 v24, -v23, v22, v21
	v_cmp_ge_f32_e64 s[4:5], 0, v24
	v_add_u32_e32 v24, 1, v22
	s_nop 0
	v_cndmask_b32_e64 v23, v22, v23, s[4:5]
	v_fma_f32 v22, -v24, v22, v21
	v_cmp_lt_f32_e64 s[4:5], 0, v22
	s_nop 1
	v_cndmask_b32_e64 v22, v23, v24, s[4:5]
	v_mul_f32_e32 v23, 0x37800000, v22
	v_cndmask_b32_e32 v22, v22, v23, vcc
	v_cmp_class_f32_e32 vcc, v21, v101
	s_nop 1
	v_cndmask_b32_e32 v21, v22, v21, vcc
	s_nop 0
	v_div_scale_f32 v24, vcc, 1.0, v21, 1.0
	v_rcp_f32_e32 v42, v21
	v_mul_f32_e32 v21, v117, v117
	v_fmac_f32_e32 v21, v133, v133
	v_fmac_f32_e32 v21, v39, v39
	v_fmac_f32_e32 v21, v14, v14
	s_nop 1
	v_add_f32_dpp v21, v21, v21 quad_perm:[1,0,3,2] row_mask:0xf bank_mask:0xf
	v_mul_f32_e32 v15, v15, v42
	s_nop 1
	v_add_f32_dpp v21, v21, v21 quad_perm:[2,3,0,1] row_mask:0xf bank_mask:0xf
	s_nop 1
	v_add_f32_dpp v21, v21, v21 row_half_mirror row_mask:0xf bank_mask:0xf
	s_nop 1
	v_add_f32_dpp v21, v21, v21 row_mirror row_mask:0xf bank_mask:0xf
	v_mov_b32_e32 v22, v21
	v_mov_b32_e32 v23, v21
	s_nop 1
	v_permlane16_swap_b32_e32 v22, v23
	v_add_f32_e32 v21, v22, v23
	v_fmamk_f32 v21, v21, 0x3c000000, v100
	v_cmp_gt_f32_e32 vcc, s34, v21
	v_mul_f32_e32 v22, 0x4f800000, v21
	s_nop 0
	v_cndmask_b32_e32 v21, v21, v22, vcc
	v_sqrt_f32_e32 v22, v21
	s_nop 0
	v_add_u32_e32 v23, -1, v22
	v_fma_f32 v24, -v23, v22, v21
	v_cmp_ge_f32_e64 s[4:5], 0, v24
	v_add_u32_e32 v24, 1, v22
	s_nop 0
	v_cndmask_b32_e64 v23, v22, v23, s[4:5]
	v_fma_f32 v22, -v24, v22, v21
	v_cmp_lt_f32_e64 s[4:5], 0, v22
	s_nop 1
	v_cndmask_b32_e64 v22, v23, v24, s[4:5]
	v_mul_f32_e32 v23, 0x37800000, v22
	v_cndmask_b32_e32 v22, v22, v23, vcc
	v_cmp_class_f32_e32 vcc, v21, v101
	s_nop 1
	v_cndmask_b32_e32 v21, v22, v21, vcc
	s_nop 0
	v_div_scale_f32 v24, vcc, 1.0, v21, 1.0
	v_rcp_f32_e32 v41, v21
	v_mul_f32_e32 v21, v116, v116
	v_fmac_f32_e32 v21, v132, v132
	v_fmac_f32_e32 v21, v38, v38
	v_fmac_f32_e32 v21, v13, v13
	s_nop 1
	v_add_f32_dpp v21, v21, v21 quad_perm:[1,0,3,2] row_mask:0xf bank_mask:0xf
	v_mul_f32_e32 v39, v39, v41
	v_mul_f32_e32 v14, v14, v41
	s_nop 1
	v_add_f32_dpp v21, v21, v21 quad_perm:[2,3,0,1] row_mask:0xf bank_mask:0xf
	s_nop 1
	v_add_f32_dpp v21, v21, v21 row_half_mirror row_mask:0xf bank_mask:0xf
	s_nop 1
	v_add_f32_dpp v21, v21, v21 row_mirror row_mask:0xf bank_mask:0xf
	v_mov_b32_e32 v22, v21
	v_mov_b32_e32 v23, v21
	s_nop 1
	v_permlane16_swap_b32_e32 v22, v23
	v_add_f32_e32 v21, v22, v23
	v_fmamk_f32 v21, v21, 0x3c000000, v100
	v_cmp_gt_f32_e32 vcc, s34, v21
	v_mul_f32_e32 v22, 0x4f800000, v21
	s_nop 0
	v_cndmask_b32_e32 v21, v21, v22, vcc
	v_sqrt_f32_e32 v22, v21
	s_nop 0
	v_add_u32_e32 v23, -1, v22
	v_fma_f32 v24, -v23, v22, v21
	v_cmp_ge_f32_e64 s[4:5], 0, v24
	v_add_u32_e32 v24, 1, v22
	s_nop 0
	v_cndmask_b32_e64 v23, v22, v23, s[4:5]
	v_fma_f32 v22, -v24, v22, v21
	v_cmp_lt_f32_e64 s[4:5], 0, v22
	s_nop 1
	v_cndmask_b32_e64 v22, v23, v24, s[4:5]
	v_mul_f32_e32 v23, 0x37800000, v22
	v_cndmask_b32_e32 v22, v22, v23, vcc
	v_cmp_class_f32_e32 vcc, v21, v101
	s_nop 1
	v_cndmask_b32_e32 v21, v22, v21, vcc
	s_nop 0
	v_div_scale_f32 v24, vcc, 1.0, v21, 1.0
	v_rcp_f32_e32 v40, v21
	v_mul_f32_e32 v21, v115, v115
	v_fmac_f32_e32 v21, v131, v131
	v_fmac_f32_e32 v21, v37, v37
	v_fmac_f32_e32 v21, v12, v12
	s_nop 1
	v_add_f32_dpp v21, v21, v21 quad_perm:[1,0,3,2] row_mask:0xf bank_mask:0xf
	v_mul_f32_e32 v38, v38, v40
	v_mul_f32_e32 v13, v13, v40
	s_nop 1
	v_add_f32_dpp v21, v21, v21 quad_perm:[2,3,0,1] row_mask:0xf bank_mask:0xf
	s_nop 1
	v_add_f32_dpp v21, v21, v21 row_half_mirror row_mask:0xf bank_mask:0xf
	s_nop 1
	v_add_f32_dpp v21, v21, v21 row_mirror row_mask:0xf bank_mask:0xf
	v_mov_b32_e32 v22, v21
	v_mov_b32_e32 v23, v21
	s_nop 1
	v_permlane16_swap_b32_e32 v22, v23
	v_add_f32_e32 v21, v22, v23
	v_fmamk_f32 v21, v21, 0x3c000000, v100
	v_cmp_gt_f32_e32 vcc, s34, v21
	v_mul_f32_e32 v22, 0x4f800000, v21
	s_nop 0
	v_cndmask_b32_e32 v21, v21, v22, vcc
	v_sqrt_f32_e32 v22, v21
	s_nop 0
	v_add_u32_e32 v23, -1, v22
	v_fma_f32 v24, -v23, v22, v21
	v_cmp_ge_f32_e64 s[4:5], 0, v24
	v_add_u32_e32 v24, 1, v22
	s_nop 0
	v_cndmask_b32_e64 v23, v22, v23, s[4:5]
	v_fma_f32 v22, -v24, v22, v21
	v_cmp_lt_f32_e64 s[4:5], 0, v22
	s_nop 1
	v_cndmask_b32_e64 v22, v23, v24, s[4:5]
	v_mul_f32_e32 v23, 0x37800000, v22
	v_cndmask_b32_e32 v22, v22, v23, vcc
	v_cmp_class_f32_e32 vcc, v21, v101
	s_nop 1
	v_cndmask_b32_e32 v21, v22, v21, vcc
	s_nop 0
	v_div_scale_f32 v24, vcc, 1.0, v21, 1.0
	v_rcp_f32_e32 v35, v21
	v_mul_f32_e32 v21, v114, v114
	v_fmac_f32_e32 v21, v130, v130
	v_fmac_f32_e32 v21, v36, v36
	v_fmac_f32_e32 v21, v11, v11
	s_nop 1
	v_add_f32_dpp v21, v21, v21 quad_perm:[1,0,3,2] row_mask:0xf bank_mask:0xf
	v_mul_f32_e32 v37, v37, v35
	v_mul_f32_e32 v12, v12, v35
; DI void gla_stage3(const Ctx& c0, int layer, int unit, int cb, LAS unsigned char* lds) {
;     ...
;     for (int rg = 0; rg < 16; ++rg) { float ss = o[0][rg] * o[0][rg] + o[1][rg] * o[1][rg] + o[2][rg] * o[2][rg] + o[3][rg] * o[3][rg];
;         ss += __shfl_xor(ss, 1); ss += __shfl_xor(ss, 2); ss += __shfl_xor(ss, 4); ss += __shfl_xor(ss, 8); ss += __shfl_xor(ss, 16);
;         rs[rg] = 1.f / sqrtf(ss * (1.f / 128.f) + EPS); }
	s_nop 1
	v_add_f32_dpp v21, v21, v21 quad_perm:[2,3,0,1] row_mask:0xf bank_mask:0xf
	s_nop 1
	v_add_f32_dpp v21, v21, v21 row_half_mirror row_mask:0xf bank_mask:0xf
	s_nop 1
	v_add_f32_dpp v21, v21, v21 row_mirror row_mask:0xf bank_mask:0xf
	v_mov_b32_e32 v22, v21
	v_mov_b32_e32 v23, v21
	s_nop 1
	v_permlane16_swap_b32_e32 v22, v23
	v_add_f32_e32 v21, v22, v23
	v_fmamk_f32 v21, v21, 0x3c000000, v100
	v_cmp_gt_f32_e32 vcc, s34, v21
	v_mul_f32_e32 v22, 0x4f800000, v21
	s_nop 0
	v_cndmask_b32_e32 v21, v21, v22, vcc
	v_sqrt_f32_e32 v22, v21
	s_nop 0
	v_add_u32_e32 v23, -1, v22
	v_fma_f32 v24, -v23, v22, v21
	v_cmp_ge_f32_e64 s[4:5], 0, v24
	v_add_u32_e32 v24, 1, v22
	s_nop 0
	v_cndmask_b32_e64 v23, v22, v23, s[4:5]
	v_fma_f32 v22, -v24, v22, v21
	v_cmp_lt_f32_e64 s[4:5], 0, v22
	s_nop 1
	v_cndmask_b32_e64 v22, v23, v24, s[4:5]
	v_mul_f32_e32 v23, 0x37800000, v22
	v_cndmask_b32_e32 v22, v22, v23, vcc
	v_cmp_class_f32_e32 vcc, v21, v101
	s_nop 1
	v_cndmask_b32_e32 v21, v22, v21, vcc
	s_nop 0
	v_div_scale_f32 v24, vcc, 1.0, v21, 1.0
	v_rcp_f32_e32 v31, v21
	v_mul_f32_e32 v21, v113, v113
	v_fmac_f32_e32 v21, v129, v129
	v_fmac_f32_e32 v21, v34, v34
	v_fmac_f32_e32 v21, v10, v10
	s_nop 1
	v_add_f32_dpp v21, v21, v21 quad_perm:[1,0,3,2] row_mask:0xf bank_mask:0xf
	v_mul_f32_e32 v36, v36, v31
	v_mul_f32_e32 v11, v11, v31
	s_nop 1
	v_add_f32_dpp v21, v21, v21 quad_perm:[2,3,0,1] row_mask:0xf bank_mask:0xf
	s_nop 1
	v_add_f32_dpp v21, v21, v21 row_half_mirror row_mask:0xf bank_mask:0xf
	s_nop 1
	v_add_f32_dpp v21, v21, v21 row_mirror row_mask:0xf bank_mask:0xf
	v_mov_b32_e32 v22, v21
	v_mov_b32_e32 v23, v21
	s_nop 1
	v_permlane16_swap_b32_e32 v22, v23
	v_add_f32_e32 v21, v22, v23
	v_fmamk_f32 v21, v21, 0x3c000000, v100
	v_cmp_gt_f32_e32 vcc, s34, v21
	v_mul_f32_e32 v22, 0x4f800000, v21
	s_nop 0
	v_cndmask_b32_e32 v21, v21, v22, vcc
	v_sqrt_f32_e32 v22, v21
	s_nop 0
	v_add_u32_e32 v23, -1, v22
	v_fma_f32 v24, -v23, v22, v21
	v_cmp_ge_f32_e64 s[4:5], 0, v24
	v_add_u32_e32 v24, 1, v22
	s_nop 0
	v_cndmask_b32_e64 v23, v22, v23, s[4:5]
	v_fma_f32 v22, -v24, v22, v21
	v_cmp_lt_f32_e64 s[4:5], 0, v22
	s_nop 1
	v_cndmask_b32_e64 v22, v23, v24, s[4:5]
	v_mul_f32_e32 v23, 0x37800000, v22
	v_cndmask_b32_e32 v22, v22, v23, vcc
	v_cmp_class_f32_e32 vcc, v21, v101
	s_nop 1
	v_cndmask_b32_e32 v21, v22, v21, vcc
	s_nop 0
	v_div_scale_f32 v24, vcc, 1.0, v21, 1.0
	v_rcp_f32_e32 v27, v21
	v_mul_f32_e32 v21, v112, v112
	v_fmac_f32_e32 v21, v128, v128
	v_fmac_f32_e32 v21, v33, v33
	v_fmac_f32_e32 v21, v9, v9
	s_nop 1
	v_add_f32_dpp v21, v21, v21 quad_perm:[1,0,3,2] row_mask:0xf bank_mask:0xf
	v_mul_f32_e32 v34, v34, v27
	v_mul_f32_e32 v10, v10, v27
	s_nop 1
	v_add_f32_dpp v21, v21, v21 quad_perm:[2,3,0,1] row_mask:0xf bank_mask:0xf
	s_nop 1
	v_add_f32_dpp v21, v21, v21 row_half_mirror row_mask:0xf bank_mask:0xf
	s_nop 1
	v_add_f32_dpp v21, v21, v21 row_mirror row_mask:0xf bank_mask:0xf
	v_mov_b32_e32 v22, v21
	v_mov_b32_e32 v23, v21
	s_nop 1
	v_permlane16_swap_b32_e32 v22, v23
	v_add_f32_e32 v21, v22, v23
	v_fmamk_f32 v21, v21, 0x3c000000, v100
	v_cmp_gt_f32_e32 vcc, s34, v21
	v_mul_f32_e32 v22, 0x4f800000, v21
	s_nop 0
	v_cndmask_b32_e32 v21, v21, v22, vcc
	v_sqrt_f32_e32 v22, v21
	s_nop 0
	v_add_u32_e32 v23, -1, v22
	v_fma_f32 v24, -v23, v22, v21
	v_cmp_ge_f32_e64 s[4:5], 0, v24
	v_add_u32_e32 v24, 1, v22
	s_nop 0
	v_cndmask_b32_e64 v23, v22, v23, s[4:5]
	v_fma_f32 v22, -v24, v22, v21
	v_cmp_lt_f32_e64 s[4:5], 0, v22
	s_nop 1
	v_cndmask_b32_e64 v22, v23, v24, s[4:5]
	v_mul_f32_e32 v23, 0x37800000, v22
	v_cndmask_b32_e32 v22, v22, v23, vcc
	v_cmp_class_f32_e32 vcc, v21, v101
	s_nop 1
	v_cndmask_b32_e32 v21, v22, v21, vcc
	s_nop 0
	v_div_scale_f32 v24, vcc, 1.0, v21, 1.0
	v_rcp_f32_e32 v25, v21
	v_mul_f32_e32 v21, v111, v111
	v_fmac_f32_e32 v21, v127, v127
	v_fmac_f32_e32 v21, v32, v32
	v_fmac_f32_e32 v21, v8, v8
	s_nop 1
	v_add_f32_dpp v21, v21, v21 quad_perm:[1,0,3,2] row_mask:0xf bank_mask:0xf
	v_mul_f32_e32 v33, v33, v25
	v_mul_f32_e32 v9, v9, v25
	s_nop 1
	v_add_f32_dpp v21, v21, v21 quad_perm:[2,3,0,1] row_mask:0xf bank_mask:0xf
	s_nop 1
	v_add_f32_dpp v21, v21, v21 row_half_mirror row_mask:0xf bank_mask:0xf
	s_nop 1
	v_add_f32_dpp v21, v21, v21 row_mirror row_mask:0xf bank_mask:0xf
	v_mov_b32_e32 v22, v21
	v_mov_b32_e32 v23, v21
	s_nop 1
	v_permlane16_swap_b32_e32 v22, v23
	v_add_f32_e32 v21, v22, v23
	v_fmamk_f32 v21, v21, 0x3c000000, v100
	v_cmp_gt_f32_e32 vcc, s34, v21
	v_mul_f32_e32 v22, 0x4f800000, v21
	s_nop 0
	v_cndmask_b32_e32 v21, v21, v22, vcc
	v_sqrt_f32_e32 v22, v21
	s_nop 0
	v_add_u32_e32 v23, -1, v22
	v_fma_f32 v24, -v23, v22, v21
	v_cmp_ge_f32_e64 s[4:5], 0, v24
	v_add_u32_e32 v24, 1, v22
	s_nop 0
	v_cndmask_b32_e64 v23, v22, v23, s[4:5]
	v_fma_f32 v22, -v24, v22, v21
	v_cmp_lt_f32_e64 s[4:5], 0, v22
	s_nop 1
	v_cndmask_b32_e64 v22, v23, v24, s[4:5]
	v_mul_f32_e32 v23, 0x37800000, v22
	v_cndmask_b32_e32 v22, v22, v23, vcc
	v_cmp_class_f32_e32 vcc, v21, v101
	s_nop 1
	v_cndmask_b32_e32 v21, v22, v21, vcc
	s_nop 0
	v_div_scale_f32 v24, vcc, 1.0, v21, 1.0
	v_rcp_f32_e32 v24, v21
	v_mul_f32_e32 v21, v110, v110
	v_fmac_f32_e32 v21, v126, v126
	v_fmac_f32_e32 v21, v30, v30
	v_fmac_f32_e32 v21, v7, v7
	s_nop 1
	v_add_f32_dpp v21, v21, v21 quad_perm:[1,0,3,2] row_mask:0xf bank_mask:0xf
	v_mul_f32_e32 v32, v32, v24
	v_mul_f32_e32 v8, v8, v24
	s_nop 1
	v_add_f32_dpp v21, v21, v21 quad_perm:[2,3,0,1] row_mask:0xf bank_mask:0xf
	s_nop 1
	v_add_f32_dpp v21, v21, v21 row_half_mirror row_mask:0xf bank_mask:0xf
	s_nop 1
	v_add_f32_dpp v21, v21, v21 row_mirror row_mask:0xf bank_mask:0xf
	v_mov_b32_e32 v22, v21
	v_mov_b32_e32 v23, v21
	s_nop 1
	v_permlane16_swap_b32_e32 v22, v23
; #define LAS __attribute__((address_space(3)))
; #define LDS_WAIT() asm volatile("s_waitcnt lgkmcnt(0)" ::: "memory")
; DI float bf2f(bf16 b) { return __uint_as_float(((unsigned)b) << 16); }
; DI void g3_tile_in(const bf16* g, LAS unsigned char* R, int lane) {
; #pragma unroll
;     for (int it = 0; it < 8; ++it) { const int row = 4 * it + (lane >> 4), ch = lane & 15;
;         *(LAS u32x4*)(R + row * G3_PITCH + ch * 16) = *(const u32x4*)(g + (size_t)row * 512 + ch * 8); }
;     LDS_WAIT();
; }
; DI void gla_stage3(const Ctx& c0, int layer, int unit, int cb, LAS unsigned char* lds) {
;     ...
;     for (int rg = 0; rg < 16; ++rg) { float ss = o[0][rg] * o[0][rg] + o[1][rg] * o[1][rg] + o[2][rg] * o[2][rg] + o[3][rg] * o[3][rg];
;         ss += __shfl_xor(ss, 1); ss += __shfl_xor(ss, 2); ss += __shfl_xor(ss, 4); ss += __shfl_xor(ss, 8); ss += __shfl_xor(ss, 16);
;         rs[rg] = 1.f / sqrtf(ss * (1.f / 128.f) + EPS); }
;     LDS_WAIT();
;     g3_tile_in((const bf16*)(c.ws + O_GR) + row0 * 512 + h * 128, R, lane);
; #pragma unroll
;     for (int vb = 0; vb < 4; ++vb) { const float g = gn[32 * vb + r];
; #pragma unroll
;         for (int rg = 0; rg < 16; ++rg) { LAS bf16* e = (LAS bf16*)(R + (4 * hi) * G3_PITCH + r * 2 + ((rg & 3) + 8 * (rg >> 2)) * G3_PITCH + 64 * vb);
;             const float z = bf2f(*e);
	v_add_f32_e32 v21, v22, v23
	v_fmamk_f32 v21, v21, 0x3c000000, v100
	v_cmp_gt_f32_e32 vcc, s34, v21
	v_mul_f32_e32 v22, 0x4f800000, v21
	s_nop 0
	v_cndmask_b32_e32 v21, v21, v22, vcc
	v_sqrt_f32_e32 v22, v21
	s_nop 0
	v_add_u32_e32 v23, -1, v22
	v_fma_f32 v49, -v23, v22, v21
	v_cmp_ge_f32_e64 s[4:5], 0, v49
	v_add_u32_e32 v49, 1, v22
	s_nop 0
	v_cndmask_b32_e64 v23, v22, v23, s[4:5]
	v_fma_f32 v22, -v49, v22, v21
	v_cmp_lt_f32_e64 s[4:5], 0, v22
	s_nop 1
	v_cndmask_b32_e64 v22, v23, v49, s[4:5]
	v_mul_f32_e32 v23, 0x37800000, v22
	v_cndmask_b32_e32 v22, v22, v23, vcc
	v_cmp_class_f32_e32 vcc, v21, v101
	s_nop 1
	v_cndmask_b32_e32 v21, v22, v21, vcc
	s_nop 0
	v_div_scale_f32 v49, vcc, 1.0, v21, 1.0
	v_rcp_f32_e32 v23, v21
	v_mul_f32_e32 v21, v109, v109
	v_fmac_f32_e32 v21, v125, v125
	v_fmac_f32_e32 v21, v29, v29
	v_fmac_f32_e32 v21, v6, v6
	s_nop 1
	v_add_f32_dpp v21, v21, v21 quad_perm:[1,0,3,2] row_mask:0xf bank_mask:0xf
	v_mul_f32_e32 v30, v30, v23
	v_mul_f32_e32 v7, v7, v23
	s_nop 1
	v_add_f32_dpp v21, v21, v21 quad_perm:[2,3,0,1] row_mask:0xf bank_mask:0xf
	s_nop 1
	v_add_f32_dpp v21, v21, v21 row_half_mirror row_mask:0xf bank_mask:0xf
	s_nop 1
	v_add_f32_dpp v21, v21, v21 row_mirror row_mask:0xf bank_mask:0xf
	v_mov_b32_e32 v22, v21
	v_mov_b32_e32 v49, v21
	s_nop 1
	v_permlane16_swap_b32_e32 v22, v49
	v_add_f32_e32 v21, v22, v49
	v_fmamk_f32 v21, v21, 0x3c000000, v100
	v_cmp_gt_f32_e32 vcc, s34, v21
	v_mul_f32_e32 v22, 0x4f800000, v21
	s_nop 0
	v_cndmask_b32_e32 v21, v21, v22, vcc
	v_sqrt_f32_e32 v22, v21
	s_nop 0
	v_add_u32_e32 v49, -1, v22
	v_fma_f32 v50, -v49, v22, v21
	v_cmp_ge_f32_e64 s[4:5], 0, v50
	v_add_u32_e32 v50, 1, v22
	s_nop 0
	v_cndmask_b32_e64 v49, v22, v49, s[4:5]
	v_fma_f32 v22, -v50, v22, v21
	v_cmp_lt_f32_e64 s[4:5], 0, v22
	s_nop 1
	v_cndmask_b32_e64 v22, v49, v50, s[4:5]
	v_mul_f32_e32 v49, 0x37800000, v22
	v_cndmask_b32_e32 v22, v22, v49, vcc
	v_cmp_class_f32_e32 vcc, v21, v101
	s_nop 1
	v_cndmask_b32_e32 v21, v22, v21, vcc
	s_nop 0
	v_div_scale_f32 v50, vcc, 1.0, v21, 1.0
	v_rcp_f32_e32 v22, v21
	v_mul_f32_e32 v21, v108, v108
	v_fmac_f32_e32 v21, v124, v124
	v_fmac_f32_e32 v21, v28, v28
	v_fmac_f32_e32 v21, v5, v5
	s_nop 1
	v_add_f32_dpp v21, v21, v21 quad_perm:[1,0,3,2] row_mask:0xf bank_mask:0xf
	v_mul_f32_e32 v29, v29, v22
	v_mul_f32_e32 v6, v6, v22
	s_nop 1
	v_add_f32_dpp v21, v21, v21 quad_perm:[2,3,0,1] row_mask:0xf bank_mask:0xf
	s_nop 1
	v_add_f32_dpp v21, v21, v21 row_half_mirror row_mask:0xf bank_mask:0xf
	s_nop 1
	v_add_f32_dpp v21, v21, v21 row_mirror row_mask:0xf bank_mask:0xf
	v_mov_b32_e32 v49, v21
	v_mov_b32_e32 v50, v21
	s_nop 1
	v_permlane16_swap_b32_e32 v49, v50
	v_add_f32_e32 v21, v49, v50
	v_fmamk_f32 v21, v21, 0x3c000000, v100
	v_cmp_gt_f32_e32 vcc, s34, v21
	v_mul_f32_e32 v49, 0x4f800000, v21
	s_nop 0
	v_cndmask_b32_e32 v21, v21, v49, vcc
	v_sqrt_f32_e32 v49, v21
	s_nop 0
	v_add_u32_e32 v50, -1, v49
	v_fma_f32 v51, -v50, v49, v21
	v_cmp_ge_f32_e64 s[4:5], 0, v51
	v_add_u32_e32 v51, 1, v49
	s_nop 0
	v_cndmask_b32_e64 v50, v49, v50, s[4:5]
	v_fma_f32 v49, -v51, v49, v21
	v_cmp_lt_f32_e64 s[4:5], 0, v49
	s_nop 1
	v_cndmask_b32_e64 v49, v50, v51, s[4:5]
	v_mul_f32_e32 v50, 0x37800000, v49
	v_cndmask_b32_e32 v49, v49, v50, vcc
	v_cmp_class_f32_e32 vcc, v21, v101
	s_nop 1
	v_cndmask_b32_e32 v21, v49, v21, vcc
	s_nop 0
	v_div_scale_f32 v51, vcc, 1.0, v21, 1.0
	v_rcp_f32_e32 v21, v21
	v_mul_f32_e32 v49, v107, v107
	v_fmac_f32_e32 v49, v123, v123
	v_fmac_f32_e32 v49, v26, v26
	v_fmac_f32_e32 v49, v4, v4
	ds_bpermute_b32 v2, v2, v49
	v_mul_f32_e32 v28, v28, v21
	v_mul_f32_e32 v5, v5, v21
	s_waitcnt lgkmcnt(0)
	v_add_f32_e32 v2, v49, v2
	ds_bpermute_b32 v3, v3, v2
	s_waitcnt lgkmcnt(0)
	v_add_f32_e32 v2, v2, v3
	ds_bpermute_b32 v3, v20, v2
	s_waitcnt lgkmcnt(0)
	v_add_f32_e32 v2, v2, v3
	ds_bpermute_b32 v3, v47, v2
	s_waitcnt lgkmcnt(0)
	v_add_f32_e32 v2, v2, v3
	ds_bpermute_b32 v3, v48, v2
	s_waitcnt lgkmcnt(0)
	v_add_f32_e32 v2, v2, v3
	v_fmamk_f32 v2, v2, 0x3c000000, v100
	v_cmp_gt_f32_e32 vcc, s34, v2
	v_mul_f32_e32 v3, 0x4f800000, v2
	s_nop 0
	v_cndmask_b32_e32 v2, v2, v3, vcc
	v_sqrt_f32_e32 v3, v2
	s_nop 0
	v_add_u32_e32 v20, -1, v3
	v_fma_f32 v47, -v20, v3, v2
	v_cmp_ge_f32_e64 s[4:5], 0, v47
	v_add_u32_e32 v47, 1, v3
	s_nop 0
	v_cndmask_b32_e64 v20, v3, v20, s[4:5]
	v_fma_f32 v3, -v47, v3, v2
	v_cmp_lt_f32_e64 s[4:5], 0, v3
	s_nop 1
	v_cndmask_b32_e64 v3, v20, v47, s[4:5]
	v_mul_f32_e32 v20, 0x37800000, v3
	v_cndmask_b32_e32 v3, v3, v20, vcc
	v_cmp_class_f32_e32 vcc, v2, v101
	s_nop 1
	v_cndmask_b32_e32 v2, v3, v2, vcc
	s_nop 0
	v_rcp_f32_e32 v20, v2
	v_mul_f32_e32 v47, v138, v46
	v_mul_f32_e32 v26, v26, v20
	v_mul_f32_e32 v4, v4, v20
	s_waitcnt vmcnt(2) lgkmcnt(0)
	ds_write_b128 v92, v[164:167]
	s_waitcnt vmcnt(0) lgkmcnt(0)
	ds_write_b128 v92, v[170:173] offset:1088
	s_waitcnt vmcnt(13) lgkmcnt(0)
	ds_write_b128 v92, v[174:177] offset:2176
	s_waitcnt vmcnt(8) lgkmcnt(0)
	ds_write_b128 v92, v[178:181] offset:3264
	s_waitcnt vmcnt(9) lgkmcnt(0)
	ds_write_b128 v92, v[196:199] offset:4352
	s_waitcnt vmcnt(10) lgkmcnt(0)
	ds_write_b128 v92, v[200:203] offset:5440
	v_lshl_add_u64 v[2:3], v[168:169], 0, v[80:81]
	s_waitcnt vmcnt(5) lgkmcnt(0)
	ds_write_b128 v92, v[204:207] offset:6528
	global_load_dwordx4 v[48:51], v[2:3], off
	s_waitcnt vmcnt(0) lgkmcnt(0)
	ds_write_b128 v92, v[48:51] offset:7616
	s_waitcnt lgkmcnt(0)
	ds_read_u16 v3, v1
	s_waitcnt lgkmcnt(0)
	v_lshlrev_b32_e32 v3, 16, v3
	v_mul_f32_e32 v48, 0xbfb8aa3b, v3
	v_exp_f32_e32 v48, v48
	s_waitcnt vmcnt(0)
; #define LAS __attribute__((address_space(3)))
; DI unsigned cvtpk(float lo, float hi) { f32x2 v = {lo, hi}; bf16x2_t b = __builtin_convertvector(v, bf16x2_t); return __builtin_bit_cast(unsigned, b); }
; DI float bf2f(bf16 b) { return __uint_as_float(((unsigned)b) << 16); }
; DI float siluf_(float x) { return x / (1.f + __expf(-x)); }
; DI void gla_stage3(const Ctx& c0, int layer, int unit, int cb, LAS unsigned char* lds) {
;     ...
; #pragma unroll
;     for (int vb = 0; vb < 4; ++vb) { const float g = gn[32 * vb + r];
; #pragma unroll
;         for (int rg = 0; rg < 16; ++rg) { LAS bf16* e = (LAS bf16*)(R + (4 * hi) * G3_PITCH + r * 2 + ((rg & 3) + 8 * (rg >> 2)) * G3_PITCH + 64 * vb);
;             const float z = bf2f(*e);
;             *e = (bf16)(cvtpk(o[vb][rg] * rs[rg] * g * siluf_(z), 0.f) & 0xffffu); }
;         asm volatile("" ::: "memory"); }
	v_mul_f32_e32 v47, v47, v232
	v_add_f32_e32 v48, 1.0, v48
	v_div_scale_f32 v49, s[0:1], v48, v48, v3
	s_nop 0
	v_rcp_f32_e32 v49, v48
	s_nop 0
	v_mul_f32_e32 v3, v3, v49
	v_mul_f32_e32 v3, v47, v3
	v_cvt_pk_bf16_f32 v3, v3, s0
	ds_write_b16 v1, v3
	ds_read_u16 v3, v1 offset:272
	v_mul_f32_e32 v47, v137, v45
	v_mul_f32_e32 v47, v47, v232
	s_waitcnt lgkmcnt(0)
	v_lshlrev_b32_e32 v3, 16, v3
	v_mul_f32_e32 v48, 0xbfb8aa3b, v3
	v_exp_f32_e32 v48, v48
	s_nop 0
	v_add_f32_e32 v48, 1.0, v48
	v_div_scale_f32 v49, s[0:1], v48, v48, v3
	s_nop 0
	v_rcp_f32_e32 v49, v48
	s_nop 0
	v_mul_f32_e32 v3, v3, v49
	v_mul_f32_e32 v3, v47, v3
	v_cvt_pk_bf16_f32 v3, v3, s0
	ds_write_b16 v1, v3 offset:272
	ds_read_u16 v3, v1 offset:544
	v_mul_f32_e32 v47, v136, v44
	v_mul_f32_e32 v47, v47, v232
	s_waitcnt lgkmcnt(0)
	v_lshlrev_b32_e32 v3, 16, v3
	v_mul_f32_e32 v48, 0xbfb8aa3b, v3
	v_exp_f32_e32 v48, v48
	s_nop 0
	v_add_f32_e32 v48, 1.0, v48
	v_div_scale_f32 v49, s[0:1], v48, v48, v3
	s_nop 0
	v_rcp_f32_e32 v49, v48
	s_nop 0
	v_mul_f32_e32 v3, v3, v49
	v_mul_f32_e32 v3, v47, v3
	v_cvt_pk_bf16_f32 v3, v3, s0
	ds_write_b16 v1, v3 offset:544
	ds_read_u16 v3, v1 offset:816
	v_mul_f32_e32 v47, v135, v43
	v_mul_f32_e32 v47, v47, v232
	s_waitcnt lgkmcnt(0)
	v_lshlrev_b32_e32 v3, 16, v3
	v_mul_f32_e32 v48, 0xbfb8aa3b, v3
	v_exp_f32_e32 v48, v48
	s_nop 0
	v_add_f32_e32 v48, 1.0, v48
	v_div_scale_f32 v49, s[0:1], v48, v48, v3
	s_nop 0
	v_rcp_f32_e32 v49, v48
	s_nop 0
	v_mul_f32_e32 v3, v3, v49
	v_mul_f32_e32 v3, v47, v3
	v_cvt_pk_bf16_f32 v3, v3, s0
	ds_write_b16 v1, v3 offset:816
	ds_read_u16 v3, v1 offset:2176
	v_mul_f32_e32 v47, v134, v42
	v_mul_f32_e32 v47, v47, v232
	s_waitcnt lgkmcnt(0)
	v_lshlrev_b32_e32 v3, 16, v3
	v_mul_f32_e32 v48, 0xbfb8aa3b, v3
	v_exp_f32_e32 v48, v48
	s_nop 0
	v_add_f32_e32 v48, 1.0, v48
	v_div_scale_f32 v49, s[0:1], v48, v48, v3
	s_nop 0
	v_rcp_f32_e32 v49, v48
	s_nop 0
	v_mul_f32_e32 v3, v3, v49
	v_mul_f32_e32 v3, v47, v3
	v_cvt_pk_bf16_f32 v3, v3, s0
	ds_write_b16 v1, v3 offset:2176
	ds_read_u16 v3, v1 offset:2448
	v_mul_f32_e32 v47, v133, v41
	v_mul_f32_e32 v47, v47, v232
	s_waitcnt lgkmcnt(0)
	v_lshlrev_b32_e32 v3, 16, v3
	v_mul_f32_e32 v48, 0xbfb8aa3b, v3
	v_exp_f32_e32 v48, v48
	s_nop 0
	v_add_f32_e32 v48, 1.0, v48
	v_div_scale_f32 v49, s[0:1], v48, v48, v3
	s_nop 0
	v_rcp_f32_e32 v49, v48
	s_nop 0
	v_mul_f32_e32 v3, v3, v49
	v_mul_f32_e32 v3, v47, v3
	v_cvt_pk_bf16_f32 v3, v3, s0
	ds_write_b16 v1, v3 offset:2448
	ds_read_u16 v3, v1 offset:2720
	v_mul_f32_e32 v47, v132, v40
	v_mul_f32_e32 v47, v47, v232
	s_waitcnt lgkmcnt(0)
	v_lshlrev_b32_e32 v3, 16, v3
	v_mul_f32_e32 v48, 0xbfb8aa3b, v3
	v_exp_f32_e32 v48, v48
	s_nop 0
	v_add_f32_e32 v48, 1.0, v48
	v_div_scale_f32 v49, s[0:1], v48, v48, v3
	s_nop 0
	v_rcp_f32_e32 v49, v48
	s_nop 0
	v_mul_f32_e32 v3, v3, v49
	v_mul_f32_e32 v3, v47, v3
	v_cvt_pk_bf16_f32 v3, v3, s0
	ds_write_b16 v1, v3 offset:2720
	ds_read_u16 v3, v1 offset:2992
	v_mul_f32_e32 v47, v131, v35
	v_mul_f32_e32 v47, v47, v232
	s_waitcnt lgkmcnt(0)
	v_lshlrev_b32_e32 v3, 16, v3
	v_mul_f32_e32 v48, 0xbfb8aa3b, v3
	v_exp_f32_e32 v48, v48
	s_nop 0
	v_add_f32_e32 v48, 1.0, v48
	v_div_scale_f32 v49, s[0:1], v48, v48, v3
	s_nop 0
	v_rcp_f32_e32 v49, v48
	s_nop 0
	v_mul_f32_e32 v3, v3, v49
	v_mul_f32_e32 v3, v47, v3
	v_cvt_pk_bf16_f32 v3, v3, s0
	ds_write_b16 v1, v3 offset:2992
	ds_read_u16 v3, v1 offset:4352
	v_mul_f32_e32 v47, v130, v31
	v_mul_f32_e32 v47, v47, v232
	s_waitcnt lgkmcnt(0)
	v_lshlrev_b32_e32 v3, 16, v3
	v_mul_f32_e32 v48, 0xbfb8aa3b, v3
	v_exp_f32_e32 v48, v48
	s_nop 0
	v_add_f32_e32 v48, 1.0, v48
	v_div_scale_f32 v49, s[0:1], v48, v48, v3
	s_nop 0
	v_rcp_f32_e32 v49, v48
	s_nop 0
	v_mul_f32_e32 v3, v3, v49
	v_mul_f32_e32 v3, v47, v3
	v_cvt_pk_bf16_f32 v3, v3, s0
	ds_write_b16 v1, v3 offset:4352
	ds_read_u16 v3, v1 offset:4624
	v_mul_f32_e32 v47, v129, v27
	v_mul_f32_e32 v47, v47, v232
	s_waitcnt lgkmcnt(0)
	v_lshlrev_b32_e32 v3, 16, v3
	v_mul_f32_e32 v48, 0xbfb8aa3b, v3
	v_exp_f32_e32 v48, v48
	s_nop 0
	v_add_f32_e32 v48, 1.0, v48
	v_div_scale_f32 v49, s[0:1], v48, v48, v3
	s_nop 0
	v_rcp_f32_e32 v49, v48
	s_nop 0
	v_mul_f32_e32 v3, v3, v49
	v_mul_f32_e32 v3, v47, v3
	v_cvt_pk_bf16_f32 v3, v3, s0
	ds_write_b16 v1, v3 offset:4624
	ds_read_u16 v3, v1 offset:4896
	v_mul_f32_e32 v47, v128, v25
	v_mul_f32_e32 v47, v47, v232
	s_waitcnt lgkmcnt(0)
	v_lshlrev_b32_e32 v3, 16, v3
	v_mul_f32_e32 v48, 0xbfb8aa3b, v3
	v_exp_f32_e32 v48, v48
	s_nop 0
	v_add_f32_e32 v48, 1.0, v48
	v_div_scale_f32 v49, s[0:1], v48, v48, v3
	s_nop 0
	v_rcp_f32_e32 v49, v48
	s_nop 0
	v_mul_f32_e32 v3, v3, v49
	v_mul_f32_e32 v3, v47, v3
	v_cvt_pk_bf16_f32 v3, v3, s0
	ds_write_b16 v1, v3 offset:4896
	ds_read_u16 v3, v1 offset:5168
	v_mul_f32_e32 v47, v127, v24
	v_mul_f32_e32 v47, v47, v232
	s_waitcnt lgkmcnt(0)
	v_lshlrev_b32_e32 v3, 16, v3
	v_mul_f32_e32 v48, 0xbfb8aa3b, v3
	v_exp_f32_e32 v48, v48
	s_nop 0
	v_add_f32_e32 v48, 1.0, v48
	v_div_scale_f32 v49, s[0:1], v48, v48, v3
	s_nop 0
	v_rcp_f32_e32 v49, v48
	s_nop 0
	v_mul_f32_e32 v3, v3, v49
	v_mul_f32_e32 v3, v47, v3
	v_cvt_pk_bf16_f32 v3, v3, s0
	ds_write_b16 v1, v3 offset:5168
	ds_read_u16 v3, v1 offset:6528
	v_mul_f32_e32 v47, v126, v23
	v_mul_f32_e32 v47, v47, v232
	s_waitcnt lgkmcnt(0)
	v_lshlrev_b32_e32 v3, 16, v3
	v_mul_f32_e32 v48, 0xbfb8aa3b, v3
	v_exp_f32_e32 v48, v48
	s_nop 0
	v_add_f32_e32 v48, 1.0, v48
	v_div_scale_f32 v49, s[0:1], v48, v48, v3
	s_nop 0
	v_rcp_f32_e32 v49, v48
	s_nop 0
	v_mul_f32_e32 v3, v3, v49
	v_mul_f32_e32 v3, v47, v3
	v_cvt_pk_bf16_f32 v3, v3, s0
	ds_write_b16 v1, v3 offset:6528
	ds_read_u16 v3, v1 offset:6800
	v_mul_f32_e32 v47, v125, v22
	v_mul_f32_e32 v47, v47, v232
	s_waitcnt lgkmcnt(0)
; #define LAS __attribute__((address_space(3)))
; DI unsigned cvtpk(float lo, float hi) { f32x2 v = {lo, hi}; bf16x2_t b = __builtin_convertvector(v, bf16x2_t); return __builtin_bit_cast(unsigned, b); }
; DI float bf2f(bf16 b) { return __uint_as_float(((unsigned)b) << 16); }
; DI float siluf_(float x) { return x / (1.f + __expf(-x)); }
; DI void gla_stage3(const Ctx& c0, int layer, int unit, int cb, LAS unsigned char* lds) {
;     ...
; #pragma unroll
;     for (int vb = 0; vb < 4; ++vb) { const float g = gn[32 * vb + r];
; #pragma unroll
;         for (int rg = 0; rg < 16; ++rg) { LAS bf16* e = (LAS bf16*)(R + (4 * hi) * G3_PITCH + r * 2 + ((rg & 3) + 8 * (rg >> 2)) * G3_PITCH + 64 * vb);
;             const float z = bf2f(*e);
;             *e = (bf16)(cvtpk(o[vb][rg] * rs[rg] * g * siluf_(z), 0.f) & 0xffffu); }
;         asm volatile("" ::: "memory"); }
	v_lshlrev_b32_e32 v3, 16, v3
	v_mul_f32_e32 v48, 0xbfb8aa3b, v3
	v_exp_f32_e32 v48, v48
	s_nop 0
	v_add_f32_e32 v48, 1.0, v48
	v_div_scale_f32 v49, s[0:1], v48, v48, v3
	s_nop 0
	v_rcp_f32_e32 v49, v48
	s_nop 0
	v_mul_f32_e32 v3, v3, v49
	v_mul_f32_e32 v3, v47, v3
	v_cvt_pk_bf16_f32 v3, v3, s0
	ds_write_b16 v1, v3 offset:6800
	ds_read_u16 v3, v1 offset:7072
	v_mul_f32_e32 v47, v124, v21
	v_mul_f32_e32 v47, v47, v232
	s_waitcnt lgkmcnt(0)
	v_lshlrev_b32_e32 v3, 16, v3
	v_mul_f32_e32 v48, 0xbfb8aa3b, v3
	v_exp_f32_e32 v48, v48
	s_nop 0
	v_add_f32_e32 v48, 1.0, v48
	v_div_scale_f32 v49, s[0:1], v48, v48, v3
	s_nop 0
	v_rcp_f32_e32 v49, v48
	s_nop 0
	v_mul_f32_e32 v3, v3, v49
	v_mul_f32_e32 v3, v47, v3
	v_cvt_pk_bf16_f32 v3, v3, s0
	ds_write_b16 v1, v3 offset:7072
	ds_read_u16 v3, v1 offset:7344
	v_mul_f32_e32 v47, v123, v20
	v_mul_f32_e32 v2, v47, v232
	s_waitcnt lgkmcnt(0)
	v_lshlrev_b32_e32 v3, 16, v3
	v_mul_f32_e32 v47, 0xbfb8aa3b, v3
	v_exp_f32_e32 v47, v47
	s_nop 0
	v_add_f32_e32 v47, 1.0, v47
	v_div_scale_f32 v48, s[0:1], v47, v47, v3
	s_nop 0
	v_rcp_f32_e32 v48, v47
	s_nop 0
	v_mul_f32_e32 v3, v3, v48
	v_mul_f32_e32 v2, v2, v3
	v_cvt_pk_bf16_f32 v2, v2, s0
	ds_write_b16 v1, v2 offset:7344
	ds_read_u16 v3, v1 offset:64
	v_mul_f32_e32 v47, v122, v46
	s_waitcnt lgkmcnt(0)
	v_lshlrev_b32_e32 v3, 16, v3
	v_mul_f32_e32 v48, 0xbfb8aa3b, v3
	v_exp_f32_e32 v48, v48
	s_waitcnt vmcnt(0)
	v_mul_f32_e32 v47, v47, v234
	v_add_f32_e32 v48, 1.0, v48
	v_div_scale_f32 v49, s[0:1], v48, v48, v3
	s_nop 0
	v_rcp_f32_e32 v49, v48
	s_nop 0
	v_mul_f32_e32 v3, v3, v49
	v_mul_f32_e32 v3, v47, v3
	v_cvt_pk_bf16_f32 v3, v3, s0
	ds_write_b16 v1, v3 offset:64
	ds_read_u16 v3, v1 offset:336
	v_mul_f32_e32 v47, v121, v45
	v_mul_f32_e32 v47, v47, v234
	s_waitcnt lgkmcnt(0)
	v_lshlrev_b32_e32 v3, 16, v3
	v_mul_f32_e32 v48, 0xbfb8aa3b, v3
	v_exp_f32_e32 v48, v48
	s_nop 0
	v_add_f32_e32 v48, 1.0, v48
	v_div_scale_f32 v49, s[0:1], v48, v48, v3
	s_nop 0
	v_rcp_f32_e32 v49, v48
	s_nop 0
	v_mul_f32_e32 v3, v3, v49
	v_mul_f32_e32 v3, v47, v3
	v_cvt_pk_bf16_f32 v3, v3, s0
	ds_write_b16 v1, v3 offset:336
	ds_read_u16 v3, v1 offset:608
	v_mul_f32_e32 v47, v120, v44
	v_mul_f32_e32 v47, v47, v234
	s_waitcnt lgkmcnt(0)
	v_lshlrev_b32_e32 v3, 16, v3
	v_mul_f32_e32 v48, 0xbfb8aa3b, v3
	v_exp_f32_e32 v48, v48
	s_nop 0
	v_add_f32_e32 v48, 1.0, v48
	v_div_scale_f32 v49, s[0:1], v48, v48, v3
	s_nop 0
	v_rcp_f32_e32 v49, v48
	s_nop 0
	v_mul_f32_e32 v3, v3, v49
	v_mul_f32_e32 v3, v47, v3
	v_cvt_pk_bf16_f32 v3, v3, s0
	ds_write_b16 v1, v3 offset:608
	ds_read_u16 v3, v1 offset:880
	v_mul_f32_e32 v47, v119, v43
	v_mul_f32_e32 v47, v47, v234
	s_waitcnt lgkmcnt(0)
	v_lshlrev_b32_e32 v3, 16, v3
	v_mul_f32_e32 v48, 0xbfb8aa3b, v3
	v_exp_f32_e32 v48, v48
	s_nop 0
	v_add_f32_e32 v48, 1.0, v48
	v_div_scale_f32 v49, s[0:1], v48, v48, v3
	s_nop 0
	v_rcp_f32_e32 v49, v48
	s_nop 0
	v_mul_f32_e32 v3, v3, v49
	v_mul_f32_e32 v3, v47, v3
	v_cvt_pk_bf16_f32 v3, v3, s0
	ds_write_b16 v1, v3 offset:880
	ds_read_u16 v3, v1 offset:2240
	v_mul_f32_e32 v47, v118, v42
	v_mul_f32_e32 v47, v47, v234
	s_waitcnt lgkmcnt(0)
	v_lshlrev_b32_e32 v3, 16, v3
	v_mul_f32_e32 v48, 0xbfb8aa3b, v3
	v_exp_f32_e32 v48, v48
	s_nop 0
	v_add_f32_e32 v48, 1.0, v48
	v_div_scale_f32 v49, s[0:1], v48, v48, v3
	s_nop 0
	v_rcp_f32_e32 v49, v48
	s_nop 0
	v_mul_f32_e32 v3, v3, v49
	v_mul_f32_e32 v3, v47, v3
	v_cvt_pk_bf16_f32 v3, v3, s0
	ds_write_b16 v1, v3 offset:2240
	ds_read_u16 v3, v1 offset:2512
	v_mul_f32_e32 v47, v117, v41
	v_mul_f32_e32 v47, v47, v234
	s_waitcnt lgkmcnt(0)
	v_lshlrev_b32_e32 v3, 16, v3
	v_mul_f32_e32 v48, 0xbfb8aa3b, v3
	v_exp_f32_e32 v48, v48
	s_nop 0
	v_add_f32_e32 v48, 1.0, v48
	v_div_scale_f32 v49, s[0:1], v48, v48, v3
	s_nop 0
	v_rcp_f32_e32 v49, v48
	s_nop 0
	v_mul_f32_e32 v3, v3, v49
	v_mul_f32_e32 v3, v47, v3
	v_cvt_pk_bf16_f32 v3, v3, s0
	ds_write_b16 v1, v3 offset:2512
	ds_read_u16 v3, v1 offset:2784
	v_mul_f32_e32 v47, v116, v40
	v_mul_f32_e32 v47, v47, v234
	s_waitcnt lgkmcnt(0)
	v_lshlrev_b32_e32 v3, 16, v3
	v_mul_f32_e32 v48, 0xbfb8aa3b, v3
	v_exp_f32_e32 v48, v48
	s_nop 0
	v_add_f32_e32 v48, 1.0, v48
	v_div_scale_f32 v49, s[0:1], v48, v48, v3
	s_nop 0
	v_rcp_f32_e32 v49, v48
	s_nop 0
	v_mul_f32_e32 v3, v3, v49
	v_mul_f32_e32 v3, v47, v3
	v_cvt_pk_bf16_f32 v3, v3, s0
	ds_write_b16 v1, v3 offset:2784
	ds_read_u16 v3, v1 offset:3056
	v_mul_f32_e32 v47, v115, v35
	v_mul_f32_e32 v47, v47, v234
	s_waitcnt lgkmcnt(0)
	v_lshlrev_b32_e32 v3, 16, v3
	v_mul_f32_e32 v48, 0xbfb8aa3b, v3
	v_exp_f32_e32 v48, v48
	s_nop 0
	v_add_f32_e32 v48, 1.0, v48
	v_div_scale_f32 v49, s[0:1], v48, v48, v3
	s_nop 0
	v_rcp_f32_e32 v49, v48
	s_nop 0
	v_mul_f32_e32 v3, v3, v49
	v_mul_f32_e32 v3, v47, v3
	v_cvt_pk_bf16_f32 v3, v3, s0
	ds_write_b16 v1, v3 offset:3056
	ds_read_u16 v3, v1 offset:4416
	v_mul_f32_e32 v47, v114, v31
	v_mul_f32_e32 v47, v47, v234
	s_waitcnt lgkmcnt(0)
	v_lshlrev_b32_e32 v3, 16, v3
	v_mul_f32_e32 v48, 0xbfb8aa3b, v3
	v_exp_f32_e32 v48, v48
	s_nop 0
	v_add_f32_e32 v48, 1.0, v48
	v_div_scale_f32 v49, s[0:1], v48, v48, v3
	s_nop 0
	v_rcp_f32_e32 v49, v48
	s_nop 0
	v_mul_f32_e32 v3, v3, v49
	v_mul_f32_e32 v3, v47, v3
	v_cvt_pk_bf16_f32 v3, v3, s0
	ds_write_b16 v1, v3 offset:4416
	ds_read_u16 v3, v1 offset:4688
	v_mul_f32_e32 v47, v113, v27
	v_mul_f32_e32 v47, v47, v234
	s_waitcnt lgkmcnt(0)
	v_lshlrev_b32_e32 v3, 16, v3
	v_mul_f32_e32 v48, 0xbfb8aa3b, v3
	v_exp_f32_e32 v48, v48
	s_nop 0
	v_add_f32_e32 v48, 1.0, v48
	v_div_scale_f32 v49, s[0:1], v48, v48, v3
	s_nop 0
	v_rcp_f32_e32 v49, v48
	s_nop 0
	v_mul_f32_e32 v3, v3, v49
	v_mul_f32_e32 v3, v47, v3
	v_cvt_pk_bf16_f32 v3, v3, s0
	ds_write_b16 v1, v3 offset:4688
	ds_read_u16 v3, v1 offset:4960
	v_mul_f32_e32 v47, v112, v25
	v_mul_f32_e32 v47, v47, v234
	s_waitcnt lgkmcnt(0)
; #define LAS __attribute__((address_space(3)))
; DI unsigned cvtpk(float lo, float hi) { f32x2 v = {lo, hi}; bf16x2_t b = __builtin_convertvector(v, bf16x2_t); return __builtin_bit_cast(unsigned, b); }
; DI float bf2f(bf16 b) { return __uint_as_float(((unsigned)b) << 16); }
; DI float siluf_(float x) { return x / (1.f + __expf(-x)); }
; DI void gla_stage3(const Ctx& c0, int layer, int unit, int cb, LAS unsigned char* lds) {
;     ...
; #pragma unroll
;     for (int vb = 0; vb < 4; ++vb) { const float g = gn[32 * vb + r];
; #pragma unroll
;         for (int rg = 0; rg < 16; ++rg) { LAS bf16* e = (LAS bf16*)(R + (4 * hi) * G3_PITCH + r * 2 + ((rg & 3) + 8 * (rg >> 2)) * G3_PITCH + 64 * vb);
;             const float z = bf2f(*e);
;             *e = (bf16)(cvtpk(o[vb][rg] * rs[rg] * g * siluf_(z), 0.f) & 0xffffu); }
;         asm volatile("" ::: "memory"); }
	v_lshlrev_b32_e32 v3, 16, v3
	v_mul_f32_e32 v48, 0xbfb8aa3b, v3
	v_exp_f32_e32 v48, v48
	s_nop 0
	v_add_f32_e32 v48, 1.0, v48
	v_div_scale_f32 v49, s[0:1], v48, v48, v3
	s_nop 0
	v_rcp_f32_e32 v49, v48
	s_nop 0
	v_mul_f32_e32 v3, v3, v49
	v_mul_f32_e32 v3, v47, v3
	v_cvt_pk_bf16_f32 v3, v3, s0
	ds_write_b16 v1, v3 offset:4960
	ds_read_u16 v3, v1 offset:5232
	v_mul_f32_e32 v47, v111, v24
	v_mul_f32_e32 v47, v47, v234
	s_waitcnt lgkmcnt(0)
	v_lshlrev_b32_e32 v3, 16, v3
	v_mul_f32_e32 v48, 0xbfb8aa3b, v3
	v_exp_f32_e32 v48, v48
	s_nop 0
	v_add_f32_e32 v48, 1.0, v48
	v_div_scale_f32 v49, s[0:1], v48, v48, v3
	s_nop 0
	v_rcp_f32_e32 v49, v48
	s_nop 0
	v_mul_f32_e32 v3, v3, v49
	v_mul_f32_e32 v3, v47, v3
	v_cvt_pk_bf16_f32 v3, v3, s0
	ds_write_b16 v1, v3 offset:5232
	ds_read_u16 v3, v1 offset:6592
	v_mul_f32_e32 v47, v110, v23
	v_mul_f32_e32 v47, v47, v234
	s_waitcnt lgkmcnt(0)
	v_lshlrev_b32_e32 v3, 16, v3
	v_mul_f32_e32 v48, 0xbfb8aa3b, v3
	v_exp_f32_e32 v48, v48
	s_nop 0
	v_add_f32_e32 v48, 1.0, v48
	v_div_scale_f32 v49, s[0:1], v48, v48, v3
	s_nop 0
	v_rcp_f32_e32 v49, v48
	s_nop 0
	v_mul_f32_e32 v3, v3, v49
	v_mul_f32_e32 v3, v47, v3
	v_cvt_pk_bf16_f32 v3, v3, s0
	ds_write_b16 v1, v3 offset:6592
	ds_read_u16 v3, v1 offset:6864
	v_mul_f32_e32 v47, v109, v22
	v_mul_f32_e32 v47, v47, v234
	s_waitcnt lgkmcnt(0)
	v_lshlrev_b32_e32 v3, 16, v3
	v_mul_f32_e32 v48, 0xbfb8aa3b, v3
	v_exp_f32_e32 v48, v48
	s_nop 0
	v_add_f32_e32 v48, 1.0, v48
	v_div_scale_f32 v49, s[0:1], v48, v48, v3
	s_nop 0
	v_rcp_f32_e32 v49, v48
	s_nop 0
	v_mul_f32_e32 v3, v3, v49
	v_mul_f32_e32 v3, v47, v3
	v_cvt_pk_bf16_f32 v3, v3, s0
	ds_write_b16 v1, v3 offset:6864
	ds_read_u16 v3, v1 offset:7136
	v_mul_f32_e32 v47, v108, v21
	v_mul_f32_e32 v47, v47, v234
	s_waitcnt lgkmcnt(0)
	v_lshlrev_b32_e32 v3, 16, v3
	v_mul_f32_e32 v48, 0xbfb8aa3b, v3
	v_exp_f32_e32 v48, v48
	s_nop 0
	v_add_f32_e32 v48, 1.0, v48
	v_div_scale_f32 v49, s[0:1], v48, v48, v3
	s_nop 0
	v_rcp_f32_e32 v49, v48
	s_nop 0
	v_mul_f32_e32 v3, v3, v49
	v_mul_f32_e32 v3, v47, v3
	v_cvt_pk_bf16_f32 v3, v3, s0
	ds_write_b16 v1, v3 offset:7136
	ds_read_u16 v3, v1 offset:7408
	v_mul_f32_e32 v47, v107, v20
	v_mul_f32_e32 v2, v47, v234
	s_waitcnt lgkmcnt(0)
	v_lshlrev_b32_e32 v3, 16, v3
	v_mul_f32_e32 v47, 0xbfb8aa3b, v3
	v_exp_f32_e32 v47, v47
	s_nop 0
	v_add_f32_e32 v47, 1.0, v47
	v_div_scale_f32 v48, s[0:1], v47, v47, v3
	s_nop 0
	v_rcp_f32_e32 v48, v47
	s_nop 0
	v_mul_f32_e32 v3, v3, v48
	v_mul_f32_e32 v2, v2, v3
	v_cvt_pk_bf16_f32 v2, v2, s0
	ds_write_b16 v1, v2 offset:7408
	ds_read_u16 v3, v1 offset:128
	v_mul_f32_e32 v47, v106, v46
	s_waitcnt lgkmcnt(0)
	v_lshlrev_b32_e32 v3, 16, v3
	v_mul_f32_e32 v48, 0xbfb8aa3b, v3
	v_exp_f32_e32 v48, v48
	s_waitcnt vmcnt(0)
	v_mul_f32_e32 v47, v47, v236
	v_add_f32_e32 v48, 1.0, v48
	v_div_scale_f32 v49, s[0:1], v48, v48, v3
	v_mul_f32_e32 v39, v39, v236
	v_mul_f32_e32 v38, v38, v236
	v_mul_f32_e32 v37, v37, v236
	v_rcp_f32_e32 v49, v48
	s_nop 0
	v_mul_f32_e32 v3, v3, v49
	v_mul_f32_e32 v3, v47, v3
	v_cvt_pk_bf16_f32 v3, v3, s0
	ds_write_b16 v1, v3 offset:128
	ds_read_u16 v3, v1 offset:400
	v_mul_f32_e32 v47, v105, v45
	v_mul_f32_e32 v47, v47, v236
	v_mul_f32_e32 v36, v36, v236
	v_mul_f32_e32 v34, v34, v236
	s_waitcnt lgkmcnt(0)
	v_lshlrev_b32_e32 v3, 16, v3
	v_mul_f32_e32 v48, 0xbfb8aa3b, v3
	v_exp_f32_e32 v48, v48
	v_mul_f32_e32 v33, v33, v236
	v_mul_f32_e32 v32, v32, v236
	v_mul_f32_e32 v30, v30, v236
	v_add_f32_e32 v48, 1.0, v48
	v_div_scale_f32 v49, s[0:1], v48, v48, v3
	v_mul_f32_e32 v29, v29, v236
	v_mul_f32_e32 v28, v28, v236
	v_rcp_f32_e32 v49, v48
	s_nop 0
	v_mul_f32_e32 v3, v3, v49
	v_mul_f32_e32 v3, v47, v3
	v_cvt_pk_bf16_f32 v3, v3, s0
	ds_write_b16 v1, v3 offset:400
	ds_read_u16 v3, v1 offset:672
	v_mul_f32_e32 v47, v104, v44
	v_mul_f32_e32 v47, v47, v236
	s_waitcnt lgkmcnt(0)
	v_lshlrev_b32_e32 v3, 16, v3
	v_mul_f32_e32 v48, 0xbfb8aa3b, v3
	v_exp_f32_e32 v48, v48
	s_nop 0
	v_add_f32_e32 v48, 1.0, v48
	v_div_scale_f32 v49, s[0:1], v48, v48, v3
	s_nop 0
	v_rcp_f32_e32 v49, v48
	s_nop 0
	v_mul_f32_e32 v3, v3, v49
	v_mul_f32_e32 v3, v47, v3
	v_cvt_pk_bf16_f32 v3, v3, s0
	ds_write_b16 v1, v3 offset:672
	ds_read_u16 v3, v1 offset:944
	v_mul_f32_e32 v47, v103, v43
	v_mul_f32_e32 v47, v47, v236
	s_waitcnt lgkmcnt(0)
	v_lshlrev_b32_e32 v3, 16, v3
	v_mul_f32_e32 v48, 0xbfb8aa3b, v3
	v_exp_f32_e32 v48, v48
	s_nop 0
	v_add_f32_e32 v48, 1.0, v48
	v_div_scale_f32 v49, s[0:1], v48, v48, v3
	s_nop 0
	v_rcp_f32_e32 v49, v48
	s_nop 0
	v_mul_f32_e32 v3, v3, v49
	v_mul_f32_e32 v3, v47, v3
	v_cvt_pk_bf16_f32 v3, v3, s0
	ds_write_b16 v1, v3 offset:944
	ds_read_u16 v3, v1 offset:2304
	v_mul_f32_e32 v47, v102, v42
	v_mul_f32_e32 v47, v47, v236
	v_mul_f32_e32 v2, v26, v236
	s_waitcnt lgkmcnt(0)
	v_lshlrev_b32_e32 v3, 16, v3
	v_mul_f32_e32 v48, 0xbfb8aa3b, v3
	v_exp_f32_e32 v48, v48
	s_nop 0
	v_add_f32_e32 v48, 1.0, v48
	v_div_scale_f32 v49, s[0:1], v48, v48, v3
	s_nop 0
	v_rcp_f32_e32 v49, v48
	s_nop 0
	v_mul_f32_e32 v3, v3, v49
	v_mul_f32_e32 v3, v47, v3
	v_cvt_pk_bf16_f32 v3, v3, s0
	ds_write_b16 v1, v3 offset:2304
	ds_read_u16 v3, v1 offset:2576
	s_waitcnt lgkmcnt(0)
	v_lshlrev_b32_e32 v3, 16, v3
	v_mul_f32_e32 v47, 0xbfb8aa3b, v3
	v_exp_f32_e32 v47, v47
	s_nop 0
	v_add_f32_e32 v47, 1.0, v47
	v_div_scale_f32 v48, s[0:1], v47, v47, v3
	s_nop 0
	v_rcp_f32_e32 v48, v47
	s_nop 0
	v_mul_f32_e32 v3, v3, v48
	v_mul_f32_e32 v3, v39, v3
	v_cvt_pk_bf16_f32 v3, v3, s0
	ds_write_b16 v1, v3 offset:2576
	ds_read_u16 v3, v1 offset:2848
	s_waitcnt lgkmcnt(0)
; #define LAS __attribute__((address_space(3)))
; DI unsigned cvtpk(float lo, float hi) { f32x2 v = {lo, hi}; bf16x2_t b = __builtin_convertvector(v, bf16x2_t); return __builtin_bit_cast(unsigned, b); }
; DI float bf2f(bf16 b) { return __uint_as_float(((unsigned)b) << 16); }
; DI float siluf_(float x) { return x / (1.f + __expf(-x)); }
; DI void gla_stage3(const Ctx& c0, int layer, int unit, int cb, LAS unsigned char* lds) {
;     ...
; #pragma unroll
;     for (int vb = 0; vb < 4; ++vb) { const float g = gn[32 * vb + r];
; #pragma unroll
;         for (int rg = 0; rg < 16; ++rg) { LAS bf16* e = (LAS bf16*)(R + (4 * hi) * G3_PITCH + r * 2 + ((rg & 3) + 8 * (rg >> 2)) * G3_PITCH + 64 * vb);
;             const float z = bf2f(*e);
;             *e = (bf16)(cvtpk(o[vb][rg] * rs[rg] * g * siluf_(z), 0.f) & 0xffffu); }
;         asm volatile("" ::: "memory"); }
	v_lshlrev_b32_e32 v3, 16, v3
	v_mul_f32_e32 v39, 0xbfb8aa3b, v3
	v_exp_f32_e32 v39, v39
	s_nop 0
	v_add_f32_e32 v39, 1.0, v39
	v_div_scale_f32 v47, s[0:1], v39, v39, v3
	s_nop 0
	v_rcp_f32_e32 v47, v39
	s_nop 0
	v_mul_f32_e32 v3, v3, v47
	v_mul_f32_e32 v3, v38, v3
	v_cvt_pk_bf16_f32 v3, v3, s0
	ds_write_b16 v1, v3 offset:2848
	ds_read_u16 v3, v1 offset:3120
	s_waitcnt lgkmcnt(0)
	v_lshlrev_b32_e32 v3, 16, v3
	v_mul_f32_e32 v38, 0xbfb8aa3b, v3
	v_exp_f32_e32 v38, v38
	s_nop 0
	v_add_f32_e32 v38, 1.0, v38
	v_div_scale_f32 v39, s[0:1], v38, v38, v3
	s_nop 0
	v_rcp_f32_e32 v39, v38
	s_nop 0
	v_mul_f32_e32 v3, v3, v39
	v_mul_f32_e32 v3, v37, v3
	v_cvt_pk_bf16_f32 v3, v3, s0
	ds_write_b16 v1, v3 offset:3120
	ds_read_u16 v3, v1 offset:4480
	s_waitcnt lgkmcnt(0)
	v_lshlrev_b32_e32 v3, 16, v3
	v_mul_f32_e32 v37, 0xbfb8aa3b, v3
	v_exp_f32_e32 v37, v37
	s_nop 0
	v_add_f32_e32 v37, 1.0, v37
	v_div_scale_f32 v38, s[0:1], v37, v37, v3
	s_nop 0
	v_rcp_f32_e32 v38, v37
	s_nop 0
	v_mul_f32_e32 v3, v3, v38
	v_mul_f32_e32 v3, v36, v3
	v_cvt_pk_bf16_f32 v3, v3, s0
	ds_write_b16 v1, v3 offset:4480
	ds_read_u16 v3, v1 offset:4752
	s_waitcnt lgkmcnt(0)
	v_lshlrev_b32_e32 v3, 16, v3
	v_mul_f32_e32 v36, 0xbfb8aa3b, v3
	v_exp_f32_e32 v36, v36
	s_nop 0
	v_add_f32_e32 v36, 1.0, v36
	v_div_scale_f32 v37, s[0:1], v36, v36, v3
	s_nop 0
	v_rcp_f32_e32 v37, v36
	s_nop 0
	v_mul_f32_e32 v3, v3, v37
	v_mul_f32_e32 v3, v34, v3
	v_cvt_pk_bf16_f32 v3, v3, s0
	ds_write_b16 v1, v3 offset:4752
	ds_read_u16 v3, v1 offset:5024
	s_waitcnt lgkmcnt(0)
	v_lshlrev_b32_e32 v3, 16, v3
	v_mul_f32_e32 v34, 0xbfb8aa3b, v3
	v_exp_f32_e32 v34, v34
	s_nop 0
	v_add_f32_e32 v34, 1.0, v34
	v_div_scale_f32 v36, s[0:1], v34, v34, v3
	s_nop 0
	v_rcp_f32_e32 v36, v34
	s_nop 0
	v_mul_f32_e32 v3, v3, v36
	v_mul_f32_e32 v3, v33, v3
	v_cvt_pk_bf16_f32 v3, v3, s0
	ds_write_b16 v1, v3 offset:5024
	ds_read_u16 v3, v1 offset:5296
	s_waitcnt lgkmcnt(0)
	v_lshlrev_b32_e32 v3, 16, v3
	v_mul_f32_e32 v33, 0xbfb8aa3b, v3
	v_exp_f32_e32 v33, v33
	s_nop 0
	v_add_f32_e32 v33, 1.0, v33
	v_div_scale_f32 v34, s[0:1], v33, v33, v3
	s_nop 0
	v_rcp_f32_e32 v34, v33
	s_nop 0
	v_mul_f32_e32 v3, v3, v34
	v_mul_f32_e32 v3, v32, v3
	v_cvt_pk_bf16_f32 v3, v3, s0
	ds_write_b16 v1, v3 offset:5296
	ds_read_u16 v3, v1 offset:6656
	s_waitcnt lgkmcnt(0)
	v_lshlrev_b32_e32 v3, 16, v3
	v_mul_f32_e32 v32, 0xbfb8aa3b, v3
	v_exp_f32_e32 v32, v32
	s_nop 0
	v_add_f32_e32 v32, 1.0, v32
	v_div_scale_f32 v33, s[0:1], v32, v32, v3
	s_nop 0
	v_rcp_f32_e32 v33, v32
	s_nop 0
	v_mul_f32_e32 v3, v3, v33
	v_mul_f32_e32 v3, v30, v3
	v_cvt_pk_bf16_f32 v3, v3, s0
	ds_write_b16 v1, v3 offset:6656
	ds_read_u16 v3, v1 offset:6928
	s_waitcnt lgkmcnt(0)
	v_lshlrev_b32_e32 v3, 16, v3
	v_mul_f32_e32 v30, 0xbfb8aa3b, v3
	v_exp_f32_e32 v30, v30
	s_nop 0
	v_add_f32_e32 v30, 1.0, v30
	v_div_scale_f32 v32, s[0:1], v30, v30, v3
	s_nop 0
	v_rcp_f32_e32 v32, v30
	s_nop 0
	v_mul_f32_e32 v3, v3, v32
	v_mul_f32_e32 v3, v29, v3
	v_cvt_pk_bf16_f32 v3, v3, s0
	ds_write_b16 v1, v3 offset:6928
	ds_read_u16 v3, v1 offset:7200
	s_waitcnt lgkmcnt(0)
	v_lshlrev_b32_e32 v3, 16, v3
	v_mul_f32_e32 v29, 0xbfb8aa3b, v3
	v_exp_f32_e32 v29, v29
	s_nop 0
	v_add_f32_e32 v29, 1.0, v29
	v_div_scale_f32 v30, s[0:1], v29, v29, v3
	s_nop 0
	v_rcp_f32_e32 v30, v29
	s_nop 0
	v_mul_f32_e32 v3, v3, v30
	v_mul_f32_e32 v3, v28, v3
	v_cvt_pk_bf16_f32 v3, v3, s0
	ds_write_b16 v1, v3 offset:7200
	ds_read_u16 v3, v1 offset:7472
	s_waitcnt lgkmcnt(0)
	v_lshlrev_b32_e32 v3, 16, v3
	v_mul_f32_e32 v26, 0xbfb8aa3b, v3
	v_exp_f32_e32 v26, v26
	s_nop 0
	v_add_f32_e32 v26, 1.0, v26
	v_div_scale_f32 v28, s[0:1], v26, v26, v3
	s_nop 0
	v_rcp_f32_e32 v28, v26
	s_nop 0
	v_mul_f32_e32 v3, v3, v28
	v_mul_f32_e32 v2, v2, v3
	v_cvt_pk_bf16_f32 v2, v2, s0
	ds_write_b16 v1, v2 offset:7472
	ds_read_u16 v3, v1 offset:192
	s_waitcnt lgkmcnt(0)
	v_lshlrev_b32_e32 v3, 16, v3
	v_mul_f32_e32 v26, 0xbfb8aa3b, v3
	v_exp_f32_e32 v26, v26
	s_waitcnt vmcnt(31)
	v_mul_f32_e32 v19, v19, v238
	v_add_f32_e32 v26, 1.0, v26
	v_div_scale_f32 v28, s[0:1], v26, v26, v3
	v_mul_f32_e32 v18, v18, v238
	v_mul_f32_e32 v17, v17, v238
	v_mul_f32_e32 v16, v16, v238
	v_rcp_f32_e32 v28, v26
	s_nop 0
	v_mul_f32_e32 v3, v3, v28
	v_mul_f32_e32 v3, v19, v3
	v_cvt_pk_bf16_f32 v3, v3, s0
	ds_write_b16 v1, v3 offset:192
	ds_read_u16 v3, v1 offset:464
	v_mul_f32_e32 v15, v15, v238
	v_mul_f32_e32 v14, v14, v238
	v_mul_f32_e32 v13, v13, v238
	v_mul_f32_e32 v12, v12, v238
	s_waitcnt lgkmcnt(0)
	v_lshlrev_b32_e32 v3, 16, v3
	v_mul_f32_e32 v19, 0xbfb8aa3b, v3
	v_exp_f32_e32 v19, v19
	v_mul_f32_e32 v11, v11, v238
	v_mul_f32_e32 v10, v10, v238
	v_mul_f32_e32 v9, v9, v238
	v_add_f32_e32 v19, 1.0, v19
	v_div_scale_f32 v26, s[0:1], v19, v19, v3
	v_mul_f32_e32 v8, v8, v238
	v_mul_f32_e32 v7, v7, v238
	v_mul_f32_e32 v6, v6, v238
	v_rcp_f32_e32 v26, v19
	s_nop 0
	v_mul_f32_e32 v3, v3, v26
	v_mul_f32_e32 v3, v18, v3
	v_cvt_pk_bf16_f32 v3, v3, s0
	ds_write_b16 v1, v3 offset:464
	ds_read_u16 v3, v1 offset:736
	v_mul_f32_e32 v5, v5, v238
	v_mul_f32_e32 v2, v4, v238
	s_waitcnt lgkmcnt(0)
	v_lshlrev_b32_e32 v3, 16, v3
	v_mul_f32_e32 v18, 0xbfb8aa3b, v3
	v_exp_f32_e32 v18, v18
	s_nop 0
	v_add_f32_e32 v18, 1.0, v18
	v_div_scale_f32 v19, s[0:1], v18, v18, v3
	s_nop 0
	v_rcp_f32_e32 v19, v18
	s_nop 0
	v_mul_f32_e32 v3, v3, v19
	v_mul_f32_e32 v3, v17, v3
	v_cvt_pk_bf16_f32 v3, v3, s0
	ds_write_b16 v1, v3 offset:736
	ds_read_u16 v3, v1 offset:1008
	s_waitcnt lgkmcnt(0)
	v_lshlrev_b32_e32 v3, 16, v3
	v_mul_f32_e32 v17, 0xbfb8aa3b, v3
	v_exp_f32_e32 v17, v17
	s_nop 0
	v_add_f32_e32 v17, 1.0, v17
	v_div_scale_f32 v18, s[0:1], v17, v17, v3
	s_nop 0
	v_rcp_f32_e32 v18, v17
	s_nop 0
	v_mul_f32_e32 v3, v3, v18
	v_mul_f32_e32 v3, v16, v3
	v_cvt_pk_bf16_f32 v3, v3, s0
	ds_write_b16 v1, v3 offset:1008
	ds_read_u16 v3, v1 offset:2368
	s_waitcnt lgkmcnt(0)
; #define LAS __attribute__((address_space(3)))
; #define LDS_WAIT() asm volatile("s_waitcnt lgkmcnt(0)" ::: "memory")
; DI unsigned cvtpk(float lo, float hi) { f32x2 v = {lo, hi}; bf16x2_t b = __builtin_convertvector(v, bf16x2_t); return __builtin_bit_cast(unsigned, b); }
; DI float bf2f(bf16 b) { return __uint_as_float(((unsigned)b) << 16); }
; DI float siluf_(float x) { return x / (1.f + __expf(-x)); }
; DI void g3_tile_out(bf16* g, const LAS unsigned char* R, int lane) {
;     LDS_WAIT();
; #pragma unroll
;     for (int it = 0; it < 8; ++it) { const int row = 4 * it + (lane >> 4), ch = lane & 15;
;         *(u32x4*)(g + (size_t)row * 512 + ch * 8) = *(const LAS u32x4*)(R + row * G3_PITCH + ch * 16); }
;     LDS_WAIT();
; }
; DI void gla_stage3(const Ctx& c0, int layer, int unit, int cb, LAS unsigned char* lds) {
;     ...
; #pragma unroll
;     for (int vb = 0; vb < 4; ++vb) { const float g = gn[32 * vb + r];
; #pragma unroll
;         for (int rg = 0; rg < 16; ++rg) { LAS bf16* e = (LAS bf16*)(R + (4 * hi) * G3_PITCH + r * 2 + ((rg & 3) + 8 * (rg >> 2)) * G3_PITCH + 64 * vb);
;             const float z = bf2f(*e);
;             *e = (bf16)(cvtpk(o[vb][rg] * rs[rg] * g * siluf_(z), 0.f) & 0xffffu); }
;         asm volatile("" ::: "memory"); }
;     g3_tile_out((bf16*)(c.ws + O_OGLA) + row0 * 512 + h * 128, R, lane);
	v_lshlrev_b32_e32 v3, 16, v3
	v_mul_f32_e32 v16, 0xbfb8aa3b, v3
	v_exp_f32_e32 v16, v16
	s_nop 0
	v_add_f32_e32 v16, 1.0, v16
	v_div_scale_f32 v17, s[0:1], v16, v16, v3
	s_nop 0
	v_rcp_f32_e32 v17, v16
	s_nop 0
	v_mul_f32_e32 v3, v3, v17
	v_mul_f32_e32 v3, v15, v3
	v_cvt_pk_bf16_f32 v3, v3, s0
	ds_write_b16 v1, v3 offset:2368
	ds_read_u16 v3, v1 offset:2640
	s_waitcnt lgkmcnt(0)
	v_lshlrev_b32_e32 v3, 16, v3
	v_mul_f32_e32 v15, 0xbfb8aa3b, v3
	v_exp_f32_e32 v15, v15
	s_nop 0
	v_add_f32_e32 v15, 1.0, v15
	v_div_scale_f32 v16, s[0:1], v15, v15, v3
	s_nop 0
	v_rcp_f32_e32 v16, v15
	s_nop 0
	v_mul_f32_e32 v3, v3, v16
	v_mul_f32_e32 v3, v14, v3
	v_cvt_pk_bf16_f32 v3, v3, s0
	ds_write_b16 v1, v3 offset:2640
	ds_read_u16 v3, v1 offset:2912
	s_waitcnt lgkmcnt(0)
	v_lshlrev_b32_e32 v3, 16, v3
	v_mul_f32_e32 v14, 0xbfb8aa3b, v3
	v_exp_f32_e32 v14, v14
	s_nop 0
	v_add_f32_e32 v14, 1.0, v14
	v_div_scale_f32 v15, s[0:1], v14, v14, v3
	s_nop 0
	v_rcp_f32_e32 v15, v14
	s_nop 0
	v_mul_f32_e32 v3, v3, v15
	v_mul_f32_e32 v3, v13, v3
	v_cvt_pk_bf16_f32 v3, v3, s0
	ds_write_b16 v1, v3 offset:2912
	ds_read_u16 v3, v1 offset:3184
	s_waitcnt lgkmcnt(0)
	v_lshlrev_b32_e32 v3, 16, v3
	v_mul_f32_e32 v13, 0xbfb8aa3b, v3
	v_exp_f32_e32 v13, v13
	s_nop 0
	v_add_f32_e32 v13, 1.0, v13
	v_div_scale_f32 v14, s[0:1], v13, v13, v3
	s_nop 0
	v_rcp_f32_e32 v14, v13
	s_nop 0
	v_mul_f32_e32 v3, v3, v14
	v_mul_f32_e32 v3, v12, v3
	v_cvt_pk_bf16_f32 v3, v3, s0
	ds_write_b16 v1, v3 offset:3184
	ds_read_u16 v3, v1 offset:4544
	s_waitcnt lgkmcnt(0)
	v_lshlrev_b32_e32 v3, 16, v3
	v_mul_f32_e32 v12, 0xbfb8aa3b, v3
	v_exp_f32_e32 v12, v12
	s_nop 0
	v_add_f32_e32 v12, 1.0, v12
	v_div_scale_f32 v13, s[0:1], v12, v12, v3
	s_nop 0
	v_rcp_f32_e32 v13, v12
	s_nop 0
	v_mul_f32_e32 v3, v3, v13
	v_mul_f32_e32 v3, v11, v3
	v_cvt_pk_bf16_f32 v3, v3, s0
	ds_write_b16 v1, v3 offset:4544
	ds_read_u16 v3, v1 offset:4816
	s_waitcnt lgkmcnt(0)
	v_lshlrev_b32_e32 v3, 16, v3
	v_mul_f32_e32 v11, 0xbfb8aa3b, v3
	v_exp_f32_e32 v11, v11
	s_nop 0
	v_add_f32_e32 v11, 1.0, v11
	v_div_scale_f32 v12, s[0:1], v11, v11, v3
	s_nop 0
	v_rcp_f32_e32 v12, v11
	s_nop 0
	v_mul_f32_e32 v3, v3, v12
	v_mul_f32_e32 v3, v10, v3
	v_cvt_pk_bf16_f32 v3, v3, s0
	ds_write_b16 v1, v3 offset:4816
	ds_read_u16 v3, v1 offset:5088
	s_waitcnt lgkmcnt(0)
	v_lshlrev_b32_e32 v3, 16, v3
	v_mul_f32_e32 v10, 0xbfb8aa3b, v3
	v_exp_f32_e32 v10, v10
	s_nop 0
	v_add_f32_e32 v10, 1.0, v10
	v_div_scale_f32 v11, s[0:1], v10, v10, v3
	s_nop 0
	v_rcp_f32_e32 v11, v10
	s_nop 0
	v_mul_f32_e32 v3, v3, v11
	v_mul_f32_e32 v3, v9, v3
	v_cvt_pk_bf16_f32 v3, v3, s0
	ds_write_b16 v1, v3 offset:5088
	ds_read_u16 v3, v1 offset:5360
	s_waitcnt lgkmcnt(0)
	v_lshlrev_b32_e32 v3, 16, v3
	v_mul_f32_e32 v9, 0xbfb8aa3b, v3
	v_exp_f32_e32 v9, v9
	s_nop 0
	v_add_f32_e32 v9, 1.0, v9
	v_div_scale_f32 v10, s[0:1], v9, v9, v3
	s_nop 0
	v_rcp_f32_e32 v10, v9
	s_nop 0
	v_mul_f32_e32 v3, v3, v10
	v_mul_f32_e32 v3, v8, v3
	v_cvt_pk_bf16_f32 v3, v3, s0
	ds_write_b16 v1, v3 offset:5360
	ds_read_u16 v3, v1 offset:6720
	s_waitcnt lgkmcnt(0)
	v_lshlrev_b32_e32 v3, 16, v3
	v_mul_f32_e32 v8, 0xbfb8aa3b, v3
	v_exp_f32_e32 v8, v8
	s_nop 0
	v_add_f32_e32 v8, 1.0, v8
	v_div_scale_f32 v9, s[0:1], v8, v8, v3
	s_nop 0
	v_rcp_f32_e32 v9, v8
	s_nop 0
	v_mul_f32_e32 v3, v3, v9
	v_mul_f32_e32 v3, v7, v3
	v_cvt_pk_bf16_f32 v3, v3, s0
	ds_write_b16 v1, v3 offset:6720
	ds_read_u16 v3, v1 offset:6992
	s_waitcnt lgkmcnt(0)
	v_lshlrev_b32_e32 v3, 16, v3
	v_mul_f32_e32 v7, 0xbfb8aa3b, v3
	v_exp_f32_e32 v7, v7
	s_nop 0
	v_add_f32_e32 v7, 1.0, v7
	v_div_scale_f32 v8, s[0:1], v7, v7, v3
	s_nop 0
	v_rcp_f32_e32 v8, v7
	s_nop 0
	v_mul_f32_e32 v3, v3, v8
	v_mul_f32_e32 v3, v6, v3
	v_cvt_pk_bf16_f32 v3, v3, s0
	ds_write_b16 v1, v3 offset:6992
	ds_read_u16 v3, v1 offset:7264
	s_waitcnt lgkmcnt(0)
	v_lshlrev_b32_e32 v3, 16, v3
	v_mul_f32_e32 v6, 0xbfb8aa3b, v3
	v_exp_f32_e32 v6, v6
	s_nop 0
	v_add_f32_e32 v6, 1.0, v6
	v_div_scale_f32 v7, s[0:1], v6, v6, v3
	s_nop 0
	v_rcp_f32_e32 v7, v6
	s_nop 0
	v_mul_f32_e32 v3, v3, v7
	v_mul_f32_e32 v3, v5, v3
	v_cvt_pk_bf16_f32 v3, v3, s0
	ds_write_b16 v1, v3 offset:7264
	ds_read_u16 v3, v1 offset:7536
	s_waitcnt lgkmcnt(0)
	v_lshlrev_b32_e32 v3, 16, v3
	v_mul_f32_e32 v4, 0xbfb8aa3b, v3
	v_exp_f32_e32 v4, v4
	s_nop 0
	v_add_f32_e32 v4, 1.0, v4
	v_div_scale_f32 v5, s[0:1], v4, v4, v3
	s_nop 0
	v_rcp_f32_e32 v5, v4
	s_nop 0
	v_mul_f32_e32 v3, v3, v5
	v_mul_f32_e32 v2, v2, v3
	v_cvt_pk_bf16_f32 v2, v2, s0
	ds_write_b16 v1, v2 offset:7536
	s_waitcnt lgkmcnt(0)
	ds_read_b128 v[2:5], v92
	v_lshl_add_u64 v[6:7], v[90:91], 0, s[22:23]
	v_lshl_add_u64 v[8:9], v[6:7], 0, v[66:67]
	s_waitcnt lgkmcnt(0)
	global_store_dwordx4 v[8:9], v[2:5], off
	ds_read_b128 v[2:5], v92 offset:1088
	v_lshl_add_u64 v[8:9], v[6:7], 0, v[68:69]
	s_waitcnt lgkmcnt(0)
	global_store_dwordx4 v[8:9], v[2:5], off
	ds_read_b128 v[2:5], v92 offset:2176
	v_lshl_add_u64 v[8:9], v[6:7], 0, v[70:71]
	s_waitcnt lgkmcnt(0)
	global_store_dwordx4 v[8:9], v[2:5], off
	ds_read_b128 v[2:5], v92 offset:3264
	v_lshl_add_u64 v[8:9], v[6:7], 0, v[72:73]
	s_waitcnt lgkmcnt(0)
	global_store_dwordx4 v[8:9], v[2:5], off
	ds_read_b128 v[2:5], v92 offset:4352
	v_lshl_add_u64 v[8:9], v[6:7], 0, v[74:75]
	s_waitcnt lgkmcnt(0)
	global_store_dwordx4 v[8:9], v[2:5], off
	ds_read_b128 v[2:5], v92 offset:5440
	v_lshl_add_u64 v[8:9], v[6:7], 0, v[76:77]
	s_waitcnt lgkmcnt(0)
	global_store_dwordx4 v[8:9], v[2:5], off
	ds_read_b128 v[2:5], v92 offset:6528
	v_lshl_add_u64 v[8:9], v[6:7], 0, v[78:79]
	v_lshl_add_u64 v[6:7], v[6:7], 0, v[80:81]
	s_waitcnt lgkmcnt(0)
	global_store_dwordx4 v[8:9], v[2:5], off
	ds_read_b128 v[2:5], v92 offset:7616
	s_waitcnt lgkmcnt(0)
	global_store_dwordx4 v[6:7], v[2:5], off
	s_waitcnt lgkmcnt(0)
	s_cbranch_scc1 .LBB0_604

; #define MFMA32(a, b, c) __builtin_amdgcn_mfma_f32_32x32x16_bf16((a), (b), (c), 0, 0, 0)
; DI void gla_stage3(const Ctx& c0, int layer, int unit, int cb, LAS unsigned char* lds) {
;     ...
;     const bf16* qgp = (const bf16*)(c.ws + O_QG) + (row0 + r) * 256 + h * 64 + 8 * hi;
;     const float* sp = (const float*)(c.ws + O_UPD) + (size_t)unit * 8192;
;     const float* gn = c.a->in[I_GNORM] + (size_t)layer * 128;
;     bf16x8 qf[4];
; #pragma unroll
;     for (int s = 0; s < 4; ++s) qf[s] = *(const bf16x8*)(qgp + 16 * s);
;     f32x16 o[4];
; #pragma unroll
;     for (int vb = 0; vb < 4; ++vb) {
;         o[vb] = f32x16{};
; #pragma unroll
;         for (int s = 0; s < 4; ++s) { const float* s0 = sp + (size_t)(16 * s + 8 * hi) * 128 + 32 * vb + r;
;             const bf16x8 bfv = pack8(s0[0], s0[128], s0[256], s0[384], s0[512], s0[640], s0[768], s0[896]);
;             o[vb] = MFMA32(qf[s], bfv, o[vb]); }
;         asm volatile("" ::: "memory");
;     }
.LBB0_1216:
	s_mov_b64 s[0:1], s[74:75]
	s_mov_b64 s[2:3], s[72:73]
	s_ashr_i32 s2, s34, 8
	s_ashr_i32 s3, s2, 31
	s_lshl_b64 s[2:3], s[2:3], 12
	s_and_b32 s9, s4, 0xfc0
	s_or_b32 s2, s2, s9
	s_or_b64 s[2:3], s[2:3], s[10:11]
	v_mov_b32_e32 v3, s3
	v_or_b32_e32 v2, s2, v152
	s_bfe_u32 s8, s34, 0x20006
	v_lshlrev_b64 v[2:3], 9, v[2:3]
	v_lshl_add_u64 v[2:3], s[0:1], 0, v[2:3]
	s_lshl_b32 s12, s8, 7
	v_lshl_add_u64 v[2:3], v[2:3], 0, s[12:13]
	v_lshl_add_u64 v[2:3], v[2:3], 0, v[86:87]
	v_lshl_add_u64 v[4:5], v[2:3], 0, s[18:19]
	v_add_co_u32_e32 v2, vcc, s6, v2
	v_lshl_add_u64 v[90:91], s[0:1], 0, v[84:85]
	s_nop 0
	v_addc_co_u32_e32 v3, vcc, 0, v3, vcc
	global_load_dwordx4 v[50:53], v[2:3], off
	global_load_dwordx4 v[110:113], v[4:5], off offset:96
	global_load_dwordx4 v[106:109], v[4:5], off offset:64
	global_load_dwordx4 v[102:105], v[4:5], off offset:32
	v_add_co_u32_e32 v2, vcc, s7, v90
	s_lshl_b64 s[2:3], s[2:3], 10
	s_nop 0
	v_addc_co_u32_e32 v3, vcc, -1, v91, vcc
	v_add_co_u32_e32 v58, vcc, s28, v90
	global_load_dword v2, v[2:3], off
	s_nop 0
	v_addc_co_u32_e32 v59, vcc, -1, v91, vcc
	global_load_dword v3, v[58:59], off offset:384
	global_load_dword v4, v[58:59], off offset:896
	global_load_dword v5, v[58:59], off offset:1408
	global_load_dword v6, v[58:59], off offset:1920
	global_load_dword v7, v[58:59], off offset:2432
	global_load_dword v8, v[58:59], off offset:2944
	global_load_dword v9, v[58:59], off offset:3456
	v_add_co_u32_e32 v18, vcc, s15, v90
	s_lshl_b32 s8, s8, 8
	s_nop 0
	v_addc_co_u32_e32 v19, vcc, -1, v91, vcc
	v_add_co_u32_e32 v114, vcc, s29, v90
	global_load_dword v18, v[18:19], off
	s_nop 0
	v_addc_co_u32_e32 v115, vcc, -1, v91, vcc
	global_load_dword v19, v[114:115], off offset:384
	global_load_dword v20, v[114:115], off offset:896
	global_load_dword v21, v[114:115], off offset:1408
	global_load_dword v22, v[114:115], off offset:1920
	global_load_dword v23, v[114:115], off offset:2432
	global_load_dword v24, v[114:115], off offset:2944
	global_load_dword v25, v[114:115], off offset:3456
	s_add_u32 s0, s0, s2
	s_addc_u32 s1, s1, s3
	s_add_u32 s0, s0, s8
	s_addc_u32 s1, s1, 0
	s_add_i32 s34, s34, s14
	s_add_i32 s4, s4, s5
	v_lshl_add_u64 v[84:85], v[84:85], 0, s[16:17]
	s_cmpk_lt_i32 s34, 0x800
	v_add_co_u32_e32 v26, vcc, s26, v90
	s_nop 1
	v_addc_co_u32_e32 v27, vcc, -1, v91, vcc
	v_add_co_u32_e32 v118, vcc, s30, v90
	global_load_dword v26, v[26:27], off
	s_nop 0
	v_addc_co_u32_e32 v119, vcc, -1, v91, vcc
	global_load_dword v27, v[118:119], off offset:384
	global_load_dword v28, v[118:119], off offset:896
	global_load_dword v29, v[118:119], off offset:1408
	global_load_dword v30, v[118:119], off offset:1920
	global_load_dword v31, v[118:119], off offset:2432
	global_load_dword v32, v[118:119], off offset:2944
	global_load_dword v33, v[118:119], off offset:3456
	v_add_co_u32_e32 v42, vcc, s27, v90
	s_nop 1
	v_addc_co_u32_e32 v43, vcc, -1, v91, vcc
	v_add_co_u32_e32 v120, vcc, s31, v90
	global_load_dword v42, v[42:43], off
	s_nop 0
	v_addc_co_u32_e32 v121, vcc, -1, v91, vcc
	global_load_dword v43, v[120:121], off offset:384
	global_load_dword v44, v[120:121], off offset:896
	global_load_dword v45, v[120:121], off offset:1408
	global_load_dword v46, v[120:121], off offset:1920
	global_load_dword v47, v[120:121], off offset:2432
	global_load_dword v48, v[120:121], off offset:2944
	global_load_dword v49, v[120:121], off offset:3456
	s_waitcnt vmcnt(16) lgkmcnt(0)
	global_load_dword v41, v[114:115], off offset:3584
	global_load_dword v40, v[114:115], off offset:3072
	global_load_dword v39, v[114:115], off offset:2560
	global_load_dword v38, v[114:115], off offset:2048
	global_load_dword v37, v[114:115], off offset:1536
	global_load_dword v36, v[114:115], off offset:1024
	global_load_dword v35, v[114:115], off offset:512
	global_load_dword v34, v[114:115], off
	global_load_dword v145, v[58:59], off offset:3584
	global_load_dword v146, v[58:59], off offset:3072
	global_load_dword v143, v[58:59], off offset:2560
	global_load_dword v144, v[58:59], off offset:2048
	global_load_dword v141, v[58:59], off offset:1536
	global_load_dword v142, v[58:59], off offset:1024
	global_load_dword v139, v[58:59], off offset:512
	global_load_dword v140, v[58:59], off
	v_cvt_pk_bf16_f32 v2, v2, v3
	v_cvt_pk_bf16_f32 v3, v4, v5
	v_cvt_pk_bf16_f32 v4, v6, v7
	v_cvt_pk_bf16_f32 v5, v8, v9
	v_cvt_pk_bf16_f32 v18, v18, v19
	s_nop 0
	v_mfma_f32_32x32x16_bf16 v[2:17], v[50:53], v[2:5], 0
	v_cvt_pk_bf16_f32 v19, v20, v21
	v_cvt_pk_bf16_f32 v20, v22, v23
	v_cvt_pk_bf16_f32 v21, v24, v25
	s_nop 1
	v_mfma_f32_32x32x16_bf16 v[2:17], v[102:105], v[18:21], v[2:17]
	s_waitcnt vmcnt(24) lgkmcnt(0)
	global_load_dword v63, v[114:115], off offset:3712
	global_load_dword v62, v[114:115], off offset:3200
	global_load_dword v61, v[114:115], off offset:2688
	global_load_dword v60, v[114:115], off offset:2176
	global_load_dword v57, v[114:115], off offset:1664
	global_load_dword v56, v[114:115], off offset:1152
	global_load_dword v55, v[114:115], off offset:640
	global_load_dword v54, v[114:115], off offset:128
	global_load_dword v173, v[58:59], off offset:3712
	global_load_dword v176, v[58:59], off offset:3200
	global_load_dword v171, v[58:59], off offset:2688
	global_load_dword v174, v[58:59], off offset:2176
	global_load_dword v169, v[58:59], off offset:1664
	global_load_dword v172, v[58:59], off offset:1152
	global_load_dword v167, v[58:59], off offset:640
	global_load_dword v170, v[58:59], off offset:128
	global_load_dword v157, v[118:119], off offset:3584
	global_load_dword v160, v[118:119], off offset:3072
	global_load_dword v155, v[118:119], off offset:2560
	global_load_dword v158, v[118:119], off offset:2048
	global_load_dword v149, v[118:119], off offset:1536
	global_load_dword v156, v[118:119], off offset:1024
	global_load_dword v147, v[118:119], off offset:512
	global_load_dword v148, v[118:119], off
	v_cvt_pk_bf16_f32 v26, v26, v27
	v_cvt_pk_bf16_f32 v27, v28, v29
	v_cvt_pk_bf16_f32 v28, v30, v31
	v_cvt_pk_bf16_f32 v29, v32, v33
	s_nop 1
	v_mfma_f32_32x32x16_bf16 v[2:17], v[106:109], v[26:29], v[2:17]
	v_cmp_lt_i32_e32 vcc, v94, v95
	s_waitcnt vmcnt(20) lgkmcnt(0)
; #define MFMA32(a, b, c) __builtin_amdgcn_mfma_f32_32x32x16_bf16((a), (b), (c), 0, 0, 0)
; DI void gla_stage3(const Ctx& c0, int layer, int unit, int cb, LAS unsigned char* lds) {
;     ...
;     for (int vb = 0; vb < 4; ++vb) {
;         o[vb] = f32x16{};
; #pragma unroll
;         for (int s = 0; s < 4; ++s) { const float* s0 = sp + (size_t)(16 * s + 8 * hi) * 128 + 32 * vb + r;
;             const bf16x8 bfv = pack8(s0[0], s0[128], s0[256], s0[384], s0[512], s0[640], s0[768], s0[896]);
;             o[vb] = MFMA32(qf[s], bfv, o[vb]); }
;         asm volatile("" ::: "memory");
;     }
;     ...
;     for (int vb = 0; vb < 4; ++vb) { const float g = gn[32 * vb + r];
	global_load_dword v127, v[114:115], off offset:3840
	global_load_dword v126, v[114:115], off offset:3328
	global_load_dword v125, v[114:115], off offset:2816
	global_load_dword v124, v[114:115], off offset:2304
	global_load_dword v123, v[114:115], off offset:1792
	global_load_dword v122, v[114:115], off offset:1280
	global_load_dword v117, v[114:115], off offset:768
	global_load_dword v116, v[114:115], off offset:256
	global_load_dword v214, v[58:59], off offset:3840
	global_load_dword v212, v[58:59], off offset:3328
	global_load_dword v205, v[58:59], off offset:2816
	global_load_dword v210, v[58:59], off offset:2304
	global_load_dword v203, v[58:59], off offset:1792
	global_load_dword v208, v[58:59], off offset:1280
	global_load_dword v201, v[58:59], off offset:768
	global_load_dword v206, v[58:59], off offset:256
	global_load_dword v199, v[120:121], off offset:3712
	global_load_dword v204, v[120:121], off offset:3200
	global_load_dword v197, v[120:121], off offset:2688
	global_load_dword v202, v[120:121], off offset:2176
	global_load_dword v195, v[120:121], off offset:1664
	global_load_dword v200, v[120:121], off offset:1152
	global_load_dword v183, v[120:121], off offset:640
	global_load_dword v198, v[120:121], off offset:128
	global_load_dword v181, v[118:119], off offset:3712
	global_load_dword v196, v[118:119], off offset:3200
	global_load_dword v179, v[118:119], off offset:2688
	global_load_dword v182, v[118:119], off offset:2176
	global_load_dword v177, v[118:119], off offset:1664
	global_load_dword v180, v[118:119], off offset:1152
	global_load_dword v175, v[118:119], off offset:640
	global_load_dword v178, v[118:119], off offset:128
	global_load_dword v165, v[120:121], off offset:3584
	global_load_dword v168, v[120:121], off offset:3072
	global_load_dword v163, v[120:121], off offset:2560
	global_load_dword v166, v[120:121], off offset:2048
	global_load_dword v161, v[120:121], off offset:1536
	global_load_dword v164, v[120:121], off offset:1024
	global_load_dword v159, v[120:121], off offset:512
	global_load_dword v162, v[120:121], off
	v_cvt_pk_bf16_f32 v42, v42, v43
	v_cvt_pk_bf16_f32 v43, v44, v45
	v_cvt_pk_bf16_f32 v44, v46, v47
	v_cvt_pk_bf16_f32 v45, v48, v49
	s_nop 1
	v_mfma_f32_32x32x16_bf16 v[2:17], v[110:113], v[42:45], v[2:17]
	s_waitcnt vmcnt(40) lgkmcnt(0)
	global_load_dword v238, v[82:83], off offset:896
	global_load_dword v236, v[82:83], off offset:768
	global_load_dword v234, v[82:83], off offset:640
	global_load_dword v232, v[82:83], off offset:512
	global_load_dword v90, v[90:91], off
	global_load_dword v230, v[120:121], off offset:3328
	global_load_dword v219, v[120:121], off offset:2816
	global_load_dword v228, v[120:121], off offset:2304
	global_load_dword v217, v[120:121], off offset:1792
	global_load_dword v226, v[120:121], off offset:1280
	global_load_dword v215, v[120:121], off offset:768
	global_load_dword v224, v[120:121], off offset:256
	global_load_dword v213, v[118:119], off offset:3840
	global_load_dword v222, v[118:119], off offset:3328
	global_load_dword v211, v[118:119], off offset:2816
	global_load_dword v220, v[118:119], off offset:2304
	global_load_dword v209, v[118:119], off offset:1792
	global_load_dword v218, v[118:119], off offset:1280
	global_load_dword v207, v[118:119], off offset:768
	global_load_dword v216, v[118:119], off offset:256
	v_cvt_pk_bf16_f32 v18, v140, v139
	v_cvt_pk_bf16_f32 v34, v34, v35
	v_cvt_pk_bf16_f32 v19, v142, v141
	v_cvt_pk_bf16_f32 v35, v36, v37
	v_cvt_pk_bf16_f32 v20, v144, v143
	v_cvt_pk_bf16_f32 v36, v38, v39
	v_cvt_pk_bf16_f32 v21, v146, v145
	v_cvt_pk_bf16_f32 v37, v40, v41
	s_nop 0
	v_mfma_f32_32x32x16_bf16 v[18:33], v[50:53], v[18:21], 0
	v_mfma_f32_32x32x16_bf16 v[18:33], v[102:105], v[34:37], v[18:33]
	s_waitcnt vmcnt(60) lgkmcnt(0)
	v_cvt_pk_bf16_f32 v34, v148, v147
	v_cvt_pk_bf16_f32 v35, v156, v149
	v_cvt_pk_bf16_f32 v36, v158, v155
	v_cvt_pk_bf16_f32 v37, v160, v157
	s_nop 1
	v_mfma_f32_32x32x16_bf16 v[18:33], v[106:109], v[34:37], v[18:33]
	s_waitcnt vmcnt(20) lgkmcnt(0)
	v_cvt_pk_bf16_f32 v34, v162, v159
	v_cvt_pk_bf16_f32 v35, v164, v161
	v_cvt_pk_bf16_f32 v36, v166, v163
	v_cvt_pk_bf16_f32 v37, v168, v165
	s_nop 1
	v_mfma_f32_32x32x16_bf16 v[18:33], v[110:113], v[34:37], v[18:33]
	s_waitcnt vmcnt(62) lgkmcnt(0)
	v_cvt_pk_bf16_f32 v34, v170, v167
	v_cvt_pk_bf16_f32 v54, v54, v55
	v_cvt_pk_bf16_f32 v35, v172, v169
	v_cvt_pk_bf16_f32 v55, v56, v57
	v_cvt_pk_bf16_f32 v36, v174, v171
	v_cvt_pk_bf16_f32 v56, v60, v61
	v_cvt_pk_bf16_f32 v37, v176, v173
	v_cvt_pk_bf16_f32 v57, v62, v63
	s_nop 0
	v_mfma_f32_32x32x16_bf16 v[34:49], v[50:53], v[34:37], 0
	v_mfma_f32_32x32x16_bf16 v[34:49], v[102:105], v[54:57], v[34:49]
	s_waitcnt vmcnt(28) lgkmcnt(0)
	v_cvt_pk_bf16_f32 v54, v178, v175
	v_cvt_pk_bf16_f32 v55, v180, v177
	v_cvt_pk_bf16_f32 v56, v182, v179
	v_cvt_pk_bf16_f32 v57, v196, v181
	s_nop 1
	v_mfma_f32_32x32x16_bf16 v[34:49], v[106:109], v[54:57], v[34:49]
	s_waitcnt vmcnt(36) lgkmcnt(0)
	v_cvt_pk_bf16_f32 v54, v198, v183
	v_cvt_pk_bf16_f32 v55, v200, v195
	v_cvt_pk_bf16_f32 v56, v202, v197
	v_cvt_pk_bf16_f32 v57, v204, v199
	s_nop 1
	v_mfma_f32_32x32x16_bf16 v[34:49], v[110:113], v[54:57], v[34:49]
	s_nop 0
	s_nop 0
	s_waitcnt vmcnt(44) lgkmcnt(0)
	v_cvt_pk_bf16_f32 v54, v206, v201
	v_cvt_pk_bf16_f32 v114, v116, v117
	v_cvt_pk_bf16_f32 v55, v208, v203
	v_cvt_pk_bf16_f32 v115, v122, v123
	v_cvt_pk_bf16_f32 v56, v210, v205
	v_cvt_pk_bf16_f32 v116, v124, v125
	v_cvt_pk_bf16_f32 v57, v212, v214
	v_cvt_pk_bf16_f32 v117, v126, v127
	s_nop 0
	v_mfma_f32_32x32x16_bf16 v[50:65], v[50:53], v[54:57], 0
	v_mfma_f32_32x32x16_bf16 v[50:65], v[102:105], v[114:117], v[50:65]
	s_waitcnt vmcnt(0) lgkmcnt(0)
; #define LAS __attribute__((address_space(3)))
; #define LDS_WAIT() asm volatile("s_waitcnt lgkmcnt(0)" ::: "memory")
; DI float bf2f(bf16 b) { return __uint_as_float(((unsigned)b) << 16); }
; DI void g3_tile_in(const bf16* g, LAS unsigned char* R, int lane) {
; #pragma unroll
;     for (int it = 0; it < 8; ++it) { const int row = 4 * it + (lane >> 4), ch = lane & 15;
;         *(LAS u32x4*)(R + row * G3_PITCH + ch * 16) = *(const u32x4*)(g + (size_t)row * 512 + ch * 8); }
;     LDS_WAIT();
; }
; DI void gla_stage3(const Ctx& c0, int layer, int unit, int cb, LAS unsigned char* lds) {
;     ...
;     g3_tile_in((const bf16*)(c.ws + O_OINTRA) + row0 * 512 + h * 128, R, lane);
; #pragma unroll
;     for (int vb = 0; vb < 4; ++vb) {
; #pragma unroll
;         for (int rg = 0; rg < 16; ++rg) o[vb][rg] += bf2f(*(const LAS bf16*)(Re + ((rg & 3) + 8 * (rg >> 2)) * G3_PITCH + 64 * vb));
;         asm volatile("" ::: "memory");
;     }
	v_cvt_pk_bf16_f32 v102, v216, v207
	v_cvt_pk_bf16_f32 v103, v218, v209
	v_cvt_pk_bf16_f32 v104, v220, v211
	v_cvt_pk_bf16_f32 v105, v222, v213
	s_nop 1
	v_mfma_f32_32x32x16_bf16 v[50:65], v[106:109], v[102:105], v[50:65]
	s_nop 0
	s_waitcnt vmcnt(8) lgkmcnt(0)
	v_cvt_pk_bf16_f32 v102, v224, v215
	v_cvt_pk_bf16_f32 v103, v226, v217
	v_cvt_pk_bf16_f32 v104, v228, v219
	v_cvt_pk_bf16_f32 v105, v230, v90
	v_lshl_add_u64 v[90:91], s[0:1], 0, v[88:89]
	v_lshl_add_u64 v[106:107], v[90:91], 0, s[20:21]
	v_mfma_f32_32x32x16_bf16 v[50:65], v[110:113], v[102:105], v[50:65]
	v_lshl_add_u64 v[102:103], v[106:107], 0, v[66:67]
	global_load_dwordx4 v[102:105], v[102:103], off
	s_waitcnt vmcnt(0) lgkmcnt(0)
	v_lshl_add_u64 v[168:169], v[90:91], 0, s[22:23]
	v_lshl_add_u64 v[140:141], v[168:169], 0, v[70:71]
	global_load_dwordx4 v[174:177], v[140:141], off
	v_lshl_add_u64 v[140:141], v[106:107], 0, v[70:71]
	global_load_dwordx4 v[146:149], v[140:141], off
	v_lshl_add_u64 v[144:145], v[106:107], 0, v[68:69]
	global_load_dwordx4 v[140:143], v[144:145], off
	ds_write_b128 v92, v[102:105]
	s_waitcnt vmcnt(0) lgkmcnt(0)
	v_lshl_add_u64 v[144:145], v[168:169], 0, v[76:77]
	global_load_dwordx4 v[200:203], v[144:145], off
	v_lshl_add_u64 v[144:145], v[168:169], 0, v[74:75]
	global_load_dwordx4 v[196:199], v[144:145], off
	v_lshl_add_u64 v[144:145], v[168:169], 0, v[72:73]
	global_load_dwordx4 v[178:181], v[144:145], off
	v_lshl_add_u64 v[144:145], v[106:107], 0, v[74:75]
	global_load_dwordx4 v[156:159], v[144:145], off
	v_lshl_add_u64 v[102:103], v[106:107], 0, v[72:73]
	global_load_dwordx4 v[102:105], v[102:103], off
	ds_write_b128 v92, v[140:143] offset:1088
	s_waitcnt vmcnt(5) lgkmcnt(0)
	v_lshl_add_u64 v[140:141], v[168:169], 0, v[78:79]
	global_load_dwordx4 v[204:207], v[140:141], off
	v_lshl_add_u64 v[140:141], v[106:107], 0, v[78:79]
	global_load_dwordx4 v[160:163], v[140:141], off
	v_lshl_add_u64 v[144:145], v[106:107], 0, v[76:77]
	global_load_dwordx4 v[140:143], v[144:145], off
	ds_write_b128 v92, v[146:149] offset:2176
	s_waitcnt vmcnt(3) lgkmcnt(0)
	v_lshl_add_u64 v[144:145], v[168:169], 0, v[66:67]
	global_load_dwordx4 v[164:167], v[144:145], off
	v_lshl_add_u64 v[148:149], v[106:107], 0, v[80:81]
	global_load_dwordx4 v[144:147], v[148:149], off
	ds_write_b128 v92, v[102:105] offset:3264
	s_waitcnt vmcnt(6) lgkmcnt(0)
	v_lshl_add_u64 v[148:149], v[168:169], 0, v[68:69]
	global_load_dwordx4 v[170:173], v[148:149], off
	ds_write_b128 v92, v[156:159] offset:4352
	s_waitcnt vmcnt(3) lgkmcnt(0)
	ds_write_b128 v92, v[140:143] offset:5440
	s_waitcnt vmcnt(4) lgkmcnt(0)
	ds_write_b128 v92, v[160:163] offset:6528
	s_waitcnt vmcnt(1) lgkmcnt(0)
	ds_write_b128 v92, v[144:147] offset:7616
	s_waitcnt lgkmcnt(0)
	ds_read_u16 v102, v1
	s_waitcnt lgkmcnt(0)
	v_lshlrev_b32_e32 v102, 16, v102
	v_add_f32_e32 v138, v2, v102
	ds_read_u16 v2, v1 offset:272
	s_waitcnt lgkmcnt(0)
	v_lshlrev_b32_e32 v2, 16, v2
	v_add_f32_e32 v137, v3, v2
	ds_read_u16 v2, v1 offset:544
	s_waitcnt lgkmcnt(0)
	v_lshlrev_b32_e32 v2, 16, v2
	v_add_f32_e32 v136, v4, v2
	ds_read_u16 v2, v1 offset:816
	s_waitcnt lgkmcnt(0)
	v_lshlrev_b32_e32 v2, 16, v2
	v_add_f32_e32 v135, v5, v2
	ds_read_u16 v2, v1 offset:2176
	s_waitcnt lgkmcnt(0)
	v_lshlrev_b32_e32 v2, 16, v2
	v_add_f32_e32 v134, v6, v2
	ds_read_u16 v2, v1 offset:2448
	s_waitcnt lgkmcnt(0)
	v_lshlrev_b32_e32 v2, 16, v2
	v_add_f32_e32 v133, v7, v2
	ds_read_u16 v2, v1 offset:2720
	s_waitcnt lgkmcnt(0)
	v_lshlrev_b32_e32 v2, 16, v2
	v_add_f32_e32 v132, v8, v2
	ds_read_u16 v2, v1 offset:2992
	s_waitcnt lgkmcnt(0)
	v_lshlrev_b32_e32 v2, 16, v2
	v_add_f32_e32 v131, v9, v2
	ds_read_u16 v2, v1 offset:4352
	s_waitcnt lgkmcnt(0)
	v_lshlrev_b32_e32 v2, 16, v2
	v_add_f32_e32 v130, v10, v2
	ds_read_u16 v2, v1 offset:4624
	s_waitcnt lgkmcnt(0)
	v_lshlrev_b32_e32 v2, 16, v2
	v_add_f32_e32 v129, v11, v2
	ds_read_u16 v2, v1 offset:4896
	s_waitcnt lgkmcnt(0)
	v_lshlrev_b32_e32 v2, 16, v2
	v_add_f32_e32 v128, v12, v2
	ds_read_u16 v2, v1 offset:5168
	s_waitcnt lgkmcnt(0)
	v_lshlrev_b32_e32 v2, 16, v2
	v_add_f32_e32 v127, v13, v2
	ds_read_u16 v2, v1 offset:6528
	s_waitcnt lgkmcnt(0)
	v_lshlrev_b32_e32 v2, 16, v2
	v_add_f32_e32 v126, v14, v2
	ds_read_u16 v2, v1 offset:6800
	s_waitcnt lgkmcnt(0)
	v_lshlrev_b32_e32 v2, 16, v2
	v_add_f32_e32 v125, v15, v2
	ds_read_u16 v2, v1 offset:7072
	s_waitcnt lgkmcnt(0)
	v_lshlrev_b32_e32 v2, 16, v2
	v_add_f32_e32 v124, v16, v2
	ds_read_u16 v2, v1 offset:7344
	s_waitcnt lgkmcnt(0)
	v_lshlrev_b32_e32 v2, 16, v2
	v_add_f32_e32 v123, v17, v2
	ds_read_u16 v2, v1 offset:64
	s_waitcnt lgkmcnt(0)
	v_lshlrev_b32_e32 v2, 16, v2
	v_add_f32_e32 v122, v18, v2
	ds_read_u16 v2, v1 offset:336
	s_waitcnt lgkmcnt(0)
	v_lshlrev_b32_e32 v2, 16, v2
	v_add_f32_e32 v121, v19, v2
	ds_read_u16 v2, v1 offset:608
	s_waitcnt lgkmcnt(0)
	v_lshlrev_b32_e32 v2, 16, v2
	v_add_f32_e32 v120, v20, v2
	ds_read_u16 v2, v1 offset:880
	s_waitcnt lgkmcnt(0)
	v_lshlrev_b32_e32 v2, 16, v2
	v_add_f32_e32 v119, v21, v2
	ds_read_u16 v2, v1 offset:2240
	s_waitcnt lgkmcnt(0)
	v_lshlrev_b32_e32 v2, 16, v2
	v_add_f32_e32 v118, v22, v2
	ds_read_u16 v2, v1 offset:2512
	s_waitcnt lgkmcnt(0)
	v_lshlrev_b32_e32 v2, 16, v2
	v_add_f32_e32 v117, v23, v2
	ds_read_u16 v2, v1 offset:2784
	s_waitcnt lgkmcnt(0)
	v_lshlrev_b32_e32 v2, 16, v2
	v_add_f32_e32 v116, v24, v2
	ds_read_u16 v2, v1 offset:3056
	s_waitcnt lgkmcnt(0)
	v_lshlrev_b32_e32 v2, 16, v2
	v_add_f32_e32 v115, v25, v2
	ds_read_u16 v2, v1 offset:4416
	s_waitcnt lgkmcnt(0)
	v_lshlrev_b32_e32 v2, 16, v2
	v_add_f32_e32 v114, v26, v2
	ds_read_u16 v2, v1 offset:4688
	s_waitcnt lgkmcnt(0)
; #define LAS __attribute__((address_space(3)))
; DI float bf2f(bf16 b) { return __uint_as_float(((unsigned)b) << 16); }
; DI void gla_stage3(const Ctx& c0, int layer, int unit, int cb, LAS unsigned char* lds) {
;     ...
;     for (int vb = 0; vb < 4; ++vb) {
; #pragma unroll
;         for (int rg = 0; rg < 16; ++rg) o[vb][rg] += bf2f(*(const LAS bf16*)(Re + ((rg & 3) + 8 * (rg >> 2)) * G3_PITCH + 64 * vb));
;         asm volatile("" ::: "memory");
;     }
	v_lshlrev_b32_e32 v2, 16, v2
	v_add_f32_e32 v113, v27, v2
	ds_read_u16 v2, v1 offset:4960
	s_waitcnt lgkmcnt(0)
	v_lshlrev_b32_e32 v2, 16, v2
	v_add_f32_e32 v112, v28, v2
	ds_read_u16 v2, v1 offset:5232
	s_waitcnt lgkmcnt(0)
	v_lshlrev_b32_e32 v2, 16, v2
	v_add_f32_e32 v111, v29, v2
	ds_read_u16 v2, v1 offset:6592
	s_waitcnt lgkmcnt(0)
	v_lshlrev_b32_e32 v2, 16, v2
	v_add_f32_e32 v110, v30, v2
	ds_read_u16 v2, v1 offset:6864
	s_waitcnt lgkmcnt(0)
	v_lshlrev_b32_e32 v2, 16, v2
	v_add_f32_e32 v109, v31, v2
	ds_read_u16 v2, v1 offset:7136
	s_waitcnt lgkmcnt(0)
	v_lshlrev_b32_e32 v2, 16, v2
	v_add_f32_e32 v108, v32, v2
	ds_read_u16 v2, v1 offset:7408
	s_waitcnt lgkmcnt(0)
	v_lshlrev_b32_e32 v2, 16, v2
	v_add_f32_e32 v107, v33, v2
	ds_read_u16 v2, v1 offset:128
	s_waitcnt lgkmcnt(0)
	v_lshlrev_b32_e32 v2, 16, v2
	v_add_f32_e32 v106, v34, v2
	ds_read_u16 v2, v1 offset:400
	s_waitcnt lgkmcnt(0)
	v_lshlrev_b32_e32 v2, 16, v2
	v_add_f32_e32 v105, v35, v2
	ds_read_u16 v2, v1 offset:672
	s_waitcnt lgkmcnt(0)
	v_lshlrev_b32_e32 v2, 16, v2
	v_add_f32_e32 v104, v36, v2
	ds_read_u16 v2, v1 offset:944
	s_waitcnt lgkmcnt(0)
	v_lshlrev_b32_e32 v2, 16, v2
	v_add_f32_e32 v103, v37, v2
	ds_read_u16 v2, v1 offset:2304
	s_waitcnt lgkmcnt(0)
	v_lshlrev_b32_e32 v2, 16, v2
	v_add_f32_e32 v102, v38, v2
	ds_read_u16 v2, v1 offset:2576
	s_waitcnt lgkmcnt(0)
	v_lshlrev_b32_e32 v2, 16, v2
	v_add_f32_e32 v39, v39, v2
	ds_read_u16 v2, v1 offset:2848
	s_waitcnt lgkmcnt(0)
	v_lshlrev_b32_e32 v2, 16, v2
	v_add_f32_e32 v38, v40, v2
	ds_read_u16 v2, v1 offset:3120
	s_waitcnt lgkmcnt(0)
	v_lshlrev_b32_e32 v2, 16, v2
	v_add_f32_e32 v37, v41, v2
	ds_read_u16 v2, v1 offset:4480
	s_waitcnt lgkmcnt(0)
	v_lshlrev_b32_e32 v2, 16, v2
	v_add_f32_e32 v36, v42, v2
	ds_read_u16 v2, v1 offset:4752
	s_waitcnt lgkmcnt(0)
	v_lshlrev_b32_e32 v2, 16, v2
	v_add_f32_e32 v34, v43, v2
	ds_read_u16 v2, v1 offset:5024
	s_waitcnt lgkmcnt(0)
	v_lshlrev_b32_e32 v2, 16, v2
	v_add_f32_e32 v33, v44, v2
	ds_read_u16 v2, v1 offset:5296
	s_waitcnt lgkmcnt(0)
	v_lshlrev_b32_e32 v2, 16, v2
	v_add_f32_e32 v32, v45, v2
	ds_read_u16 v2, v1 offset:6656
	s_waitcnt lgkmcnt(0)
	v_lshlrev_b32_e32 v2, 16, v2
	v_add_f32_e32 v30, v46, v2
	ds_read_u16 v2, v1 offset:6928
	s_waitcnt lgkmcnt(0)
	v_lshlrev_b32_e32 v2, 16, v2
	v_add_f32_e32 v29, v47, v2
	ds_read_u16 v2, v1 offset:7200
	s_waitcnt lgkmcnt(0)
	v_lshlrev_b32_e32 v2, 16, v2
	v_add_f32_e32 v28, v48, v2
	ds_read_u16 v2, v1 offset:7472
	s_waitcnt lgkmcnt(0)
	v_lshlrev_b32_e32 v2, 16, v2
	v_add_f32_e32 v26, v49, v2
	ds_read_u16 v2, v1 offset:192
	s_waitcnt lgkmcnt(0)
	v_lshlrev_b32_e32 v2, 16, v2
	v_add_f32_e32 v19, v50, v2
	ds_read_u16 v2, v1 offset:464
	s_waitcnt lgkmcnt(0)
	v_lshlrev_b32_e32 v2, 16, v2
	v_add_f32_e32 v18, v51, v2
	ds_read_u16 v2, v1 offset:736
	s_waitcnt lgkmcnt(0)
	v_lshlrev_b32_e32 v2, 16, v2
	v_add_f32_e32 v17, v52, v2
	ds_read_u16 v2, v1 offset:1008
	s_waitcnt lgkmcnt(0)
	v_lshlrev_b32_e32 v2, 16, v2
	v_add_f32_e32 v16, v53, v2
	ds_read_u16 v2, v1 offset:2368
	s_waitcnt lgkmcnt(0)
	v_lshlrev_b32_e32 v2, 16, v2
	v_add_f32_e32 v15, v54, v2
	ds_read_u16 v2, v1 offset:2640
	s_waitcnt lgkmcnt(0)
	v_lshlrev_b32_e32 v2, 16, v2
	v_add_f32_e32 v14, v55, v2
	ds_read_u16 v2, v1 offset:2912
	s_waitcnt lgkmcnt(0)
	v_lshlrev_b32_e32 v2, 16, v2
	v_add_f32_e32 v13, v56, v2
	ds_read_u16 v2, v1 offset:3184
	s_waitcnt lgkmcnt(0)
	v_lshlrev_b32_e32 v2, 16, v2
	v_add_f32_e32 v12, v57, v2
	ds_read_u16 v2, v1 offset:4544
	s_waitcnt lgkmcnt(0)
	v_lshlrev_b32_e32 v2, 16, v2
	v_add_f32_e32 v11, v58, v2
	ds_read_u16 v2, v1 offset:4816
	s_waitcnt lgkmcnt(0)
	v_lshlrev_b32_e32 v2, 16, v2
	v_add_f32_e32 v10, v59, v2
	ds_read_u16 v2, v1 offset:5088
	s_waitcnt lgkmcnt(0)
	v_lshlrev_b32_e32 v2, 16, v2
	v_add_f32_e32 v9, v60, v2
	ds_read_u16 v2, v1 offset:5360
	s_waitcnt lgkmcnt(0)
	v_lshlrev_b32_e32 v2, 16, v2
	v_add_f32_e32 v8, v61, v2
	ds_read_u16 v2, v1 offset:6720
	s_waitcnt lgkmcnt(0)
	v_lshlrev_b32_e32 v2, 16, v2
	v_add_f32_e32 v7, v62, v2
	ds_read_u16 v2, v1 offset:6992
	s_waitcnt lgkmcnt(0)
	v_lshlrev_b32_e32 v2, 16, v2
	v_add_f32_e32 v6, v63, v2
	ds_read_u16 v2, v1 offset:7264
	s_waitcnt lgkmcnt(0)
	v_lshlrev_b32_e32 v2, 16, v2
	v_add_f32_e32 v5, v64, v2
	ds_read_u16 v2, v1 offset:7536
	s_waitcnt lgkmcnt(0)
	s_waitcnt lgkmcnt(0)
; DI void gla_stage3(const Ctx& c0, int layer, int unit, int cb, LAS unsigned char* lds) {
;     ...
;     float rs[16];
; #pragma unroll
;     for (int rg = 0; rg < 16; ++rg) { float ss = o[0][rg] * o[0][rg] + o[1][rg] * o[1][rg] + o[2][rg] * o[2][rg] + o[3][rg] * o[3][rg];
;         ss += __shfl_xor(ss, 1); ss += __shfl_xor(ss, 2); ss += __shfl_xor(ss, 4); ss += __shfl_xor(ss, 8); ss += __shfl_xor(ss, 16);
;         rs[rg] = 1.f / sqrtf(ss * (1.f / 128.f) + EPS); }
	v_lshlrev_b32_e32 v2, 16, v2
	v_add_f32_e32 v4, v65, v2
	v_cndmask_b32_e32 v2, v93, v94, vcc
	v_cmp_lt_i32_e32 vcc, v96, v95
	v_lshlrev_b32_e32 v2, 2, v2
	s_nop 0
	v_cndmask_b32_e32 v3, v93, v96, vcc
	v_cmp_lt_i32_e32 vcc, v97, v95
	v_lshlrev_b32_e32 v3, 2, v3
	s_nop 0
	v_cndmask_b32_e32 v20, v93, v97, vcc
	v_cmp_lt_i32_e32 vcc, v98, v95
	v_lshlrev_b32_e32 v20, 2, v20
	s_nop 0
	v_cndmask_b32_e32 v21, v93, v98, vcc
	v_cmp_lt_i32_e32 vcc, v99, v95
	v_lshlrev_b32_e32 v47, 2, v21
	s_nop 0
	v_cndmask_b32_e32 v21, v93, v99, vcc
	v_lshlrev_b32_e32 v48, 2, v21
	v_mul_f32_e32 v21, v122, v122
	v_fmac_f32_e32 v21, v138, v138
	v_fmac_f32_e32 v21, v106, v106
	v_fmac_f32_e32 v21, v19, v19
	s_nop 1
	v_add_f32_dpp v21, v21, v21 quad_perm:[1,0,3,2] row_mask:0xf bank_mask:0xf
	s_nop 1
	v_add_f32_dpp v21, v21, v21 quad_perm:[2,3,0,1] row_mask:0xf bank_mask:0xf
	s_nop 1
	v_add_f32_dpp v21, v21, v21 row_half_mirror row_mask:0xf bank_mask:0xf
	s_nop 1
	v_add_f32_dpp v21, v21, v21 row_mirror row_mask:0xf bank_mask:0xf
	v_mov_b32_e32 v22, v21
	v_mov_b32_e32 v23, v21
	s_nop 1
	v_permlane16_swap_b32_e32 v22, v23
	v_add_f32_e32 v21, v22, v23
	v_fmamk_f32 v21, v21, 0x3c000000, v100
	v_cmp_gt_f32_e32 vcc, s33, v21
	v_mul_f32_e32 v22, 0x4f800000, v21
	s_nop 0
	v_cndmask_b32_e32 v21, v21, v22, vcc
	v_sqrt_f32_e32 v22, v21
	s_nop 0
	v_add_u32_e32 v23, -1, v22
	v_fma_f32 v24, -v23, v22, v21
	v_cmp_ge_f32_e64 s[8:9], 0, v24
	v_add_u32_e32 v24, 1, v22
	s_nop 0
	v_cndmask_b32_e64 v23, v22, v23, s[8:9]
	v_fma_f32 v22, -v24, v22, v21
	v_cmp_lt_f32_e64 s[8:9], 0, v22
	s_nop 1
	v_cndmask_b32_e64 v22, v23, v24, s[8:9]
	v_mul_f32_e32 v23, 0x37800000, v22
	v_cndmask_b32_e32 v22, v22, v23, vcc
	v_cmp_class_f32_e32 vcc, v21, v101
	s_nop 1
	v_cndmask_b32_e32 v21, v22, v21, vcc
	s_nop 0
	v_div_scale_f32 v24, vcc, 1.0, v21, 1.0
	v_rcp_f32_e32 v46, v21
	v_mul_f32_e32 v21, v121, v121
	v_fmac_f32_e32 v21, v137, v137
	v_fmac_f32_e32 v21, v105, v105
	v_fmac_f32_e32 v21, v18, v18
	s_nop 1
	v_add_f32_dpp v21, v21, v21 quad_perm:[1,0,3,2] row_mask:0xf bank_mask:0xf
	v_mul_f32_e32 v19, v19, v46
	s_nop 1
	v_add_f32_dpp v21, v21, v21 quad_perm:[2,3,0,1] row_mask:0xf bank_mask:0xf
	s_nop 1
	v_add_f32_dpp v21, v21, v21 row_half_mirror row_mask:0xf bank_mask:0xf
	s_nop 1
	v_add_f32_dpp v21, v21, v21 row_mirror row_mask:0xf bank_mask:0xf
	v_mov_b32_e32 v22, v21
	v_mov_b32_e32 v23, v21
	s_nop 1
	v_permlane16_swap_b32_e32 v22, v23
	v_add_f32_e32 v21, v22, v23
	v_fmamk_f32 v21, v21, 0x3c000000, v100
	v_cmp_gt_f32_e32 vcc, s33, v21
	v_mul_f32_e32 v22, 0x4f800000, v21
	s_nop 0
	v_cndmask_b32_e32 v21, v21, v22, vcc
	v_sqrt_f32_e32 v22, v21
	s_nop 0
	v_add_u32_e32 v23, -1, v22
	v_fma_f32 v24, -v23, v22, v21
	v_cmp_ge_f32_e64 s[8:9], 0, v24
	v_add_u32_e32 v24, 1, v22
	s_nop 0
	v_cndmask_b32_e64 v23, v22, v23, s[8:9]
	v_fma_f32 v22, -v24, v22, v21
	v_cmp_lt_f32_e64 s[8:9], 0, v22
	s_nop 1
	v_cndmask_b32_e64 v22, v23, v24, s[8:9]
	v_mul_f32_e32 v23, 0x37800000, v22
	v_cndmask_b32_e32 v22, v22, v23, vcc
	v_cmp_class_f32_e32 vcc, v21, v101
	s_nop 1
	v_cndmask_b32_e32 v21, v22, v21, vcc
	s_nop 0
	v_div_scale_f32 v24, vcc, 1.0, v21, 1.0
	v_rcp_f32_e32 v45, v21
	v_mul_f32_e32 v21, v120, v120
	v_fmac_f32_e32 v21, v136, v136
	v_fmac_f32_e32 v21, v104, v104
	v_fmac_f32_e32 v21, v17, v17
	s_nop 1
	v_add_f32_dpp v21, v21, v21 quad_perm:[1,0,3,2] row_mask:0xf bank_mask:0xf
	v_mul_f32_e32 v18, v18, v45
	s_nop 1
	v_add_f32_dpp v21, v21, v21 quad_perm:[2,3,0,1] row_mask:0xf bank_mask:0xf
	s_nop 1
	v_add_f32_dpp v21, v21, v21 row_half_mirror row_mask:0xf bank_mask:0xf
	s_nop 1
	v_add_f32_dpp v21, v21, v21 row_mirror row_mask:0xf bank_mask:0xf
	v_mov_b32_e32 v22, v21
	v_mov_b32_e32 v23, v21
	s_nop 1
	v_permlane16_swap_b32_e32 v22, v23
	v_add_f32_e32 v21, v22, v23
	v_fmamk_f32 v21, v21, 0x3c000000, v100
	v_cmp_gt_f32_e32 vcc, s33, v21
	v_mul_f32_e32 v22, 0x4f800000, v21
	s_nop 0
	v_cndmask_b32_e32 v21, v21, v22, vcc
	v_sqrt_f32_e32 v22, v21
	s_nop 0
	v_add_u32_e32 v23, -1, v22
	v_fma_f32 v24, -v23, v22, v21
	v_cmp_ge_f32_e64 s[8:9], 0, v24
	v_add_u32_e32 v24, 1, v22
	s_nop 0
	v_cndmask_b32_e64 v23, v22, v23, s[8:9]
	v_fma_f32 v22, -v24, v22, v21
	v_cmp_lt_f32_e64 s[8:9], 0, v22
	s_nop 1
	v_cndmask_b32_e64 v22, v23, v24, s[8:9]
	v_mul_f32_e32 v23, 0x37800000, v22
	v_cndmask_b32_e32 v22, v22, v23, vcc
	v_cmp_class_f32_e32 vcc, v21, v101
	s_nop 1
	v_cndmask_b32_e32 v21, v22, v21, vcc
	s_nop 0
	v_div_scale_f32 v24, vcc, 1.0, v21, 1.0
	v_rcp_f32_e32 v44, v21
	v_mul_f32_e32 v21, v119, v119
	v_fmac_f32_e32 v21, v135, v135
	v_fmac_f32_e32 v21, v103, v103
	v_fmac_f32_e32 v21, v16, v16
	s_nop 1
	v_add_f32_dpp v21, v21, v21 quad_perm:[1,0,3,2] row_mask:0xf bank_mask:0xf
	v_mul_f32_e32 v17, v17, v44
	s_nop 1
	v_add_f32_dpp v21, v21, v21 quad_perm:[2,3,0,1] row_mask:0xf bank_mask:0xf
	s_nop 1
	v_add_f32_dpp v21, v21, v21 row_half_mirror row_mask:0xf bank_mask:0xf
	s_nop 1
	v_add_f32_dpp v21, v21, v21 row_mirror row_mask:0xf bank_mask:0xf
	v_mov_b32_e32 v22, v21
	v_mov_b32_e32 v23, v21
	s_nop 1
	v_permlane16_swap_b32_e32 v22, v23
	v_add_f32_e32 v21, v22, v23
	v_fmamk_f32 v21, v21, 0x3c000000, v100
	v_cmp_gt_f32_e32 vcc, s33, v21
	v_mul_f32_e32 v22, 0x4f800000, v21
	s_nop 0
	v_cndmask_b32_e32 v21, v21, v22, vcc
	v_sqrt_f32_e32 v22, v21
	s_nop 0
	v_add_u32_e32 v23, -1, v22
	v_fma_f32 v24, -v23, v22, v21
	v_cmp_ge_f32_e64 s[8:9], 0, v24
	v_add_u32_e32 v24, 1, v22
	s_nop 0
	v_cndmask_b32_e64 v23, v22, v23, s[8:9]
	v_fma_f32 v22, -v24, v22, v21
	v_cmp_lt_f32_e64 s[8:9], 0, v22
	s_nop 1
	v_cndmask_b32_e64 v22, v23, v24, s[8:9]
	v_mul_f32_e32 v23, 0x37800000, v22
	v_cndmask_b32_e32 v22, v22, v23, vcc
	v_cmp_class_f32_e32 vcc, v21, v101
	s_nop 1
; DI void gla_stage3(const Ctx& c0, int layer, int unit, int cb, LAS unsigned char* lds) {
;     ...
;     for (int rg = 0; rg < 16; ++rg) { float ss = o[0][rg] * o[0][rg] + o[1][rg] * o[1][rg] + o[2][rg] * o[2][rg] + o[3][rg] * o[3][rg];
;         ss += __shfl_xor(ss, 1); ss += __shfl_xor(ss, 2); ss += __shfl_xor(ss, 4); ss += __shfl_xor(ss, 8); ss += __shfl_xor(ss, 16);
;         rs[rg] = 1.f / sqrtf(ss * (1.f / 128.f) + EPS); }
	v_cndmask_b32_e32 v21, v22, v21, vcc
	s_nop 0
	v_div_scale_f32 v24, vcc, 1.0, v21, 1.0
	v_rcp_f32_e32 v43, v21
	v_mul_f32_e32 v21, v118, v118
	v_fmac_f32_e32 v21, v134, v134
	v_fmac_f32_e32 v21, v102, v102
	v_fmac_f32_e32 v21, v15, v15
	s_nop 1
	v_add_f32_dpp v21, v21, v21 quad_perm:[1,0,3,2] row_mask:0xf bank_mask:0xf
	v_mul_f32_e32 v16, v16, v43
	s_nop 1
	v_add_f32_dpp v21, v21, v21 quad_perm:[2,3,0,1] row_mask:0xf bank_mask:0xf
	s_nop 1
	v_add_f32_dpp v21, v21, v21 row_half_mirror row_mask:0xf bank_mask:0xf
	s_nop 1
	v_add_f32_dpp v21, v21, v21 row_mirror row_mask:0xf bank_mask:0xf
	v_mov_b32_e32 v22, v21
	v_mov_b32_e32 v23, v21
	s_nop 1
	v_permlane16_swap_b32_e32 v22, v23
	v_add_f32_e32 v21, v22, v23
	v_fmamk_f32 v21, v21, 0x3c000000, v100
	v_cmp_gt_f32_e32 vcc, s33, v21
	v_mul_f32_e32 v22, 0x4f800000, v21
	s_nop 0
	v_cndmask_b32_e32 v21, v21, v22, vcc
	v_sqrt_f32_e32 v22, v21
	s_nop 0
	v_add_u32_e32 v23, -1, v22
	v_fma_f32 v24, -v23, v22, v21
	v_cmp_ge_f32_e64 s[8:9], 0, v24
	v_add_u32_e32 v24, 1, v22
	s_nop 0
	v_cndmask_b32_e64 v23, v22, v23, s[8:9]
	v_fma_f32 v22, -v24, v22, v21
	v_cmp_lt_f32_e64 s[8:9], 0, v22
	s_nop 1
	v_cndmask_b32_e64 v22, v23, v24, s[8:9]
	v_mul_f32_e32 v23, 0x37800000, v22
	v_cndmask_b32_e32 v22, v22, v23, vcc
	v_cmp_class_f32_e32 vcc, v21, v101
	s_nop 1
	v_cndmask_b32_e32 v21, v22, v21, vcc
	s_nop 0
	v_div_scale_f32 v24, vcc, 1.0, v21, 1.0
	v_rcp_f32_e32 v42, v21
	v_mul_f32_e32 v21, v117, v117
	v_fmac_f32_e32 v21, v133, v133
	v_fmac_f32_e32 v21, v39, v39
	v_fmac_f32_e32 v21, v14, v14
	s_nop 1
	v_add_f32_dpp v21, v21, v21 quad_perm:[1,0,3,2] row_mask:0xf bank_mask:0xf
	v_mul_f32_e32 v15, v15, v42
	s_nop 1
	v_add_f32_dpp v21, v21, v21 quad_perm:[2,3,0,1] row_mask:0xf bank_mask:0xf
	s_nop 1
	v_add_f32_dpp v21, v21, v21 row_half_mirror row_mask:0xf bank_mask:0xf
	s_nop 1
	v_add_f32_dpp v21, v21, v21 row_mirror row_mask:0xf bank_mask:0xf
	v_mov_b32_e32 v22, v21
	v_mov_b32_e32 v23, v21
	s_nop 1
	v_permlane16_swap_b32_e32 v22, v23
	v_add_f32_e32 v21, v22, v23
	v_fmamk_f32 v21, v21, 0x3c000000, v100
	v_cmp_gt_f32_e32 vcc, s33, v21
	v_mul_f32_e32 v22, 0x4f800000, v21
	s_nop 0
	v_cndmask_b32_e32 v21, v21, v22, vcc
	v_sqrt_f32_e32 v22, v21
	s_nop 0
	v_add_u32_e32 v23, -1, v22
	v_fma_f32 v24, -v23, v22, v21
	v_cmp_ge_f32_e64 s[8:9], 0, v24
	v_add_u32_e32 v24, 1, v22
	s_nop 0
	v_cndmask_b32_e64 v23, v22, v23, s[8:9]
	v_fma_f32 v22, -v24, v22, v21
	v_cmp_lt_f32_e64 s[8:9], 0, v22
	s_nop 1
	v_cndmask_b32_e64 v22, v23, v24, s[8:9]
	v_mul_f32_e32 v23, 0x37800000, v22
	v_cndmask_b32_e32 v22, v22, v23, vcc
	v_cmp_class_f32_e32 vcc, v21, v101
	s_nop 1
	v_cndmask_b32_e32 v21, v22, v21, vcc
	s_nop 0
	v_div_scale_f32 v24, vcc, 1.0, v21, 1.0
	v_rcp_f32_e32 v41, v21
	v_mul_f32_e32 v21, v116, v116
	v_fmac_f32_e32 v21, v132, v132
	v_fmac_f32_e32 v21, v38, v38
	v_fmac_f32_e32 v21, v13, v13
	s_nop 1
	v_add_f32_dpp v21, v21, v21 quad_perm:[1,0,3,2] row_mask:0xf bank_mask:0xf
	v_mul_f32_e32 v39, v39, v41
	v_mul_f32_e32 v14, v14, v41
	s_nop 1
	v_add_f32_dpp v21, v21, v21 quad_perm:[2,3,0,1] row_mask:0xf bank_mask:0xf
	s_nop 1
	v_add_f32_dpp v21, v21, v21 row_half_mirror row_mask:0xf bank_mask:0xf
	s_nop 1
	v_add_f32_dpp v21, v21, v21 row_mirror row_mask:0xf bank_mask:0xf
	v_mov_b32_e32 v22, v21
	v_mov_b32_e32 v23, v21
	s_nop 1
	v_permlane16_swap_b32_e32 v22, v23
	v_add_f32_e32 v21, v22, v23
	v_fmamk_f32 v21, v21, 0x3c000000, v100
	v_cmp_gt_f32_e32 vcc, s33, v21
	v_mul_f32_e32 v22, 0x4f800000, v21
	s_nop 0
	v_cndmask_b32_e32 v21, v21, v22, vcc
	v_sqrt_f32_e32 v22, v21
	s_nop 0
	v_add_u32_e32 v23, -1, v22
	v_fma_f32 v24, -v23, v22, v21
	v_cmp_ge_f32_e64 s[8:9], 0, v24
	v_add_u32_e32 v24, 1, v22
	s_nop 0
	v_cndmask_b32_e64 v23, v22, v23, s[8:9]
	v_fma_f32 v22, -v24, v22, v21
	v_cmp_lt_f32_e64 s[8:9], 0, v22
	s_nop 1
	v_cndmask_b32_e64 v22, v23, v24, s[8:9]
	v_mul_f32_e32 v23, 0x37800000, v22
	v_cndmask_b32_e32 v22, v22, v23, vcc
	v_cmp_class_f32_e32 vcc, v21, v101
	s_nop 1
	v_cndmask_b32_e32 v21, v22, v21, vcc
	s_nop 0
	v_div_scale_f32 v24, vcc, 1.0, v21, 1.0
	v_rcp_f32_e32 v40, v21
	v_mul_f32_e32 v21, v115, v115
	v_fmac_f32_e32 v21, v131, v131
	v_fmac_f32_e32 v21, v37, v37
	v_fmac_f32_e32 v21, v12, v12
	s_nop 1
	v_add_f32_dpp v21, v21, v21 quad_perm:[1,0,3,2] row_mask:0xf bank_mask:0xf
	v_mul_f32_e32 v38, v38, v40
	v_mul_f32_e32 v13, v13, v40
	s_nop 1
	v_add_f32_dpp v21, v21, v21 quad_perm:[2,3,0,1] row_mask:0xf bank_mask:0xf
	s_nop 1
	v_add_f32_dpp v21, v21, v21 row_half_mirror row_mask:0xf bank_mask:0xf
	s_nop 1
	v_add_f32_dpp v21, v21, v21 row_mirror row_mask:0xf bank_mask:0xf
	v_mov_b32_e32 v22, v21
	v_mov_b32_e32 v23, v21
	s_nop 1
	v_permlane16_swap_b32_e32 v22, v23
	v_add_f32_e32 v21, v22, v23
	v_fmamk_f32 v21, v21, 0x3c000000, v100
	v_cmp_gt_f32_e32 vcc, s33, v21
	v_mul_f32_e32 v22, 0x4f800000, v21
	s_nop 0
	v_cndmask_b32_e32 v21, v21, v22, vcc
	v_sqrt_f32_e32 v22, v21
	s_nop 0
	v_add_u32_e32 v23, -1, v22
	v_fma_f32 v24, -v23, v22, v21
	v_cmp_ge_f32_e64 s[8:9], 0, v24
	v_add_u32_e32 v24, 1, v22
	s_nop 0
	v_cndmask_b32_e64 v23, v22, v23, s[8:9]
	v_fma_f32 v22, -v24, v22, v21
	v_cmp_lt_f32_e64 s[8:9], 0, v22
	s_nop 1
	v_cndmask_b32_e64 v22, v23, v24, s[8:9]
	v_mul_f32_e32 v23, 0x37800000, v22
	v_cndmask_b32_e32 v22, v22, v23, vcc
	v_cmp_class_f32_e32 vcc, v21, v101
	s_nop 1
	v_cndmask_b32_e32 v21, v22, v21, vcc
	s_nop 0
	v_div_scale_f32 v24, vcc, 1.0, v21, 1.0
	v_rcp_f32_e32 v35, v21
	v_mul_f32_e32 v21, v114, v114
	v_fmac_f32_e32 v21, v130, v130
	v_fmac_f32_e32 v21, v36, v36
	v_fmac_f32_e32 v21, v11, v11
	s_nop 1
	v_add_f32_dpp v21, v21, v21 quad_perm:[1,0,3,2] row_mask:0xf bank_mask:0xf
	v_mul_f32_e32 v37, v37, v35
	v_mul_f32_e32 v12, v12, v35
; DI void gla_stage3(const Ctx& c0, int layer, int unit, int cb, LAS unsigned char* lds) {
;     ...
;     for (int rg = 0; rg < 16; ++rg) { float ss = o[0][rg] * o[0][rg] + o[1][rg] * o[1][rg] + o[2][rg] * o[2][rg] + o[3][rg] * o[3][rg];
;         ss += __shfl_xor(ss, 1); ss += __shfl_xor(ss, 2); ss += __shfl_xor(ss, 4); ss += __shfl_xor(ss, 8); ss += __shfl_xor(ss, 16);
;         rs[rg] = 1.f / sqrtf(ss * (1.f / 128.f) + EPS); }
	s_nop 1
	v_add_f32_dpp v21, v21, v21 quad_perm:[2,3,0,1] row_mask:0xf bank_mask:0xf
	s_nop 1
	v_add_f32_dpp v21, v21, v21 row_half_mirror row_mask:0xf bank_mask:0xf
	s_nop 1
	v_add_f32_dpp v21, v21, v21 row_mirror row_mask:0xf bank_mask:0xf
	v_mov_b32_e32 v22, v21
	v_mov_b32_e32 v23, v21
	s_nop 1
	v_permlane16_swap_b32_e32 v22, v23
	v_add_f32_e32 v21, v22, v23
	v_fmamk_f32 v21, v21, 0x3c000000, v100
	v_cmp_gt_f32_e32 vcc, s33, v21
	v_mul_f32_e32 v22, 0x4f800000, v21
	s_nop 0
	v_cndmask_b32_e32 v21, v21, v22, vcc
	v_sqrt_f32_e32 v22, v21
	s_nop 0
	v_add_u32_e32 v23, -1, v22
	v_fma_f32 v24, -v23, v22, v21
	v_cmp_ge_f32_e64 s[8:9], 0, v24
	v_add_u32_e32 v24, 1, v22
	s_nop 0
	v_cndmask_b32_e64 v23, v22, v23, s[8:9]
	v_fma_f32 v22, -v24, v22, v21
	v_cmp_lt_f32_e64 s[8:9], 0, v22
	s_nop 1
	v_cndmask_b32_e64 v22, v23, v24, s[8:9]
	v_mul_f32_e32 v23, 0x37800000, v22
	v_cndmask_b32_e32 v22, v22, v23, vcc
	v_cmp_class_f32_e32 vcc, v21, v101
	s_nop 1
	v_cndmask_b32_e32 v21, v22, v21, vcc
	s_nop 0
	v_div_scale_f32 v24, vcc, 1.0, v21, 1.0
	v_rcp_f32_e32 v31, v21
	v_mul_f32_e32 v21, v113, v113
	v_fmac_f32_e32 v21, v129, v129
	v_fmac_f32_e32 v21, v34, v34
	v_fmac_f32_e32 v21, v10, v10
	s_nop 1
	v_add_f32_dpp v21, v21, v21 quad_perm:[1,0,3,2] row_mask:0xf bank_mask:0xf
	v_mul_f32_e32 v36, v36, v31
	v_mul_f32_e32 v11, v11, v31
	s_nop 1
	v_add_f32_dpp v21, v21, v21 quad_perm:[2,3,0,1] row_mask:0xf bank_mask:0xf
	s_nop 1
	v_add_f32_dpp v21, v21, v21 row_half_mirror row_mask:0xf bank_mask:0xf
	s_nop 1
	v_add_f32_dpp v21, v21, v21 row_mirror row_mask:0xf bank_mask:0xf
	v_mov_b32_e32 v22, v21
	v_mov_b32_e32 v23, v21
	s_nop 1
	v_permlane16_swap_b32_e32 v22, v23
	v_add_f32_e32 v21, v22, v23
	v_fmamk_f32 v21, v21, 0x3c000000, v100
	v_cmp_gt_f32_e32 vcc, s33, v21
	v_mul_f32_e32 v22, 0x4f800000, v21
	s_nop 0
	v_cndmask_b32_e32 v21, v21, v22, vcc
	v_sqrt_f32_e32 v22, v21
	s_nop 0
	v_add_u32_e32 v23, -1, v22
	v_fma_f32 v24, -v23, v22, v21
	v_cmp_ge_f32_e64 s[8:9], 0, v24
	v_add_u32_e32 v24, 1, v22
	s_nop 0
	v_cndmask_b32_e64 v23, v22, v23, s[8:9]
	v_fma_f32 v22, -v24, v22, v21
	v_cmp_lt_f32_e64 s[8:9], 0, v22
	s_nop 1
	v_cndmask_b32_e64 v22, v23, v24, s[8:9]
	v_mul_f32_e32 v23, 0x37800000, v22
	v_cndmask_b32_e32 v22, v22, v23, vcc
	v_cmp_class_f32_e32 vcc, v21, v101
	s_nop 1
	v_cndmask_b32_e32 v21, v22, v21, vcc
	s_nop 0
	v_div_scale_f32 v24, vcc, 1.0, v21, 1.0
	v_rcp_f32_e32 v27, v21
	v_mul_f32_e32 v21, v112, v112
	v_fmac_f32_e32 v21, v128, v128
	v_fmac_f32_e32 v21, v33, v33
	v_fmac_f32_e32 v21, v9, v9
	s_nop 1
	v_add_f32_dpp v21, v21, v21 quad_perm:[1,0,3,2] row_mask:0xf bank_mask:0xf
	v_mul_f32_e32 v34, v34, v27
	v_mul_f32_e32 v10, v10, v27
	s_nop 1
	v_add_f32_dpp v21, v21, v21 quad_perm:[2,3,0,1] row_mask:0xf bank_mask:0xf
	s_nop 1
	v_add_f32_dpp v21, v21, v21 row_half_mirror row_mask:0xf bank_mask:0xf
	s_nop 1
	v_add_f32_dpp v21, v21, v21 row_mirror row_mask:0xf bank_mask:0xf
	v_mov_b32_e32 v22, v21
	v_mov_b32_e32 v23, v21
	s_nop 1
	v_permlane16_swap_b32_e32 v22, v23
	v_add_f32_e32 v21, v22, v23
	v_fmamk_f32 v21, v21, 0x3c000000, v100
	v_cmp_gt_f32_e32 vcc, s33, v21
	v_mul_f32_e32 v22, 0x4f800000, v21
	s_nop 0
	v_cndmask_b32_e32 v21, v21, v22, vcc
	v_sqrt_f32_e32 v22, v21
	s_nop 0
	v_add_u32_e32 v23, -1, v22
	v_fma_f32 v24, -v23, v22, v21
	v_cmp_ge_f32_e64 s[8:9], 0, v24
	v_add_u32_e32 v24, 1, v22
	s_nop 0
	v_cndmask_b32_e64 v23, v22, v23, s[8:9]
	v_fma_f32 v22, -v24, v22, v21
	v_cmp_lt_f32_e64 s[8:9], 0, v22
	s_nop 1
	v_cndmask_b32_e64 v22, v23, v24, s[8:9]
	v_mul_f32_e32 v23, 0x37800000, v22
	v_cndmask_b32_e32 v22, v22, v23, vcc
	v_cmp_class_f32_e32 vcc, v21, v101
	s_nop 1
	v_cndmask_b32_e32 v21, v22, v21, vcc
	s_nop 0
	v_div_scale_f32 v24, vcc, 1.0, v21, 1.0
	v_rcp_f32_e32 v25, v21
	v_mul_f32_e32 v21, v111, v111
	v_fmac_f32_e32 v21, v127, v127
	v_fmac_f32_e32 v21, v32, v32
	v_fmac_f32_e32 v21, v8, v8
	s_nop 1
	v_add_f32_dpp v21, v21, v21 quad_perm:[1,0,3,2] row_mask:0xf bank_mask:0xf
	v_mul_f32_e32 v33, v33, v25
	v_mul_f32_e32 v9, v9, v25
	s_nop 1
	v_add_f32_dpp v21, v21, v21 quad_perm:[2,3,0,1] row_mask:0xf bank_mask:0xf
	s_nop 1
	v_add_f32_dpp v21, v21, v21 row_half_mirror row_mask:0xf bank_mask:0xf
	s_nop 1
	v_add_f32_dpp v21, v21, v21 row_mirror row_mask:0xf bank_mask:0xf
	v_mov_b32_e32 v22, v21
	v_mov_b32_e32 v23, v21
	s_nop 1
	v_permlane16_swap_b32_e32 v22, v23
	v_add_f32_e32 v21, v22, v23
	v_fmamk_f32 v21, v21, 0x3c000000, v100
	v_cmp_gt_f32_e32 vcc, s33, v21
	v_mul_f32_e32 v22, 0x4f800000, v21
	s_nop 0
	v_cndmask_b32_e32 v21, v21, v22, vcc
	v_sqrt_f32_e32 v22, v21
	s_nop 0
	v_add_u32_e32 v23, -1, v22
	v_fma_f32 v24, -v23, v22, v21
	v_cmp_ge_f32_e64 s[8:9], 0, v24
	v_add_u32_e32 v24, 1, v22
	s_nop 0
	v_cndmask_b32_e64 v23, v22, v23, s[8:9]
	v_fma_f32 v22, -v24, v22, v21
	v_cmp_lt_f32_e64 s[8:9], 0, v22
	s_nop 1
	v_cndmask_b32_e64 v22, v23, v24, s[8:9]
	v_mul_f32_e32 v23, 0x37800000, v22
	v_cndmask_b32_e32 v22, v22, v23, vcc
	v_cmp_class_f32_e32 vcc, v21, v101
	s_nop 1
	v_cndmask_b32_e32 v21, v22, v21, vcc
	s_nop 0
	v_div_scale_f32 v24, vcc, 1.0, v21, 1.0
	v_rcp_f32_e32 v24, v21
	v_mul_f32_e32 v21, v110, v110
	v_fmac_f32_e32 v21, v126, v126
	v_fmac_f32_e32 v21, v30, v30
	v_fmac_f32_e32 v21, v7, v7
	s_nop 1
	v_add_f32_dpp v21, v21, v21 quad_perm:[1,0,3,2] row_mask:0xf bank_mask:0xf
	v_mul_f32_e32 v32, v32, v24
	v_mul_f32_e32 v8, v8, v24
	s_nop 1
	v_add_f32_dpp v21, v21, v21 quad_perm:[2,3,0,1] row_mask:0xf bank_mask:0xf
	s_nop 1
	v_add_f32_dpp v21, v21, v21 row_half_mirror row_mask:0xf bank_mask:0xf
	s_nop 1
	v_add_f32_dpp v21, v21, v21 row_mirror row_mask:0xf bank_mask:0xf
	v_mov_b32_e32 v22, v21
	v_mov_b32_e32 v23, v21
	s_nop 1
	v_permlane16_swap_b32_e32 v22, v23
; #define LAS __attribute__((address_space(3)))
; #define LDS_WAIT() asm volatile("s_waitcnt lgkmcnt(0)" ::: "memory")
; DI float bf2f(bf16 b) { return __uint_as_float(((unsigned)b) << 16); }
; DI void g3_tile_in(const bf16* g, LAS unsigned char* R, int lane) {
; #pragma unroll
;     for (int it = 0; it < 8; ++it) { const int row = 4 * it + (lane >> 4), ch = lane & 15;
;         *(LAS u32x4*)(R + row * G3_PITCH + ch * 16) = *(const u32x4*)(g + (size_t)row * 512 + ch * 8); }
;     LDS_WAIT();
; }
; DI void gla_stage3(const Ctx& c0, int layer, int unit, int cb, LAS unsigned char* lds) {
;     ...
;     for (int rg = 0; rg < 16; ++rg) { float ss = o[0][rg] * o[0][rg] + o[1][rg] * o[1][rg] + o[2][rg] * o[2][rg] + o[3][rg] * o[3][rg];
;         ss += __shfl_xor(ss, 1); ss += __shfl_xor(ss, 2); ss += __shfl_xor(ss, 4); ss += __shfl_xor(ss, 8); ss += __shfl_xor(ss, 16);
;         rs[rg] = 1.f / sqrtf(ss * (1.f / 128.f) + EPS); }
;     LDS_WAIT();
;     g3_tile_in((const bf16*)(c.ws + O_GR) + row0 * 512 + h * 128, R, lane);
; #pragma unroll
;     for (int vb = 0; vb < 4; ++vb) { const float g = gn[32 * vb + r];
; #pragma unroll
;         for (int rg = 0; rg < 16; ++rg) { LAS bf16* e = (LAS bf16*)(R + (4 * hi) * G3_PITCH + r * 2 + ((rg & 3) + 8 * (rg >> 2)) * G3_PITCH + 64 * vb);
;             const float z = bf2f(*e);
	v_add_f32_e32 v21, v22, v23
	v_fmamk_f32 v21, v21, 0x3c000000, v100
	v_cmp_gt_f32_e32 vcc, s33, v21
	v_mul_f32_e32 v22, 0x4f800000, v21
	s_nop 0
	v_cndmask_b32_e32 v21, v21, v22, vcc
	v_sqrt_f32_e32 v22, v21
	s_nop 0
	v_add_u32_e32 v23, -1, v22
	v_fma_f32 v49, -v23, v22, v21
	v_cmp_ge_f32_e64 s[8:9], 0, v49
	v_add_u32_e32 v49, 1, v22
	s_nop 0
	v_cndmask_b32_e64 v23, v22, v23, s[8:9]
	v_fma_f32 v22, -v49, v22, v21
	v_cmp_lt_f32_e64 s[8:9], 0, v22
	s_nop 1
	v_cndmask_b32_e64 v22, v23, v49, s[8:9]
	v_mul_f32_e32 v23, 0x37800000, v22
	v_cndmask_b32_e32 v22, v22, v23, vcc
	v_cmp_class_f32_e32 vcc, v21, v101
	s_nop 1
	v_cndmask_b32_e32 v21, v22, v21, vcc
	s_nop 0
	v_div_scale_f32 v49, vcc, 1.0, v21, 1.0
	v_rcp_f32_e32 v23, v21
	v_mul_f32_e32 v21, v109, v109
	v_fmac_f32_e32 v21, v125, v125
	v_fmac_f32_e32 v21, v29, v29
	v_fmac_f32_e32 v21, v6, v6
	s_nop 1
	v_add_f32_dpp v21, v21, v21 quad_perm:[1,0,3,2] row_mask:0xf bank_mask:0xf
	v_mul_f32_e32 v30, v30, v23
	v_mul_f32_e32 v7, v7, v23
	s_nop 1
	v_add_f32_dpp v21, v21, v21 quad_perm:[2,3,0,1] row_mask:0xf bank_mask:0xf
	s_nop 1
	v_add_f32_dpp v21, v21, v21 row_half_mirror row_mask:0xf bank_mask:0xf
	s_nop 1
	v_add_f32_dpp v21, v21, v21 row_mirror row_mask:0xf bank_mask:0xf
	v_mov_b32_e32 v22, v21
	v_mov_b32_e32 v49, v21
	s_nop 1
	v_permlane16_swap_b32_e32 v22, v49
	v_add_f32_e32 v21, v22, v49
	v_fmamk_f32 v21, v21, 0x3c000000, v100
	v_cmp_gt_f32_e32 vcc, s33, v21
	v_mul_f32_e32 v22, 0x4f800000, v21
	s_nop 0
	v_cndmask_b32_e32 v21, v21, v22, vcc
	v_sqrt_f32_e32 v22, v21
	s_nop 0
	v_add_u32_e32 v49, -1, v22
	v_fma_f32 v50, -v49, v22, v21
	v_cmp_ge_f32_e64 s[8:9], 0, v50
	v_add_u32_e32 v50, 1, v22
	s_nop 0
	v_cndmask_b32_e64 v49, v22, v49, s[8:9]
	v_fma_f32 v22, -v50, v22, v21
	v_cmp_lt_f32_e64 s[8:9], 0, v22
	s_nop 1
	v_cndmask_b32_e64 v22, v49, v50, s[8:9]
	v_mul_f32_e32 v49, 0x37800000, v22
	v_cndmask_b32_e32 v22, v22, v49, vcc
	v_cmp_class_f32_e32 vcc, v21, v101
	s_nop 1
	v_cndmask_b32_e32 v21, v22, v21, vcc
	s_nop 0
	v_div_scale_f32 v50, vcc, 1.0, v21, 1.0
	v_rcp_f32_e32 v22, v21
	v_mul_f32_e32 v21, v108, v108
	v_fmac_f32_e32 v21, v124, v124
	v_fmac_f32_e32 v21, v28, v28
	v_fmac_f32_e32 v21, v5, v5
	s_nop 1
	v_add_f32_dpp v21, v21, v21 quad_perm:[1,0,3,2] row_mask:0xf bank_mask:0xf
	v_mul_f32_e32 v29, v29, v22
	v_mul_f32_e32 v6, v6, v22
	s_nop 1
	v_add_f32_dpp v21, v21, v21 quad_perm:[2,3,0,1] row_mask:0xf bank_mask:0xf
	s_nop 1
	v_add_f32_dpp v21, v21, v21 row_half_mirror row_mask:0xf bank_mask:0xf
	s_nop 1
	v_add_f32_dpp v21, v21, v21 row_mirror row_mask:0xf bank_mask:0xf
	v_mov_b32_e32 v49, v21
	v_mov_b32_e32 v50, v21
	s_nop 1
	v_permlane16_swap_b32_e32 v49, v50
	v_add_f32_e32 v21, v49, v50
	v_fmamk_f32 v21, v21, 0x3c000000, v100
	v_cmp_gt_f32_e32 vcc, s33, v21
	v_mul_f32_e32 v49, 0x4f800000, v21
	s_nop 0
	v_cndmask_b32_e32 v21, v21, v49, vcc
	v_sqrt_f32_e32 v49, v21
	s_nop 0
	v_add_u32_e32 v50, -1, v49
	v_fma_f32 v51, -v50, v49, v21
	v_cmp_ge_f32_e64 s[8:9], 0, v51
	v_add_u32_e32 v51, 1, v49
	s_nop 0
	v_cndmask_b32_e64 v50, v49, v50, s[8:9]
	v_fma_f32 v49, -v51, v49, v21
	v_cmp_lt_f32_e64 s[8:9], 0, v49
	s_nop 1
	v_cndmask_b32_e64 v49, v50, v51, s[8:9]
	v_mul_f32_e32 v50, 0x37800000, v49
	v_cndmask_b32_e32 v49, v49, v50, vcc
	v_cmp_class_f32_e32 vcc, v21, v101
	s_nop 1
	v_cndmask_b32_e32 v21, v49, v21, vcc
	s_nop 0
	v_div_scale_f32 v51, vcc, 1.0, v21, 1.0
	v_rcp_f32_e32 v21, v21
	v_mul_f32_e32 v49, v107, v107
	v_fmac_f32_e32 v49, v123, v123
	v_fmac_f32_e32 v49, v26, v26
	v_fmac_f32_e32 v49, v4, v4
	ds_bpermute_b32 v2, v2, v49
	v_mul_f32_e32 v28, v28, v21
	v_mul_f32_e32 v5, v5, v21
	s_waitcnt lgkmcnt(0)
	v_add_f32_e32 v2, v49, v2
	ds_bpermute_b32 v3, v3, v2
	s_waitcnt lgkmcnt(0)
	v_add_f32_e32 v2, v2, v3
	ds_bpermute_b32 v3, v20, v2
	s_waitcnt lgkmcnt(0)
	v_add_f32_e32 v2, v2, v3
	ds_bpermute_b32 v3, v47, v2
	s_waitcnt lgkmcnt(0)
	v_add_f32_e32 v2, v2, v3
	ds_bpermute_b32 v3, v48, v2
	s_waitcnt lgkmcnt(0)
	v_add_f32_e32 v2, v2, v3
	v_fmamk_f32 v2, v2, 0x3c000000, v100
	v_cmp_gt_f32_e32 vcc, s33, v2
	v_mul_f32_e32 v3, 0x4f800000, v2
	s_nop 0
	v_cndmask_b32_e32 v2, v2, v3, vcc
	v_sqrt_f32_e32 v3, v2
	s_nop 0
	v_add_u32_e32 v20, -1, v3
	v_fma_f32 v47, -v20, v3, v2
	v_cmp_ge_f32_e64 s[8:9], 0, v47
	v_add_u32_e32 v47, 1, v3
	s_nop 0
	v_cndmask_b32_e64 v20, v3, v20, s[8:9]
	v_fma_f32 v3, -v47, v3, v2
	v_cmp_lt_f32_e64 s[8:9], 0, v3
	s_nop 1
	v_cndmask_b32_e64 v3, v20, v47, s[8:9]
	v_mul_f32_e32 v20, 0x37800000, v3
	v_cndmask_b32_e32 v3, v3, v20, vcc
	v_cmp_class_f32_e32 vcc, v2, v101
	s_nop 1
	v_cndmask_b32_e32 v2, v3, v2, vcc
	s_nop 0
	v_rcp_f32_e32 v20, v2
	v_mul_f32_e32 v47, v138, v46
	v_mul_f32_e32 v26, v26, v20
	v_mul_f32_e32 v4, v4, v20
	s_waitcnt vmcnt(2) lgkmcnt(0)
	ds_write_b128 v92, v[164:167]
	s_waitcnt vmcnt(0) lgkmcnt(0)
	ds_write_b128 v92, v[170:173] offset:1088
	s_waitcnt vmcnt(13) lgkmcnt(0)
	ds_write_b128 v92, v[174:177] offset:2176
	s_waitcnt vmcnt(8) lgkmcnt(0)
	ds_write_b128 v92, v[178:181] offset:3264
	s_waitcnt vmcnt(9) lgkmcnt(0)
	ds_write_b128 v92, v[196:199] offset:4352
	s_waitcnt vmcnt(10) lgkmcnt(0)
	ds_write_b128 v92, v[200:203] offset:5440
	v_lshl_add_u64 v[2:3], v[168:169], 0, v[80:81]
	s_waitcnt vmcnt(5) lgkmcnt(0)
	ds_write_b128 v92, v[204:207] offset:6528
	global_load_dwordx4 v[48:51], v[2:3], off
	s_waitcnt vmcnt(0) lgkmcnt(0)
	ds_write_b128 v92, v[48:51] offset:7616
	s_waitcnt lgkmcnt(0)
	ds_read_u16 v3, v1
	s_waitcnt lgkmcnt(0)
	v_lshlrev_b32_e32 v3, 16, v3
	v_mul_f32_e32 v48, 0xbfb8aa3b, v3
	v_exp_f32_e32 v48, v48
	s_waitcnt vmcnt(0)
; #define LAS __attribute__((address_space(3)))
; DI unsigned cvtpk(float lo, float hi) { f32x2 v = {lo, hi}; bf16x2_t b = __builtin_convertvector(v, bf16x2_t); return __builtin_bit_cast(unsigned, b); }
; DI float bf2f(bf16 b) { return __uint_as_float(((unsigned)b) << 16); }
; DI float siluf_(float x) { return x / (1.f + __expf(-x)); }
; DI void gla_stage3(const Ctx& c0, int layer, int unit, int cb, LAS unsigned char* lds) {
;     ...
; #pragma unroll
;     for (int vb = 0; vb < 4; ++vb) { const float g = gn[32 * vb + r];
; #pragma unroll
;         for (int rg = 0; rg < 16; ++rg) { LAS bf16* e = (LAS bf16*)(R + (4 * hi) * G3_PITCH + r * 2 + ((rg & 3) + 8 * (rg >> 2)) * G3_PITCH + 64 * vb);
;             const float z = bf2f(*e);
;             *e = (bf16)(cvtpk(o[vb][rg] * rs[rg] * g * siluf_(z), 0.f) & 0xffffu); }
;         asm volatile("" ::: "memory"); }
	v_mul_f32_e32 v47, v47, v232
	v_add_f32_e32 v48, 1.0, v48
	v_div_scale_f32 v49, s[0:1], v48, v48, v3
	s_nop 0
	v_rcp_f32_e32 v49, v48
	s_nop 0
	v_mul_f32_e32 v3, v3, v49
	v_mul_f32_e32 v3, v47, v3
	v_cvt_pk_bf16_f32 v3, v3, s0
	ds_write_b16 v1, v3
	ds_read_u16 v3, v1 offset:272
	v_mul_f32_e32 v47, v137, v45
	v_mul_f32_e32 v47, v47, v232
	s_waitcnt lgkmcnt(0)
	v_lshlrev_b32_e32 v3, 16, v3
	v_mul_f32_e32 v48, 0xbfb8aa3b, v3
	v_exp_f32_e32 v48, v48
	s_nop 0
	v_add_f32_e32 v48, 1.0, v48
	v_div_scale_f32 v49, s[0:1], v48, v48, v3
	s_nop 0
	v_rcp_f32_e32 v49, v48
	s_nop 0
	v_mul_f32_e32 v3, v3, v49
	v_mul_f32_e32 v3, v47, v3
	v_cvt_pk_bf16_f32 v3, v3, s0
	ds_write_b16 v1, v3 offset:272
	ds_read_u16 v3, v1 offset:544
	v_mul_f32_e32 v47, v136, v44
	v_mul_f32_e32 v47, v47, v232
	s_waitcnt lgkmcnt(0)
	v_lshlrev_b32_e32 v3, 16, v3
	v_mul_f32_e32 v48, 0xbfb8aa3b, v3
	v_exp_f32_e32 v48, v48
	s_nop 0
	v_add_f32_e32 v48, 1.0, v48
	v_div_scale_f32 v49, s[0:1], v48, v48, v3
	s_nop 0
	v_rcp_f32_e32 v49, v48
	s_nop 0
	v_mul_f32_e32 v3, v3, v49
	v_mul_f32_e32 v3, v47, v3
	v_cvt_pk_bf16_f32 v3, v3, s0
	ds_write_b16 v1, v3 offset:544
	ds_read_u16 v3, v1 offset:816
	v_mul_f32_e32 v47, v135, v43
	v_mul_f32_e32 v47, v47, v232
	s_waitcnt lgkmcnt(0)
	v_lshlrev_b32_e32 v3, 16, v3
	v_mul_f32_e32 v48, 0xbfb8aa3b, v3
	v_exp_f32_e32 v48, v48
	s_nop 0
	v_add_f32_e32 v48, 1.0, v48
	v_div_scale_f32 v49, s[0:1], v48, v48, v3
	s_nop 0
	v_rcp_f32_e32 v49, v48
	s_nop 0
	v_mul_f32_e32 v3, v3, v49
	v_mul_f32_e32 v3, v47, v3
	v_cvt_pk_bf16_f32 v3, v3, s0
	ds_write_b16 v1, v3 offset:816
	ds_read_u16 v3, v1 offset:2176
	v_mul_f32_e32 v47, v134, v42
	v_mul_f32_e32 v47, v47, v232
	s_waitcnt lgkmcnt(0)
	v_lshlrev_b32_e32 v3, 16, v3
	v_mul_f32_e32 v48, 0xbfb8aa3b, v3
	v_exp_f32_e32 v48, v48
	s_nop 0
	v_add_f32_e32 v48, 1.0, v48
	v_div_scale_f32 v49, s[0:1], v48, v48, v3
	s_nop 0
	v_rcp_f32_e32 v49, v48
	s_nop 0
	v_mul_f32_e32 v3, v3, v49
	v_mul_f32_e32 v3, v47, v3
	v_cvt_pk_bf16_f32 v3, v3, s0
	ds_write_b16 v1, v3 offset:2176
	ds_read_u16 v3, v1 offset:2448
	v_mul_f32_e32 v47, v133, v41
	v_mul_f32_e32 v47, v47, v232
	s_waitcnt lgkmcnt(0)
	v_lshlrev_b32_e32 v3, 16, v3
	v_mul_f32_e32 v48, 0xbfb8aa3b, v3
	v_exp_f32_e32 v48, v48
	s_nop 0
	v_add_f32_e32 v48, 1.0, v48
	v_div_scale_f32 v49, s[0:1], v48, v48, v3
	s_nop 0
	v_rcp_f32_e32 v49, v48
	s_nop 0
	v_mul_f32_e32 v3, v3, v49
	v_mul_f32_e32 v3, v47, v3
	v_cvt_pk_bf16_f32 v3, v3, s0
	ds_write_b16 v1, v3 offset:2448
	ds_read_u16 v3, v1 offset:2720
	v_mul_f32_e32 v47, v132, v40
	v_mul_f32_e32 v47, v47, v232
	s_waitcnt lgkmcnt(0)
	v_lshlrev_b32_e32 v3, 16, v3
	v_mul_f32_e32 v48, 0xbfb8aa3b, v3
	v_exp_f32_e32 v48, v48
	s_nop 0
	v_add_f32_e32 v48, 1.0, v48
	v_div_scale_f32 v49, s[0:1], v48, v48, v3
	s_nop 0
	v_rcp_f32_e32 v49, v48
	s_nop 0
	v_mul_f32_e32 v3, v3, v49
	v_mul_f32_e32 v3, v47, v3
	v_cvt_pk_bf16_f32 v3, v3, s0
	ds_write_b16 v1, v3 offset:2720
	ds_read_u16 v3, v1 offset:2992
	v_mul_f32_e32 v47, v131, v35
	v_mul_f32_e32 v47, v47, v232
	s_waitcnt lgkmcnt(0)
	v_lshlrev_b32_e32 v3, 16, v3
	v_mul_f32_e32 v48, 0xbfb8aa3b, v3
	v_exp_f32_e32 v48, v48
	s_nop 0
	v_add_f32_e32 v48, 1.0, v48
	v_div_scale_f32 v49, s[0:1], v48, v48, v3
	s_nop 0
	v_rcp_f32_e32 v49, v48
	s_nop 0
	v_mul_f32_e32 v3, v3, v49
	v_mul_f32_e32 v3, v47, v3
	v_cvt_pk_bf16_f32 v3, v3, s0
	ds_write_b16 v1, v3 offset:2992
	ds_read_u16 v3, v1 offset:4352
	v_mul_f32_e32 v47, v130, v31
	v_mul_f32_e32 v47, v47, v232
	s_waitcnt lgkmcnt(0)
	v_lshlrev_b32_e32 v3, 16, v3
	v_mul_f32_e32 v48, 0xbfb8aa3b, v3
	v_exp_f32_e32 v48, v48
	s_nop 0
	v_add_f32_e32 v48, 1.0, v48
	v_div_scale_f32 v49, s[0:1], v48, v48, v3
	s_nop 0
	v_rcp_f32_e32 v49, v48
	s_nop 0
	v_mul_f32_e32 v3, v3, v49
	v_mul_f32_e32 v3, v47, v3
	v_cvt_pk_bf16_f32 v3, v3, s0
	ds_write_b16 v1, v3 offset:4352
	ds_read_u16 v3, v1 offset:4624
	v_mul_f32_e32 v47, v129, v27
	v_mul_f32_e32 v47, v47, v232
	s_waitcnt lgkmcnt(0)
	v_lshlrev_b32_e32 v3, 16, v3
	v_mul_f32_e32 v48, 0xbfb8aa3b, v3
	v_exp_f32_e32 v48, v48
	s_nop 0
	v_add_f32_e32 v48, 1.0, v48
	v_div_scale_f32 v49, s[0:1], v48, v48, v3
	s_nop 0
	v_rcp_f32_e32 v49, v48
	s_nop 0
	v_mul_f32_e32 v3, v3, v49
	v_mul_f32_e32 v3, v47, v3
	v_cvt_pk_bf16_f32 v3, v3, s0
	ds_write_b16 v1, v3 offset:4624
	ds_read_u16 v3, v1 offset:4896
	v_mul_f32_e32 v47, v128, v25
	v_mul_f32_e32 v47, v47, v232
	s_waitcnt lgkmcnt(0)
	v_lshlrev_b32_e32 v3, 16, v3
	v_mul_f32_e32 v48, 0xbfb8aa3b, v3
	v_exp_f32_e32 v48, v48
	s_nop 0
	v_add_f32_e32 v48, 1.0, v48
	v_div_scale_f32 v49, s[0:1], v48, v48, v3
	s_nop 0
	v_rcp_f32_e32 v49, v48
	s_nop 0
	v_mul_f32_e32 v3, v3, v49
	v_mul_f32_e32 v3, v47, v3
	v_cvt_pk_bf16_f32 v3, v3, s0
	ds_write_b16 v1, v3 offset:4896
	ds_read_u16 v3, v1 offset:5168
	v_mul_f32_e32 v47, v127, v24
	v_mul_f32_e32 v47, v47, v232
	s_waitcnt lgkmcnt(0)
	v_lshlrev_b32_e32 v3, 16, v3
	v_mul_f32_e32 v48, 0xbfb8aa3b, v3
	v_exp_f32_e32 v48, v48
	s_nop 0
	v_add_f32_e32 v48, 1.0, v48
	v_div_scale_f32 v49, s[0:1], v48, v48, v3
	s_nop 0
	v_rcp_f32_e32 v49, v48
	s_nop 0
	v_mul_f32_e32 v3, v3, v49
	v_mul_f32_e32 v3, v47, v3
	v_cvt_pk_bf16_f32 v3, v3, s0
	ds_write_b16 v1, v3 offset:5168
	ds_read_u16 v3, v1 offset:6528
	v_mul_f32_e32 v47, v126, v23
	v_mul_f32_e32 v47, v47, v232
	s_waitcnt lgkmcnt(0)
	v_lshlrev_b32_e32 v3, 16, v3
	v_mul_f32_e32 v48, 0xbfb8aa3b, v3
	v_exp_f32_e32 v48, v48
	s_nop 0
	v_add_f32_e32 v48, 1.0, v48
	v_div_scale_f32 v49, s[0:1], v48, v48, v3
	s_nop 0
	v_rcp_f32_e32 v49, v48
	s_nop 0
	v_mul_f32_e32 v3, v3, v49
	v_mul_f32_e32 v3, v47, v3
	v_cvt_pk_bf16_f32 v3, v3, s0
	ds_write_b16 v1, v3 offset:6528
	ds_read_u16 v3, v1 offset:6800
	v_mul_f32_e32 v47, v125, v22
	v_mul_f32_e32 v47, v47, v232
	s_waitcnt lgkmcnt(0)
; #define LAS __attribute__((address_space(3)))
; DI unsigned cvtpk(float lo, float hi) { f32x2 v = {lo, hi}; bf16x2_t b = __builtin_convertvector(v, bf16x2_t); return __builtin_bit_cast(unsigned, b); }
; DI float bf2f(bf16 b) { return __uint_as_float(((unsigned)b) << 16); }
; DI float siluf_(float x) { return x / (1.f + __expf(-x)); }
; DI void gla_stage3(const Ctx& c0, int layer, int unit, int cb, LAS unsigned char* lds) {
;     ...
; #pragma unroll
;     for (int vb = 0; vb < 4; ++vb) { const float g = gn[32 * vb + r];
; #pragma unroll
;         for (int rg = 0; rg < 16; ++rg) { LAS bf16* e = (LAS bf16*)(R + (4 * hi) * G3_PITCH + r * 2 + ((rg & 3) + 8 * (rg >> 2)) * G3_PITCH + 64 * vb);
;             const float z = bf2f(*e);
;             *e = (bf16)(cvtpk(o[vb][rg] * rs[rg] * g * siluf_(z), 0.f) & 0xffffu); }
;         asm volatile("" ::: "memory"); }
	v_lshlrev_b32_e32 v3, 16, v3
	v_mul_f32_e32 v48, 0xbfb8aa3b, v3
	v_exp_f32_e32 v48, v48
	s_nop 0
	v_add_f32_e32 v48, 1.0, v48
	v_div_scale_f32 v49, s[0:1], v48, v48, v3
	s_nop 0
	v_rcp_f32_e32 v49, v48
	s_nop 0
	v_mul_f32_e32 v3, v3, v49
	v_mul_f32_e32 v3, v47, v3
	v_cvt_pk_bf16_f32 v3, v3, s0
	ds_write_b16 v1, v3 offset:6800
	ds_read_u16 v3, v1 offset:7072
	v_mul_f32_e32 v47, v124, v21
	v_mul_f32_e32 v47, v47, v232
	s_waitcnt lgkmcnt(0)
	v_lshlrev_b32_e32 v3, 16, v3
	v_mul_f32_e32 v48, 0xbfb8aa3b, v3
	v_exp_f32_e32 v48, v48
	s_nop 0
	v_add_f32_e32 v48, 1.0, v48
	v_div_scale_f32 v49, s[0:1], v48, v48, v3
	s_nop 0
	v_rcp_f32_e32 v49, v48
	s_nop 0
	v_mul_f32_e32 v3, v3, v49
	v_mul_f32_e32 v3, v47, v3
	v_cvt_pk_bf16_f32 v3, v3, s0
	ds_write_b16 v1, v3 offset:7072
	ds_read_u16 v3, v1 offset:7344
	v_mul_f32_e32 v47, v123, v20
	v_mul_f32_e32 v2, v47, v232
	s_waitcnt lgkmcnt(0)
	v_lshlrev_b32_e32 v3, 16, v3
	v_mul_f32_e32 v47, 0xbfb8aa3b, v3
	v_exp_f32_e32 v47, v47
	s_nop 0
	v_add_f32_e32 v47, 1.0, v47
	v_div_scale_f32 v48, s[0:1], v47, v47, v3
	s_nop 0
	v_rcp_f32_e32 v48, v47
	s_nop 0
	v_mul_f32_e32 v3, v3, v48
	v_mul_f32_e32 v2, v2, v3
	v_cvt_pk_bf16_f32 v2, v2, s0
	ds_write_b16 v1, v2 offset:7344
	ds_read_u16 v3, v1 offset:64
	v_mul_f32_e32 v47, v122, v46
	s_waitcnt lgkmcnt(0)
	v_lshlrev_b32_e32 v3, 16, v3
	v_mul_f32_e32 v48, 0xbfb8aa3b, v3
	v_exp_f32_e32 v48, v48
	s_waitcnt vmcnt(0)
	v_mul_f32_e32 v47, v47, v234
	v_add_f32_e32 v48, 1.0, v48
	v_div_scale_f32 v49, s[0:1], v48, v48, v3
	s_nop 0
	v_rcp_f32_e32 v49, v48
	s_nop 0
	v_mul_f32_e32 v3, v3, v49
	v_mul_f32_e32 v3, v47, v3
	v_cvt_pk_bf16_f32 v3, v3, s0
	ds_write_b16 v1, v3 offset:64
	ds_read_u16 v3, v1 offset:336
	v_mul_f32_e32 v47, v121, v45
	v_mul_f32_e32 v47, v47, v234
	s_waitcnt lgkmcnt(0)
	v_lshlrev_b32_e32 v3, 16, v3
	v_mul_f32_e32 v48, 0xbfb8aa3b, v3
	v_exp_f32_e32 v48, v48
	s_nop 0
	v_add_f32_e32 v48, 1.0, v48
	v_div_scale_f32 v49, s[0:1], v48, v48, v3
	s_nop 0
	v_rcp_f32_e32 v49, v48
	s_nop 0
	v_mul_f32_e32 v3, v3, v49
	v_mul_f32_e32 v3, v47, v3
	v_cvt_pk_bf16_f32 v3, v3, s0
	ds_write_b16 v1, v3 offset:336
	ds_read_u16 v3, v1 offset:608
	v_mul_f32_e32 v47, v120, v44
	v_mul_f32_e32 v47, v47, v234
	s_waitcnt lgkmcnt(0)
	v_lshlrev_b32_e32 v3, 16, v3
	v_mul_f32_e32 v48, 0xbfb8aa3b, v3
	v_exp_f32_e32 v48, v48
	s_nop 0
	v_add_f32_e32 v48, 1.0, v48
	v_div_scale_f32 v49, s[0:1], v48, v48, v3
	s_nop 0
	v_rcp_f32_e32 v49, v48
	s_nop 0
	v_mul_f32_e32 v3, v3, v49
	v_mul_f32_e32 v3, v47, v3
	v_cvt_pk_bf16_f32 v3, v3, s0
	ds_write_b16 v1, v3 offset:608
	ds_read_u16 v3, v1 offset:880
	v_mul_f32_e32 v47, v119, v43
	v_mul_f32_e32 v47, v47, v234
	s_waitcnt lgkmcnt(0)
	v_lshlrev_b32_e32 v3, 16, v3
	v_mul_f32_e32 v48, 0xbfb8aa3b, v3
	v_exp_f32_e32 v48, v48
	s_nop 0
	v_add_f32_e32 v48, 1.0, v48
	v_div_scale_f32 v49, s[0:1], v48, v48, v3
	s_nop 0
	v_rcp_f32_e32 v49, v48
	s_nop 0
	v_mul_f32_e32 v3, v3, v49
	v_mul_f32_e32 v3, v47, v3
	v_cvt_pk_bf16_f32 v3, v3, s0
	ds_write_b16 v1, v3 offset:880
	ds_read_u16 v3, v1 offset:2240
	v_mul_f32_e32 v47, v118, v42
	v_mul_f32_e32 v47, v47, v234
	s_waitcnt lgkmcnt(0)
	v_lshlrev_b32_e32 v3, 16, v3
	v_mul_f32_e32 v48, 0xbfb8aa3b, v3
	v_exp_f32_e32 v48, v48
	s_nop 0
	v_add_f32_e32 v48, 1.0, v48
	v_div_scale_f32 v49, s[0:1], v48, v48, v3
	s_nop 0
	v_rcp_f32_e32 v49, v48
	s_nop 0
	v_mul_f32_e32 v3, v3, v49
	v_mul_f32_e32 v3, v47, v3
	v_cvt_pk_bf16_f32 v3, v3, s0
	ds_write_b16 v1, v3 offset:2240
	ds_read_u16 v3, v1 offset:2512
	v_mul_f32_e32 v47, v117, v41
	v_mul_f32_e32 v47, v47, v234
	s_waitcnt lgkmcnt(0)
	v_lshlrev_b32_e32 v3, 16, v3
	v_mul_f32_e32 v48, 0xbfb8aa3b, v3
	v_exp_f32_e32 v48, v48
	s_nop 0
	v_add_f32_e32 v48, 1.0, v48
	v_div_scale_f32 v49, s[0:1], v48, v48, v3
	s_nop 0
	v_rcp_f32_e32 v49, v48
	s_nop 0
	v_mul_f32_e32 v3, v3, v49
	v_mul_f32_e32 v3, v47, v3
	v_cvt_pk_bf16_f32 v3, v3, s0
	ds_write_b16 v1, v3 offset:2512
	ds_read_u16 v3, v1 offset:2784
	v_mul_f32_e32 v47, v116, v40
	v_mul_f32_e32 v47, v47, v234
	s_waitcnt lgkmcnt(0)
	v_lshlrev_b32_e32 v3, 16, v3
	v_mul_f32_e32 v48, 0xbfb8aa3b, v3
	v_exp_f32_e32 v48, v48
	s_nop 0
	v_add_f32_e32 v48, 1.0, v48
	v_div_scale_f32 v49, s[0:1], v48, v48, v3
	s_nop 0
	v_rcp_f32_e32 v49, v48
	s_nop 0
	v_mul_f32_e32 v3, v3, v49
	v_mul_f32_e32 v3, v47, v3
	v_cvt_pk_bf16_f32 v3, v3, s0
	ds_write_b16 v1, v3 offset:2784
	ds_read_u16 v3, v1 offset:3056
	v_mul_f32_e32 v47, v115, v35
	v_mul_f32_e32 v47, v47, v234
	s_waitcnt lgkmcnt(0)
	v_lshlrev_b32_e32 v3, 16, v3
	v_mul_f32_e32 v48, 0xbfb8aa3b, v3
	v_exp_f32_e32 v48, v48
	s_nop 0
	v_add_f32_e32 v48, 1.0, v48
	v_div_scale_f32 v49, s[0:1], v48, v48, v3
	s_nop 0
	v_rcp_f32_e32 v49, v48
	s_nop 0
	v_mul_f32_e32 v3, v3, v49
	v_mul_f32_e32 v3, v47, v3
	v_cvt_pk_bf16_f32 v3, v3, s0
	ds_write_b16 v1, v3 offset:3056
	ds_read_u16 v3, v1 offset:4416
	v_mul_f32_e32 v47, v114, v31
	v_mul_f32_e32 v47, v47, v234
	s_waitcnt lgkmcnt(0)
	v_lshlrev_b32_e32 v3, 16, v3
	v_mul_f32_e32 v48, 0xbfb8aa3b, v3
	v_exp_f32_e32 v48, v48
	s_nop 0
	v_add_f32_e32 v48, 1.0, v48
	v_div_scale_f32 v49, s[0:1], v48, v48, v3
	s_nop 0
	v_rcp_f32_e32 v49, v48
	s_nop 0
	v_mul_f32_e32 v3, v3, v49
	v_mul_f32_e32 v3, v47, v3
	v_cvt_pk_bf16_f32 v3, v3, s0
	ds_write_b16 v1, v3 offset:4416
	ds_read_u16 v3, v1 offset:4688
	v_mul_f32_e32 v47, v113, v27
	v_mul_f32_e32 v47, v47, v234
	s_waitcnt lgkmcnt(0)
	v_lshlrev_b32_e32 v3, 16, v3
	v_mul_f32_e32 v48, 0xbfb8aa3b, v3
	v_exp_f32_e32 v48, v48
	s_nop 0
	v_add_f32_e32 v48, 1.0, v48
	v_div_scale_f32 v49, s[0:1], v48, v48, v3
	s_nop 0
	v_rcp_f32_e32 v49, v48
	s_nop 0
	v_mul_f32_e32 v3, v3, v49
	v_mul_f32_e32 v3, v47, v3
	v_cvt_pk_bf16_f32 v3, v3, s0
	ds_write_b16 v1, v3 offset:4688
	ds_read_u16 v3, v1 offset:4960
	v_mul_f32_e32 v47, v112, v25
	v_mul_f32_e32 v47, v47, v234
	s_waitcnt lgkmcnt(0)
; #define LAS __attribute__((address_space(3)))
; DI unsigned cvtpk(float lo, float hi) { f32x2 v = {lo, hi}; bf16x2_t b = __builtin_convertvector(v, bf16x2_t); return __builtin_bit_cast(unsigned, b); }
; DI float bf2f(bf16 b) { return __uint_as_float(((unsigned)b) << 16); }
; DI float siluf_(float x) { return x / (1.f + __expf(-x)); }
; DI void gla_stage3(const Ctx& c0, int layer, int unit, int cb, LAS unsigned char* lds) {
;     ...
; #pragma unroll
;     for (int vb = 0; vb < 4; ++vb) { const float g = gn[32 * vb + r];
; #pragma unroll
;         for (int rg = 0; rg < 16; ++rg) { LAS bf16* e = (LAS bf16*)(R + (4 * hi) * G3_PITCH + r * 2 + ((rg & 3) + 8 * (rg >> 2)) * G3_PITCH + 64 * vb);
;             const float z = bf2f(*e);
;             *e = (bf16)(cvtpk(o[vb][rg] * rs[rg] * g * siluf_(z), 0.f) & 0xffffu); }
;         asm volatile("" ::: "memory"); }
	v_lshlrev_b32_e32 v3, 16, v3
	v_mul_f32_e32 v48, 0xbfb8aa3b, v3
	v_exp_f32_e32 v48, v48
	s_nop 0
	v_add_f32_e32 v48, 1.0, v48
	v_div_scale_f32 v49, s[0:1], v48, v48, v3
	s_nop 0
	v_rcp_f32_e32 v49, v48
	s_nop 0
	v_mul_f32_e32 v3, v3, v49
	v_mul_f32_e32 v3, v47, v3
	v_cvt_pk_bf16_f32 v3, v3, s0
	ds_write_b16 v1, v3 offset:4960
	ds_read_u16 v3, v1 offset:5232
	v_mul_f32_e32 v47, v111, v24
	v_mul_f32_e32 v47, v47, v234
	s_waitcnt lgkmcnt(0)
	v_lshlrev_b32_e32 v3, 16, v3
	v_mul_f32_e32 v48, 0xbfb8aa3b, v3
	v_exp_f32_e32 v48, v48
	s_nop 0
	v_add_f32_e32 v48, 1.0, v48
	v_div_scale_f32 v49, s[0:1], v48, v48, v3
	s_nop 0
	v_rcp_f32_e32 v49, v48
	s_nop 0
	v_mul_f32_e32 v3, v3, v49
	v_mul_f32_e32 v3, v47, v3
	v_cvt_pk_bf16_f32 v3, v3, s0
	ds_write_b16 v1, v3 offset:5232
	ds_read_u16 v3, v1 offset:6592
	v_mul_f32_e32 v47, v110, v23
	v_mul_f32_e32 v47, v47, v234
	s_waitcnt lgkmcnt(0)
	v_lshlrev_b32_e32 v3, 16, v3
	v_mul_f32_e32 v48, 0xbfb8aa3b, v3
	v_exp_f32_e32 v48, v48
	s_nop 0
	v_add_f32_e32 v48, 1.0, v48
	v_div_scale_f32 v49, s[0:1], v48, v48, v3
	s_nop 0
	v_rcp_f32_e32 v49, v48
	s_nop 0
	v_mul_f32_e32 v3, v3, v49
	v_mul_f32_e32 v3, v47, v3
	v_cvt_pk_bf16_f32 v3, v3, s0
	ds_write_b16 v1, v3 offset:6592
	ds_read_u16 v3, v1 offset:6864
	v_mul_f32_e32 v47, v109, v22
	v_mul_f32_e32 v47, v47, v234
	s_waitcnt lgkmcnt(0)
	v_lshlrev_b32_e32 v3, 16, v3
	v_mul_f32_e32 v48, 0xbfb8aa3b, v3
	v_exp_f32_e32 v48, v48
	s_nop 0
	v_add_f32_e32 v48, 1.0, v48
	v_div_scale_f32 v49, s[0:1], v48, v48, v3
	s_nop 0
	v_rcp_f32_e32 v49, v48
	s_nop 0
	v_mul_f32_e32 v3, v3, v49
	v_mul_f32_e32 v3, v47, v3
	v_cvt_pk_bf16_f32 v3, v3, s0
	ds_write_b16 v1, v3 offset:6864
	ds_read_u16 v3, v1 offset:7136
	v_mul_f32_e32 v47, v108, v21
	v_mul_f32_e32 v47, v47, v234
	s_waitcnt lgkmcnt(0)
	v_lshlrev_b32_e32 v3, 16, v3
	v_mul_f32_e32 v48, 0xbfb8aa3b, v3
	v_exp_f32_e32 v48, v48
	s_nop 0
	v_add_f32_e32 v48, 1.0, v48
	v_div_scale_f32 v49, s[0:1], v48, v48, v3
	s_nop 0
	v_rcp_f32_e32 v49, v48
	s_nop 0
	v_mul_f32_e32 v3, v3, v49
	v_mul_f32_e32 v3, v47, v3
	v_cvt_pk_bf16_f32 v3, v3, s0
	ds_write_b16 v1, v3 offset:7136
	ds_read_u16 v3, v1 offset:7408
	v_mul_f32_e32 v47, v107, v20
	v_mul_f32_e32 v2, v47, v234
	s_waitcnt lgkmcnt(0)
	v_lshlrev_b32_e32 v3, 16, v3
	v_mul_f32_e32 v47, 0xbfb8aa3b, v3
	v_exp_f32_e32 v47, v47
	s_nop 0
	v_add_f32_e32 v47, 1.0, v47
	v_div_scale_f32 v48, s[0:1], v47, v47, v3
	s_nop 0
	v_rcp_f32_e32 v48, v47
	s_nop 0
	v_mul_f32_e32 v3, v3, v48
	v_mul_f32_e32 v2, v2, v3
	v_cvt_pk_bf16_f32 v2, v2, s0
	ds_write_b16 v1, v2 offset:7408
	ds_read_u16 v3, v1 offset:128
	v_mul_f32_e32 v47, v106, v46
	s_waitcnt lgkmcnt(0)
	v_lshlrev_b32_e32 v3, 16, v3
	v_mul_f32_e32 v48, 0xbfb8aa3b, v3
	v_exp_f32_e32 v48, v48
	s_waitcnt vmcnt(0)
	v_mul_f32_e32 v47, v47, v236
	v_add_f32_e32 v48, 1.0, v48
	v_div_scale_f32 v49, s[0:1], v48, v48, v3
	v_mul_f32_e32 v39, v39, v236
	v_mul_f32_e32 v38, v38, v236
	v_mul_f32_e32 v37, v37, v236
	v_rcp_f32_e32 v49, v48
	s_nop 0
	v_mul_f32_e32 v3, v3, v49
	v_mul_f32_e32 v3, v47, v3
	v_cvt_pk_bf16_f32 v3, v3, s0
	ds_write_b16 v1, v3 offset:128
	ds_read_u16 v3, v1 offset:400
	v_mul_f32_e32 v47, v105, v45
	v_mul_f32_e32 v47, v47, v236
	v_mul_f32_e32 v36, v36, v236
	v_mul_f32_e32 v34, v34, v236
	s_waitcnt lgkmcnt(0)
	v_lshlrev_b32_e32 v3, 16, v3
	v_mul_f32_e32 v48, 0xbfb8aa3b, v3
	v_exp_f32_e32 v48, v48
	v_mul_f32_e32 v33, v33, v236
	v_mul_f32_e32 v32, v32, v236
	v_mul_f32_e32 v30, v30, v236
	v_add_f32_e32 v48, 1.0, v48
	v_div_scale_f32 v49, s[0:1], v48, v48, v3
	v_mul_f32_e32 v29, v29, v236
	v_mul_f32_e32 v28, v28, v236
	v_rcp_f32_e32 v49, v48
	s_nop 0
	v_mul_f32_e32 v3, v3, v49
	v_mul_f32_e32 v3, v47, v3
	v_cvt_pk_bf16_f32 v3, v3, s0
	ds_write_b16 v1, v3 offset:400
	ds_read_u16 v3, v1 offset:672
	v_mul_f32_e32 v47, v104, v44
	v_mul_f32_e32 v47, v47, v236
	s_waitcnt lgkmcnt(0)
	v_lshlrev_b32_e32 v3, 16, v3
	v_mul_f32_e32 v48, 0xbfb8aa3b, v3
	v_exp_f32_e32 v48, v48
	s_nop 0
	v_add_f32_e32 v48, 1.0, v48
	v_div_scale_f32 v49, s[0:1], v48, v48, v3
	s_nop 0
	v_rcp_f32_e32 v49, v48
	s_nop 0
	v_mul_f32_e32 v3, v3, v49
	v_mul_f32_e32 v3, v47, v3
	v_cvt_pk_bf16_f32 v3, v3, s0
	ds_write_b16 v1, v3 offset:672
	ds_read_u16 v3, v1 offset:944
	v_mul_f32_e32 v47, v103, v43
	v_mul_f32_e32 v47, v47, v236
	s_waitcnt lgkmcnt(0)
	v_lshlrev_b32_e32 v3, 16, v3
	v_mul_f32_e32 v48, 0xbfb8aa3b, v3
	v_exp_f32_e32 v48, v48
	s_nop 0
	v_add_f32_e32 v48, 1.0, v48
	v_div_scale_f32 v49, s[0:1], v48, v48, v3
	s_nop 0
	v_rcp_f32_e32 v49, v48
	s_nop 0
	v_mul_f32_e32 v3, v3, v49
	v_mul_f32_e32 v3, v47, v3
	v_cvt_pk_bf16_f32 v3, v3, s0
	ds_write_b16 v1, v3 offset:944
	ds_read_u16 v3, v1 offset:2304
	v_mul_f32_e32 v47, v102, v42
	v_mul_f32_e32 v47, v47, v236
	v_mul_f32_e32 v2, v26, v236
	s_waitcnt lgkmcnt(0)
	v_lshlrev_b32_e32 v3, 16, v3
	v_mul_f32_e32 v48, 0xbfb8aa3b, v3
	v_exp_f32_e32 v48, v48
	s_nop 0
	v_add_f32_e32 v48, 1.0, v48
	v_div_scale_f32 v49, s[0:1], v48, v48, v3
	s_nop 0
	v_rcp_f32_e32 v49, v48
	s_nop 0
	v_mul_f32_e32 v3, v3, v49
	v_mul_f32_e32 v3, v47, v3
	v_cvt_pk_bf16_f32 v3, v3, s0
	ds_write_b16 v1, v3 offset:2304
	ds_read_u16 v3, v1 offset:2576
	s_waitcnt lgkmcnt(0)
	v_lshlrev_b32_e32 v3, 16, v3
	v_mul_f32_e32 v47, 0xbfb8aa3b, v3
	v_exp_f32_e32 v47, v47
	s_nop 0
	v_add_f32_e32 v47, 1.0, v47
	v_div_scale_f32 v48, s[0:1], v47, v47, v3
	s_nop 0
	v_rcp_f32_e32 v48, v47
	s_nop 0
	v_mul_f32_e32 v3, v3, v48
	v_mul_f32_e32 v3, v39, v3
	v_cvt_pk_bf16_f32 v3, v3, s0
	ds_write_b16 v1, v3 offset:2576
	ds_read_u16 v3, v1 offset:2848
	s_waitcnt lgkmcnt(0)
; #define LAS __attribute__((address_space(3)))
; DI unsigned cvtpk(float lo, float hi) { f32x2 v = {lo, hi}; bf16x2_t b = __builtin_convertvector(v, bf16x2_t); return __builtin_bit_cast(unsigned, b); }
; DI float bf2f(bf16 b) { return __uint_as_float(((unsigned)b) << 16); }
; DI float siluf_(float x) { return x / (1.f + __expf(-x)); }
; DI void gla_stage3(const Ctx& c0, int layer, int unit, int cb, LAS unsigned char* lds) {
;     ...
; #pragma unroll
;     for (int vb = 0; vb < 4; ++vb) { const float g = gn[32 * vb + r];
; #pragma unroll
;         for (int rg = 0; rg < 16; ++rg) { LAS bf16* e = (LAS bf16*)(R + (4 * hi) * G3_PITCH + r * 2 + ((rg & 3) + 8 * (rg >> 2)) * G3_PITCH + 64 * vb);
;             const float z = bf2f(*e);
;             *e = (bf16)(cvtpk(o[vb][rg] * rs[rg] * g * siluf_(z), 0.f) & 0xffffu); }
;         asm volatile("" ::: "memory"); }
	v_lshlrev_b32_e32 v3, 16, v3
	v_mul_f32_e32 v39, 0xbfb8aa3b, v3
	v_exp_f32_e32 v39, v39
	s_nop 0
	v_add_f32_e32 v39, 1.0, v39
	v_div_scale_f32 v47, s[0:1], v39, v39, v3
	s_nop 0
	v_rcp_f32_e32 v47, v39
	s_nop 0
	v_mul_f32_e32 v3, v3, v47
	v_mul_f32_e32 v3, v38, v3
	v_cvt_pk_bf16_f32 v3, v3, s0
	ds_write_b16 v1, v3 offset:2848
	ds_read_u16 v3, v1 offset:3120
	s_waitcnt lgkmcnt(0)
	v_lshlrev_b32_e32 v3, 16, v3
	v_mul_f32_e32 v38, 0xbfb8aa3b, v3
	v_exp_f32_e32 v38, v38
	s_nop 0
	v_add_f32_e32 v38, 1.0, v38
	v_div_scale_f32 v39, s[0:1], v38, v38, v3
	s_nop 0
	v_rcp_f32_e32 v39, v38
	s_nop 0
	v_mul_f32_e32 v3, v3, v39
	v_mul_f32_e32 v3, v37, v3
	v_cvt_pk_bf16_f32 v3, v3, s0
	ds_write_b16 v1, v3 offset:3120
	ds_read_u16 v3, v1 offset:4480
	s_waitcnt lgkmcnt(0)
	v_lshlrev_b32_e32 v3, 16, v3
	v_mul_f32_e32 v37, 0xbfb8aa3b, v3
	v_exp_f32_e32 v37, v37
	s_nop 0
	v_add_f32_e32 v37, 1.0, v37
	v_div_scale_f32 v38, s[0:1], v37, v37, v3
	s_nop 0
	v_rcp_f32_e32 v38, v37
	s_nop 0
	v_mul_f32_e32 v3, v3, v38
	v_mul_f32_e32 v3, v36, v3
	v_cvt_pk_bf16_f32 v3, v3, s0
	ds_write_b16 v1, v3 offset:4480
	ds_read_u16 v3, v1 offset:4752
	s_waitcnt lgkmcnt(0)
	v_lshlrev_b32_e32 v3, 16, v3
	v_mul_f32_e32 v36, 0xbfb8aa3b, v3
	v_exp_f32_e32 v36, v36
	s_nop 0
	v_add_f32_e32 v36, 1.0, v36
	v_div_scale_f32 v37, s[0:1], v36, v36, v3
	s_nop 0
	v_rcp_f32_e32 v37, v36
	s_nop 0
	v_mul_f32_e32 v3, v3, v37
	v_mul_f32_e32 v3, v34, v3
	v_cvt_pk_bf16_f32 v3, v3, s0
	ds_write_b16 v1, v3 offset:4752
	ds_read_u16 v3, v1 offset:5024
	s_waitcnt lgkmcnt(0)
	v_lshlrev_b32_e32 v3, 16, v3
	v_mul_f32_e32 v34, 0xbfb8aa3b, v3
	v_exp_f32_e32 v34, v34
	s_nop 0
	v_add_f32_e32 v34, 1.0, v34
	v_div_scale_f32 v36, s[0:1], v34, v34, v3
	s_nop 0
	v_rcp_f32_e32 v36, v34
	s_nop 0
	v_mul_f32_e32 v3, v3, v36
	v_mul_f32_e32 v3, v33, v3
	v_cvt_pk_bf16_f32 v3, v3, s0
	ds_write_b16 v1, v3 offset:5024
	ds_read_u16 v3, v1 offset:5296
	s_waitcnt lgkmcnt(0)
	v_lshlrev_b32_e32 v3, 16, v3
	v_mul_f32_e32 v33, 0xbfb8aa3b, v3
	v_exp_f32_e32 v33, v33
	s_nop 0
	v_add_f32_e32 v33, 1.0, v33
	v_div_scale_f32 v34, s[0:1], v33, v33, v3
	s_nop 0
	v_rcp_f32_e32 v34, v33
	s_nop 0
	v_mul_f32_e32 v3, v3, v34
	v_mul_f32_e32 v3, v32, v3
	v_cvt_pk_bf16_f32 v3, v3, s0
	ds_write_b16 v1, v3 offset:5296
	ds_read_u16 v3, v1 offset:6656
	s_waitcnt lgkmcnt(0)
	v_lshlrev_b32_e32 v3, 16, v3
	v_mul_f32_e32 v32, 0xbfb8aa3b, v3
	v_exp_f32_e32 v32, v32
	s_nop 0
	v_add_f32_e32 v32, 1.0, v32
	v_div_scale_f32 v33, s[0:1], v32, v32, v3
	s_nop 0
	v_rcp_f32_e32 v33, v32
	s_nop 0
	v_mul_f32_e32 v3, v3, v33
	v_mul_f32_e32 v3, v30, v3
	v_cvt_pk_bf16_f32 v3, v3, s0
	ds_write_b16 v1, v3 offset:6656
	ds_read_u16 v3, v1 offset:6928
	s_waitcnt lgkmcnt(0)
	v_lshlrev_b32_e32 v3, 16, v3
	v_mul_f32_e32 v30, 0xbfb8aa3b, v3
	v_exp_f32_e32 v30, v30
	s_nop 0
	v_add_f32_e32 v30, 1.0, v30
	v_div_scale_f32 v32, s[0:1], v30, v30, v3
	s_nop 0
	v_rcp_f32_e32 v32, v30
	s_nop 0
	v_mul_f32_e32 v3, v3, v32
	v_mul_f32_e32 v3, v29, v3
	v_cvt_pk_bf16_f32 v3, v3, s0
	ds_write_b16 v1, v3 offset:6928
	ds_read_u16 v3, v1 offset:7200
	s_waitcnt lgkmcnt(0)
	v_lshlrev_b32_e32 v3, 16, v3
	v_mul_f32_e32 v29, 0xbfb8aa3b, v3
	v_exp_f32_e32 v29, v29
	s_nop 0
	v_add_f32_e32 v29, 1.0, v29
	v_div_scale_f32 v30, s[0:1], v29, v29, v3
	s_nop 0
	v_rcp_f32_e32 v30, v29
	s_nop 0
	v_mul_f32_e32 v3, v3, v30
	v_mul_f32_e32 v3, v28, v3
	v_cvt_pk_bf16_f32 v3, v3, s0
	ds_write_b16 v1, v3 offset:7200
	ds_read_u16 v3, v1 offset:7472
	s_waitcnt lgkmcnt(0)
	v_lshlrev_b32_e32 v3, 16, v3
	v_mul_f32_e32 v26, 0xbfb8aa3b, v3
	v_exp_f32_e32 v26, v26
	s_nop 0
	v_add_f32_e32 v26, 1.0, v26
	v_div_scale_f32 v28, s[0:1], v26, v26, v3
	s_nop 0
	v_rcp_f32_e32 v28, v26
	s_nop 0
	v_mul_f32_e32 v3, v3, v28
	v_mul_f32_e32 v2, v2, v3
	v_cvt_pk_bf16_f32 v2, v2, s0
	ds_write_b16 v1, v2 offset:7472
	ds_read_u16 v3, v1 offset:192
	s_waitcnt lgkmcnt(0)
	v_lshlrev_b32_e32 v3, 16, v3
	v_mul_f32_e32 v26, 0xbfb8aa3b, v3
	v_exp_f32_e32 v26, v26
	s_waitcnt vmcnt(31)
	v_mul_f32_e32 v19, v19, v238
	v_add_f32_e32 v26, 1.0, v26
	v_div_scale_f32 v28, s[0:1], v26, v26, v3
	v_mul_f32_e32 v18, v18, v238
	v_mul_f32_e32 v17, v17, v238
	v_mul_f32_e32 v16, v16, v238
	v_rcp_f32_e32 v28, v26
	s_nop 0
	v_mul_f32_e32 v3, v3, v28
	v_mul_f32_e32 v3, v19, v3
	v_cvt_pk_bf16_f32 v3, v3, s0
	ds_write_b16 v1, v3 offset:192
	ds_read_u16 v3, v1 offset:464
	v_mul_f32_e32 v15, v15, v238
	v_mul_f32_e32 v14, v14, v238
	v_mul_f32_e32 v13, v13, v238
	v_mul_f32_e32 v12, v12, v238
	s_waitcnt lgkmcnt(0)
	v_lshlrev_b32_e32 v3, 16, v3
	v_mul_f32_e32 v19, 0xbfb8aa3b, v3
	v_exp_f32_e32 v19, v19
	v_mul_f32_e32 v11, v11, v238
	v_mul_f32_e32 v10, v10, v238
	v_mul_f32_e32 v9, v9, v238
	v_add_f32_e32 v19, 1.0, v19
	v_div_scale_f32 v26, s[0:1], v19, v19, v3
	v_mul_f32_e32 v8, v8, v238
	v_mul_f32_e32 v7, v7, v238
	v_mul_f32_e32 v6, v6, v238
	v_rcp_f32_e32 v26, v19
	s_nop 0
	v_mul_f32_e32 v3, v3, v26
	v_mul_f32_e32 v3, v18, v3
	v_cvt_pk_bf16_f32 v3, v3, s0
	ds_write_b16 v1, v3 offset:464
	ds_read_u16 v3, v1 offset:736
	v_mul_f32_e32 v5, v5, v238
	v_mul_f32_e32 v2, v4, v238
	s_waitcnt lgkmcnt(0)
	v_lshlrev_b32_e32 v3, 16, v3
	v_mul_f32_e32 v18, 0xbfb8aa3b, v3
	v_exp_f32_e32 v18, v18
	s_nop 0
	v_add_f32_e32 v18, 1.0, v18
	v_div_scale_f32 v19, s[0:1], v18, v18, v3
	s_nop 0
	v_rcp_f32_e32 v19, v18
	s_nop 0
	v_mul_f32_e32 v3, v3, v19
	v_mul_f32_e32 v3, v17, v3
	v_cvt_pk_bf16_f32 v3, v3, s0
	ds_write_b16 v1, v3 offset:736
	ds_read_u16 v3, v1 offset:1008
	s_waitcnt lgkmcnt(0)
	v_lshlrev_b32_e32 v3, 16, v3
	v_mul_f32_e32 v17, 0xbfb8aa3b, v3
	v_exp_f32_e32 v17, v17
	s_nop 0
	v_add_f32_e32 v17, 1.0, v17
	v_div_scale_f32 v18, s[0:1], v17, v17, v3
	s_nop 0
	v_rcp_f32_e32 v18, v17
	s_nop 0
	v_mul_f32_e32 v3, v3, v18
	v_mul_f32_e32 v3, v16, v3
	v_cvt_pk_bf16_f32 v3, v3, s0
	ds_write_b16 v1, v3 offset:1008
	ds_read_u16 v3, v1 offset:2368
	s_waitcnt lgkmcnt(0)
; #define LAS __attribute__((address_space(3)))
; #define LDS_WAIT() asm volatile("s_waitcnt lgkmcnt(0)" ::: "memory")
; DI unsigned cvtpk(float lo, float hi) { f32x2 v = {lo, hi}; bf16x2_t b = __builtin_convertvector(v, bf16x2_t); return __builtin_bit_cast(unsigned, b); }
; DI float bf2f(bf16 b) { return __uint_as_float(((unsigned)b) << 16); }
; DI float siluf_(float x) { return x / (1.f + __expf(-x)); }
; DI void g3_tile_out(bf16* g, const LAS unsigned char* R, int lane) {
;     LDS_WAIT();
; #pragma unroll
;     for (int it = 0; it < 8; ++it) { const int row = 4 * it + (lane >> 4), ch = lane & 15;
;         *(u32x4*)(g + (size_t)row * 512 + ch * 8) = *(const LAS u32x4*)(R + row * G3_PITCH + ch * 16); }
;     LDS_WAIT();
; }
; DI void gla_stage3(const Ctx& c0, int layer, int unit, int cb, LAS unsigned char* lds) {
;     ...
; #pragma unroll
;     for (int vb = 0; vb < 4; ++vb) { const float g = gn[32 * vb + r];
; #pragma unroll
;         for (int rg = 0; rg < 16; ++rg) { LAS bf16* e = (LAS bf16*)(R + (4 * hi) * G3_PITCH + r * 2 + ((rg & 3) + 8 * (rg >> 2)) * G3_PITCH + 64 * vb);
;             const float z = bf2f(*e);
;             *e = (bf16)(cvtpk(o[vb][rg] * rs[rg] * g * siluf_(z), 0.f) & 0xffffu); }
;         asm volatile("" ::: "memory"); }
;     g3_tile_out((bf16*)(c.ws + O_OGLA) + row0 * 512 + h * 128, R, lane);
	v_lshlrev_b32_e32 v3, 16, v3
	v_mul_f32_e32 v16, 0xbfb8aa3b, v3
	v_exp_f32_e32 v16, v16
	s_nop 0
	v_add_f32_e32 v16, 1.0, v16
	v_div_scale_f32 v17, s[0:1], v16, v16, v3
	s_nop 0
	v_rcp_f32_e32 v17, v16
	s_nop 0
	v_mul_f32_e32 v3, v3, v17
	v_mul_f32_e32 v3, v15, v3
	v_cvt_pk_bf16_f32 v3, v3, s0
	ds_write_b16 v1, v3 offset:2368
	ds_read_u16 v3, v1 offset:2640
	s_waitcnt lgkmcnt(0)
	v_lshlrev_b32_e32 v3, 16, v3
	v_mul_f32_e32 v15, 0xbfb8aa3b, v3
	v_exp_f32_e32 v15, v15
	s_nop 0
	v_add_f32_e32 v15, 1.0, v15
	v_div_scale_f32 v16, s[0:1], v15, v15, v3
	s_nop 0
	v_rcp_f32_e32 v16, v15
	s_nop 0
	v_mul_f32_e32 v3, v3, v16
	v_mul_f32_e32 v3, v14, v3
	v_cvt_pk_bf16_f32 v3, v3, s0
	ds_write_b16 v1, v3 offset:2640
	ds_read_u16 v3, v1 offset:2912
	s_waitcnt lgkmcnt(0)
	v_lshlrev_b32_e32 v3, 16, v3
	v_mul_f32_e32 v14, 0xbfb8aa3b, v3
	v_exp_f32_e32 v14, v14
	s_nop 0
	v_add_f32_e32 v14, 1.0, v14
	v_div_scale_f32 v15, s[0:1], v14, v14, v3
	s_nop 0
	v_rcp_f32_e32 v15, v14
	s_nop 0
	v_mul_f32_e32 v3, v3, v15
	v_mul_f32_e32 v3, v13, v3
	v_cvt_pk_bf16_f32 v3, v3, s0
	ds_write_b16 v1, v3 offset:2912
	ds_read_u16 v3, v1 offset:3184
	s_waitcnt lgkmcnt(0)
	v_lshlrev_b32_e32 v3, 16, v3
	v_mul_f32_e32 v13, 0xbfb8aa3b, v3
	v_exp_f32_e32 v13, v13
	s_nop 0
	v_add_f32_e32 v13, 1.0, v13
	v_div_scale_f32 v14, s[0:1], v13, v13, v3
	s_nop 0
	v_rcp_f32_e32 v14, v13
	s_nop 0
	v_mul_f32_e32 v3, v3, v14
	v_mul_f32_e32 v3, v12, v3
	v_cvt_pk_bf16_f32 v3, v3, s0
	ds_write_b16 v1, v3 offset:3184
	ds_read_u16 v3, v1 offset:4544
	s_waitcnt lgkmcnt(0)
	v_lshlrev_b32_e32 v3, 16, v3
	v_mul_f32_e32 v12, 0xbfb8aa3b, v3
	v_exp_f32_e32 v12, v12
	s_nop 0
	v_add_f32_e32 v12, 1.0, v12
	v_div_scale_f32 v13, s[0:1], v12, v12, v3
	s_nop 0
	v_rcp_f32_e32 v13, v12
	s_nop 0
	v_mul_f32_e32 v3, v3, v13
	v_mul_f32_e32 v3, v11, v3
	v_cvt_pk_bf16_f32 v3, v3, s0
	ds_write_b16 v1, v3 offset:4544
	ds_read_u16 v3, v1 offset:4816
	s_waitcnt lgkmcnt(0)
	v_lshlrev_b32_e32 v3, 16, v3
	v_mul_f32_e32 v11, 0xbfb8aa3b, v3
	v_exp_f32_e32 v11, v11
	s_nop 0
	v_add_f32_e32 v11, 1.0, v11
	v_div_scale_f32 v12, s[0:1], v11, v11, v3
	s_nop 0
	v_rcp_f32_e32 v12, v11
	s_nop 0
	v_mul_f32_e32 v3, v3, v12
	v_mul_f32_e32 v3, v10, v3
	v_cvt_pk_bf16_f32 v3, v3, s0
	ds_write_b16 v1, v3 offset:4816
	ds_read_u16 v3, v1 offset:5088
	s_waitcnt lgkmcnt(0)
	v_lshlrev_b32_e32 v3, 16, v3
	v_mul_f32_e32 v10, 0xbfb8aa3b, v3
	v_exp_f32_e32 v10, v10
	s_nop 0
	v_add_f32_e32 v10, 1.0, v10
	v_div_scale_f32 v11, s[0:1], v10, v10, v3
	s_nop 0
	v_rcp_f32_e32 v11, v10
	s_nop 0
	v_mul_f32_e32 v3, v3, v11
	v_mul_f32_e32 v3, v9, v3
	v_cvt_pk_bf16_f32 v3, v3, s0
	ds_write_b16 v1, v3 offset:5088
	ds_read_u16 v3, v1 offset:5360
	s_waitcnt lgkmcnt(0)
	v_lshlrev_b32_e32 v3, 16, v3
	v_mul_f32_e32 v9, 0xbfb8aa3b, v3
	v_exp_f32_e32 v9, v9
	s_nop 0
	v_add_f32_e32 v9, 1.0, v9
	v_div_scale_f32 v10, s[0:1], v9, v9, v3
	s_nop 0
	v_rcp_f32_e32 v10, v9
	s_nop 0
	v_mul_f32_e32 v3, v3, v10
	v_mul_f32_e32 v3, v8, v3
	v_cvt_pk_bf16_f32 v3, v3, s0
	ds_write_b16 v1, v3 offset:5360
	ds_read_u16 v3, v1 offset:6720
	s_waitcnt lgkmcnt(0)
	v_lshlrev_b32_e32 v3, 16, v3
	v_mul_f32_e32 v8, 0xbfb8aa3b, v3
	v_exp_f32_e32 v8, v8
	s_nop 0
	v_add_f32_e32 v8, 1.0, v8
	v_div_scale_f32 v9, s[0:1], v8, v8, v3
	s_nop 0
	v_rcp_f32_e32 v9, v8
	s_nop 0
	v_mul_f32_e32 v3, v3, v9
	v_mul_f32_e32 v3, v7, v3
	v_cvt_pk_bf16_f32 v3, v3, s0
	ds_write_b16 v1, v3 offset:6720
	ds_read_u16 v3, v1 offset:6992
	s_waitcnt lgkmcnt(0)
	v_lshlrev_b32_e32 v3, 16, v3
	v_mul_f32_e32 v7, 0xbfb8aa3b, v3
	v_exp_f32_e32 v7, v7
	s_nop 0
	v_add_f32_e32 v7, 1.0, v7
	v_div_scale_f32 v8, s[0:1], v7, v7, v3
	s_nop 0
	v_rcp_f32_e32 v8, v7
	s_nop 0
	v_mul_f32_e32 v3, v3, v8
	v_mul_f32_e32 v3, v6, v3
	v_cvt_pk_bf16_f32 v3, v3, s0
	ds_write_b16 v1, v3 offset:6992
	ds_read_u16 v3, v1 offset:7264
	s_waitcnt lgkmcnt(0)
	v_lshlrev_b32_e32 v3, 16, v3
	v_mul_f32_e32 v6, 0xbfb8aa3b, v3
	v_exp_f32_e32 v6, v6
	s_nop 0
	v_add_f32_e32 v6, 1.0, v6
	v_div_scale_f32 v7, s[0:1], v6, v6, v3
	s_nop 0
	v_rcp_f32_e32 v7, v6
	s_nop 0
	v_mul_f32_e32 v3, v3, v7
	v_mul_f32_e32 v3, v5, v3
	v_cvt_pk_bf16_f32 v3, v3, s0
	ds_write_b16 v1, v3 offset:7264
	ds_read_u16 v3, v1 offset:7536
	s_waitcnt lgkmcnt(0)
	v_lshlrev_b32_e32 v3, 16, v3
	v_mul_f32_e32 v4, 0xbfb8aa3b, v3
	v_exp_f32_e32 v4, v4
	s_nop 0
	v_add_f32_e32 v4, 1.0, v4
	v_div_scale_f32 v5, s[0:1], v4, v4, v3
	s_nop 0
	v_rcp_f32_e32 v5, v4
	s_nop 0
	v_mul_f32_e32 v3, v3, v5
	v_mul_f32_e32 v2, v2, v3
	v_cvt_pk_bf16_f32 v2, v2, s0
	ds_write_b16 v1, v2 offset:7536
	s_waitcnt lgkmcnt(0)
	ds_read_b128 v[2:5], v92
	v_lshl_add_u64 v[6:7], v[90:91], 0, s[24:25]
	v_lshl_add_u64 v[8:9], v[6:7], 0, v[66:67]
	s_waitcnt lgkmcnt(0)
	global_store_dwordx4 v[8:9], v[2:5], off
	ds_read_b128 v[2:5], v92 offset:1088
	v_lshl_add_u64 v[8:9], v[6:7], 0, v[68:69]
	s_waitcnt lgkmcnt(0)
	global_store_dwordx4 v[8:9], v[2:5], off
	ds_read_b128 v[2:5], v92 offset:2176
	v_lshl_add_u64 v[8:9], v[6:7], 0, v[70:71]
	s_waitcnt lgkmcnt(0)
	global_store_dwordx4 v[8:9], v[2:5], off
	ds_read_b128 v[2:5], v92 offset:3264
	v_lshl_add_u64 v[8:9], v[6:7], 0, v[72:73]
	s_waitcnt lgkmcnt(0)
	global_store_dwordx4 v[8:9], v[2:5], off
	ds_read_b128 v[2:5], v92 offset:4352
	v_lshl_add_u64 v[8:9], v[6:7], 0, v[74:75]
	s_waitcnt lgkmcnt(0)
	global_store_dwordx4 v[8:9], v[2:5], off
	ds_read_b128 v[2:5], v92 offset:5440
	v_lshl_add_u64 v[8:9], v[6:7], 0, v[76:77]
	s_waitcnt lgkmcnt(0)
	global_store_dwordx4 v[8:9], v[2:5], off
	ds_read_b128 v[2:5], v92 offset:6528
	v_lshl_add_u64 v[8:9], v[6:7], 0, v[78:79]
	v_lshl_add_u64 v[6:7], v[6:7], 0, v[80:81]
	s_waitcnt lgkmcnt(0)
	global_store_dwordx4 v[8:9], v[2:5], off
	ds_read_b128 v[2:5], v92 offset:7616
	s_waitcnt lgkmcnt(0)
	global_store_dwordx4 v[6:7], v[2:5], off
	s_waitcnt lgkmcnt(0)
	s_cbranch_scc1 .LBB0_1216
